# P5 scan: the next half's eight 32x32x16 MFMAs issued one per step inside the current half's packed recurrence instead of as a block (MFMA-VALU interleave)
# speedup vs baseline: 1.0042x; 1.0042x over previous
; __device__ __forceinline__ unsigned cvt_pk_bf16(float lo, float hi) { unsigned r; asm volatile("v_cvt_pk_bf16_f32 %0, %1, %2" : "=v"(r) : "v"(lo), "v"(hi)); return r; }
; __device__ __forceinline__ float bflo(unsigned w) { return __uint_as_float(w << 16); }
; __device__ __forceinline__ float bfhi(unsigned w) { return __uint_as_float(w & 0xffff0000u); }
; #define LAS __attribute__((address_space(3)))
; __device__ __forceinline__ void ssm_load_bfrag(Frame& F, int g, int lane, bf16x8 (&bf)[8]) {
;     const int q = lane >> 4, hs = (q & 1) * 8; const bool lo = q >= 2;
; #pragma unroll
;     for (int cb = 0; cb < 8; ++cb) { const int col = 16 * cb + (lane & 15), p = col & 63, im = col >> 6;
;         const float* src = (const float*)(F.ws + WS_BB) + (size_t)(g * NST + p) * 32 + im * 16 + hs;
;         const f32x4 x0 = *(const f32x4*)src, x1 = *(const f32x4*)(src + 4);
;         float v[8] = {x0.x, x0.y, x0.z, x0.w, x1.x, x1.y, x1.z, x1.w};
;         unsigned w[4];
; #pragma unroll
;         for (int j = 0; j < 4; ++j) { const unsigned hi = cvt_pk_bf16(v[2 * j], v[2 * j + 1]);
;             const unsigned l2 = cvt_pk_bf16(v[2 * j] - bflo(hi), v[2 * j + 1] - bfhi(hi)); w[j] = lo ? l2 : hi; }
;         v4u ww = (v4u){w[0], w[1], w[2], w[3]}; bf[cb] = __builtin_bit_cast(bf16x8, ww); }
; __device__ __forceinline__ void p5_phase(Frame& F) {
;     LAS float* bubuf = (LAS float*)(F.lds + RING_OFF + F.wave * SSM_LDS_W);
;     const bf16* U = (const bf16*)(F.ws + WS_U);
;     const int g = F.gw & (NGRP - 1);
;     bf16x8 bf[8]; ssm_load_bfrag(F, g, F.lane, bf);
;     const f32x2 ab = ((const f32x2*)(F.ws + WS_ABAR))[g * NST + F.lane];
;     bf16x8 nfr[4];
;     { const int bc = F.gw >> 7, r0 = (bc / NCH) * SEQ + (bc % NCH) * TCH;
; #pragma unroll
;       for (int sub = 0; sub < 4; ++sub) nfr[sub] = ssm_load_afrag(U, r0 + 16 * sub, g, F.lane); }
;     for (int it = F.gw; it < NB * NCH * NGRP; it += F.ngw) {
;         bf16x8 afr[4];
; #pragma unroll
;         for (int sub = 0; sub < 4; ++sub) afr[sub] = nfr[sub];
;         if (it + F.ngw < NB * NCH * NGRP) { const int bc = (it + F.ngw) >> 7, r0 = (bc / NCH) * SEQ + (bc % NCH) * TCH;
; #pragma unroll
;             for (int sub = 0; sub < 4; ++sub) nfr[sub] = ssm_load_afrag(U, r0 + 16 * sub, g, F.lane); }
.LBB0_684:
	s_cmp_lt_i32 s8, 6
	s_cselect_b64 s[0:1], -1, 0
	s_cmp_gt_i32 s9, 5
	s_cselect_b64 s[2:3], -1, 0
	s_and_b64 s[0:1], s[0:1], s[2:3]
	s_andn2_b64 vcc, exec, s[0:1]
	v_lshlrev_b32_e32 v1, 7, v0
	s_cbranch_vccnz .LBB0_783
	s_waitcnt vmcnt(0)
	s_and_b32 s56, s88, 0x7f
	v_and_b32_e32 v177, 31, v198
	v_lshrrev_b32_e32 v2, 5, v198
	v_lshlrev_b32_e32 v3, 7, v177
	v_lshl_or_b32 v3, v2, 5, v3
	s_lshl_b32 s57, s56, 13
	s_add_u32 s50, s96, 0x120000
	s_addc_u32 s51, s97, 0
	s_add_u32 s50, s50, s57
	s_addc_u32 s51, s51, 0
	s_add_u32 s52, s50, 0x1000
	s_addc_u32 s53, s51, 0
	global_load_dwordx4 v[16:19], v3, s[50:51]
	global_load_dwordx4 v[20:23], v3, s[50:51] offset:16
	global_load_dwordx4 v[24:27], v3, s[52:53]
	global_load_dwordx4 v[28:31], v3, s[52:53] offset:16
	global_load_dwordx4 v[32:35], v3, s[50:51] offset:64
	global_load_dwordx4 v[36:39], v3, s[50:51] offset:80
	global_load_dwordx4 v[40:43], v3, s[52:53] offset:64
	global_load_dwordx4 v[44:47], v3, s[52:53] offset:80
	v_lshlrev_b32_e32 v7, 3, v198
	v_lshl_or_b32 v4, s56, 9, v7
	s_add_u32 s58, s96, 0x100000
	s_addc_u32 s59, s97, 0
	global_load_dwordx2 v[8:9], v4, s[58:59]
	v_lshrrev_b32_e32 v5, 1, v177
	v_and_b32_e32 v6, 1, v177
	v_lshl_or_b32 v5, v6, 4, v5
	v_lshlrev_b32_e32 v5, 12, v5
	v_lshl_or_b32 v5, v2, 4, v5
	v_add_u32_e32 v6, 0x20000, v5
	s_lshr_b32 s54, s88, 7
	s_lshl_b32 s54, s54, 18
	s_lshl_b32 s60, s56, 5
	s_add_u32 s54, s54, s60
	s_add_u32 s54, s54, 0x39600000
	s_add_u32 s54, s96, s54
	s_addc_u32 s55, s97, 0
	s_lshl_b32 s48, s88, 9
	s_add_u32 s48, s48, 0x400000
	s_add_u32 s48, s96, s48
	s_addc_u32 s49, s97, 0
	global_load_dwordx4 v[80:83], v5, s[54:55]
	global_load_dwordx4 v[84:87], v6, s[54:55]
	s_add_u32 s54, s54, 0x400000
	s_addc_u32 s55, s55, 0
	global_load_dwordx4 v[88:91], v5, s[54:55]
	global_load_dwordx4 v[92:95], v6, s[54:55]
	s_add_u32 s54, s54, 0x400000
	s_addc_u32 s55, s55, 0
	global_load_dwordx4 v[96:99], v5, s[54:55]
	global_load_dwordx4 v[100:103], v6, s[54:55]
	s_add_u32 s54, s54, 0x400000
	s_addc_u32 s55, s55, 0
	global_load_dwordx4 v[104:107], v5, s[54:55]
	global_load_dwordx4 v[108:111], v6, s[54:55]
	s_add_u32 s54, s54, 0x400000
	s_addc_u32 s55, s55, 0
	s_waitcnt vmcnt(15)
	v_cvt_pk_bf16_f32 v48, v16, v17
	s_nop 0
	v_lshlrev_b32_e32 v14, 16, v48
	v_and_b32_e32 v15, 0xffff0000, v48
	v_sub_f32_e32 v14, v16, v14
	v_sub_f32_e32 v15, v17, v15
	v_cvt_pk_bf16_f32 v64, v14, v15
	v_cvt_pk_bf16_f32 v49, v18, v19
	s_nop 0
	v_lshlrev_b32_e32 v14, 16, v49
	v_and_b32_e32 v15, 0xffff0000, v49
	v_sub_f32_e32 v14, v18, v14
	v_sub_f32_e32 v15, v19, v15
	v_cvt_pk_bf16_f32 v65, v14, v15
	v_cvt_pk_bf16_f32 v50, v20, v21
	s_nop 0
	v_lshlrev_b32_e32 v14, 16, v50
	v_and_b32_e32 v15, 0xffff0000, v50
	v_sub_f32_e32 v14, v20, v14
	v_sub_f32_e32 v15, v21, v15
	v_cvt_pk_bf16_f32 v66, v14, v15
	v_cvt_pk_bf16_f32 v51, v22, v23
	s_nop 0
	v_lshlrev_b32_e32 v14, 16, v51
	v_and_b32_e32 v15, 0xffff0000, v51
	v_sub_f32_e32 v14, v22, v14
	v_sub_f32_e32 v15, v23, v15
	v_cvt_pk_bf16_f32 v67, v14, v15
	s_waitcnt vmcnt(13)
	v_cvt_pk_bf16_f32 v52, v24, v25
	s_nop 0
	v_lshlrev_b32_e32 v14, 16, v52
	v_and_b32_e32 v15, 0xffff0000, v52
	v_sub_f32_e32 v14, v24, v14
	v_sub_f32_e32 v15, v25, v15
	v_cvt_pk_bf16_f32 v68, v14, v15
	v_cvt_pk_bf16_f32 v53, v26, v27
	s_nop 0
	v_lshlrev_b32_e32 v14, 16, v53
	v_and_b32_e32 v15, 0xffff0000, v53
	v_sub_f32_e32 v14, v26, v14
	v_sub_f32_e32 v15, v27, v15
	v_cvt_pk_bf16_f32 v69, v14, v15
	v_cvt_pk_bf16_f32 v54, v28, v29
	s_nop 0
	v_lshlrev_b32_e32 v14, 16, v54
	v_and_b32_e32 v15, 0xffff0000, v54
	v_sub_f32_e32 v14, v28, v14
	v_sub_f32_e32 v15, v29, v15
	v_cvt_pk_bf16_f32 v70, v14, v15
	v_cvt_pk_bf16_f32 v55, v30, v31
	s_nop 0
	v_lshlrev_b32_e32 v14, 16, v55
	v_and_b32_e32 v15, 0xffff0000, v55
	v_sub_f32_e32 v14, v30, v14
	v_sub_f32_e32 v15, v31, v15
	v_cvt_pk_bf16_f32 v71, v14, v15
	s_waitcnt vmcnt(11)
	v_cvt_pk_bf16_f32 v56, v32, v33
	s_nop 0
	v_lshlrev_b32_e32 v14, 16, v56
	v_and_b32_e32 v15, 0xffff0000, v56
	v_sub_f32_e32 v14, v32, v14
	v_sub_f32_e32 v15, v33, v15
	v_cvt_pk_bf16_f32 v72, v14, v15
	v_cvt_pk_bf16_f32 v57, v34, v35
	s_nop 0
	v_lshlrev_b32_e32 v14, 16, v57
	v_and_b32_e32 v15, 0xffff0000, v57
	v_sub_f32_e32 v14, v34, v14
	v_sub_f32_e32 v15, v35, v15
	v_cvt_pk_bf16_f32 v73, v14, v15
	v_cvt_pk_bf16_f32 v58, v36, v37
	s_nop 0
	v_lshlrev_b32_e32 v14, 16, v58
	v_and_b32_e32 v15, 0xffff0000, v58
	v_sub_f32_e32 v14, v36, v14
	v_sub_f32_e32 v15, v37, v15
	v_cvt_pk_bf16_f32 v74, v14, v15
	v_cvt_pk_bf16_f32 v59, v38, v39
	s_nop 0
	v_lshlrev_b32_e32 v14, 16, v59
	v_and_b32_e32 v15, 0xffff0000, v59
	v_sub_f32_e32 v14, v38, v14
	v_sub_f32_e32 v15, v39, v15
	v_cvt_pk_bf16_f32 v75, v14, v15
	s_waitcnt vmcnt(9)
	v_cvt_pk_bf16_f32 v60, v40, v41
	s_nop 0
	v_lshlrev_b32_e32 v14, 16, v60
	v_and_b32_e32 v15, 0xffff0000, v60
	v_sub_f32_e32 v14, v40, v14
	v_sub_f32_e32 v15, v41, v15
	v_cvt_pk_bf16_f32 v76, v14, v15
	v_cvt_pk_bf16_f32 v61, v42, v43
	s_nop 0
	v_lshlrev_b32_e32 v14, 16, v61
	v_and_b32_e32 v15, 0xffff0000, v61
	v_sub_f32_e32 v14, v42, v14
	v_sub_f32_e32 v15, v43, v15
	v_cvt_pk_bf16_f32 v77, v14, v15
	v_cvt_pk_bf16_f32 v62, v44, v45
	s_nop 0
	v_lshlrev_b32_e32 v14, 16, v62
	v_and_b32_e32 v15, 0xffff0000, v62
	v_sub_f32_e32 v14, v44, v14
	v_sub_f32_e32 v15, v45, v15
	v_cvt_pk_bf16_f32 v78, v14, v15
	v_cvt_pk_bf16_f32 v63, v46, v47
	s_nop 0
	v_lshlrev_b32_e32 v14, 16, v63
	v_and_b32_e32 v15, 0xffff0000, v63
	v_sub_f32_e32 v14, v46, v14
	v_sub_f32_e32 v15, v47, v15
	v_cvt_pk_bf16_f32 v79, v14, v15
	s_waitcnt vmcnt(8)
; #define LDS_WAIT() asm volatile("s_waitcnt lgkmcnt(0)" ::: "memory")
; __device__ __forceinline__ void p5_phase(Frame& F) {
;     ...
;     for (int it = F.gw; it < NB * NCH * NGRP; it += F.ngw) {
;         bf16x8 afr[4];
; #pragma unroll
;         for (int sub = 0; sub < 4; ++sub) afr[sub] = nfr[sub];
;         if (it + F.ngw < NB * NCH * NGRP) { const int bc = (it + F.ngw) >> 7, r0 = (bc / NCH) * SEQ + (bc % NCH) * TCH;
; #pragma unroll
;             for (int sub = 0; sub < 4; ++sub) nfr[sub] = ssm_load_afrag(U, r0 + 16 * sub, g, F.lane); }
;         float sr = 0.f, si = 0.f;
; #pragma unroll
;         for (int sub = 0; sub < 4; ++sub) {
;             ssm_bu16(afr[sub], bf, bubuf, F.lane);
; #pragma unroll
;             for (int tt = 0; tt < 16; ++tt) { const float bur = bubuf[tt * BUP + F.lane], bui = bubuf[tt * BUP + 64 + F.lane];
;                 const float nr = fmaf(ab.x, sr, fmaf(-ab.y, si, bur)), ni = fmaf(ab.x, si, fmaf(ab.y, sr, bui)); sr = nr; si = ni; }
;             LDS_WAIT(); asm volatile("" ::: "memory");
;         }
	v_xor_b32_e32 v10, 0x80000000, v9
	v_mov_b32_e32 v178, v8
	v_mov_b32_e32 v179, v9
	v_mul_f32_e32 v181, v179, v179
	v_mul_f32_e32 v179, v178, v179
	v_fma_f32 v178, v178, v178, -v181
	v_add_f32_e32 v179, v179, v179
	v_mul_f32_e32 v181, v179, v179
	v_mul_f32_e32 v179, v178, v179
	v_fma_f32 v178, v178, v178, -v181
	v_add_f32_e32 v179, v179, v179
	v_mul_f32_e32 v181, v179, v179
	v_mul_f32_e32 v179, v178, v179
	v_fma_f32 v178, v178, v178, -v181
	v_add_f32_e32 v179, v179, v179
	v_mul_f32_e32 v181, v179, v179
	v_mul_f32_e32 v179, v178, v179
	v_fma_f32 v178, v178, v178, -v181
	v_add_f32_e32 v179, v179, v179
	v_xor_b32_e32 v180, 0x80000000, v179
	s_nop 1
	s_waitcnt vmcnt(7)
	v_mfma_f32_32x32x16_bf16 v[112:127], v[80:83], v[48:51], 0
	v_mfma_f32_32x32x16_bf16 v[128:143], v[80:83], v[52:55], 0
	v_mfma_f32_32x32x16_bf16 v[144:159], v[80:83], v[56:59], 0
	v_mfma_f32_32x32x16_bf16 v[160:175], v[80:83], v[60:63], 0
	v_mfma_f32_32x32x16_bf16 v[112:127], v[80:83], v[64:67], v[112:127]
	v_mfma_f32_32x32x16_bf16 v[128:143], v[80:83], v[68:71], v[128:143]
	v_mfma_f32_32x32x16_bf16 v[144:159], v[80:83], v[72:75], v[144:159]
	v_mfma_f32_32x32x16_bf16 v[160:175], v[80:83], v[76:79], v[160:175]
	v_mov_b32_e32 v12, 0
	v_mov_b32_e32 v13, 0
	v_mov_b32_e32 v14, 0
	v_mov_b32_e32 v15, 0
	s_nop 15
	s_nop 3
	v_permlane32_swap_b32_e32 v112, v128
	v_permlane32_swap_b32_e32 v144, v160
	v_permlane32_swap_b32_e32 v113, v129
	v_permlane32_swap_b32_e32 v145, v161
	v_permlane32_swap_b32_e32 v114, v130
	v_permlane32_swap_b32_e32 v146, v162
	v_permlane32_swap_b32_e32 v115, v131
	v_permlane32_swap_b32_e32 v147, v163
	v_pk_fma_f32 v[112:113], v[10:11], v[14:15], v[112:113] op_sel_hi:[0,1,1]
	v_pk_fma_f32 v[144:145], v[8:9], v[12:13], v[144:145] op_sel:[1,0,0]
	v_permlane32_swap_b32_e32 v116, v132
	v_pk_fma_f32 v[12:13], v[8:9], v[12:13], v[112:113] op_sel_hi:[0,1,1]
	v_pk_fma_f32 v[14:15], v[8:9], v[14:15], v[144:145] op_sel_hi:[0,1,1]
	v_permlane32_swap_b32_e32 v148, v164
	s_waitcnt vmcnt(6)
	v_mfma_f32_32x32x16_bf16 v[16:31], v[84:87], v[48:51], 0
	v_pk_fma_f32 v[114:115], v[10:11], v[14:15], v[114:115] op_sel_hi:[0,1,1]
	v_pk_fma_f32 v[146:147], v[8:9], v[12:13], v[146:147] op_sel:[1,0,0]
	v_permlane32_swap_b32_e32 v117, v133
	v_pk_fma_f32 v[12:13], v[8:9], v[12:13], v[114:115] op_sel_hi:[0,1,1]
	v_pk_fma_f32 v[14:15], v[8:9], v[14:15], v[146:147] op_sel_hi:[0,1,1]
	v_permlane32_swap_b32_e32 v149, v165
	v_mfma_f32_32x32x16_bf16 v[32:47], v[84:87], v[52:55], 0
	v_pk_fma_f32 v[128:129], v[10:11], v[14:15], v[128:129] op_sel_hi:[0,1,1]
	v_pk_fma_f32 v[160:161], v[8:9], v[12:13], v[160:161] op_sel:[1,0,0]
	v_permlane32_swap_b32_e32 v118, v134
	v_pk_fma_f32 v[12:13], v[8:9], v[12:13], v[128:129] op_sel_hi:[0,1,1]
	v_pk_fma_f32 v[14:15], v[8:9], v[14:15], v[160:161] op_sel_hi:[0,1,1]
	v_permlane32_swap_b32_e32 v150, v166
	v_mfma_f32_32x32x16_bf16 v[200:215], v[84:87], v[56:59], 0
	v_pk_fma_f32 v[130:131], v[10:11], v[14:15], v[130:131] op_sel_hi:[0,1,1]
	v_pk_fma_f32 v[162:163], v[8:9], v[12:13], v[162:163] op_sel:[1,0,0]
	v_permlane32_swap_b32_e32 v119, v135
	v_pk_fma_f32 v[12:13], v[8:9], v[12:13], v[130:131] op_sel_hi:[0,1,1]
	v_pk_fma_f32 v[14:15], v[8:9], v[14:15], v[162:163] op_sel_hi:[0,1,1]
	v_permlane32_swap_b32_e32 v151, v167
	v_mfma_f32_32x32x16_bf16 v[216:231], v[84:87], v[60:63], 0
	v_pk_fma_f32 v[116:117], v[10:11], v[14:15], v[116:117] op_sel_hi:[0,1,1]
	v_pk_fma_f32 v[148:149], v[8:9], v[12:13], v[148:149] op_sel:[1,0,0]
	v_permlane32_swap_b32_e32 v120, v136
	v_pk_fma_f32 v[12:13], v[8:9], v[12:13], v[116:117] op_sel_hi:[0,1,1]
	v_pk_fma_f32 v[14:15], v[8:9], v[14:15], v[148:149] op_sel_hi:[0,1,1]
	v_permlane32_swap_b32_e32 v152, v168
	v_mfma_f32_32x32x16_bf16 v[16:31], v[84:87], v[64:67], v[16:31]
	v_pk_fma_f32 v[118:119], v[10:11], v[14:15], v[118:119] op_sel_hi:[0,1,1]
	v_pk_fma_f32 v[150:151], v[8:9], v[12:13], v[150:151] op_sel:[1,0,0]
	v_permlane32_swap_b32_e32 v121, v137
	v_pk_fma_f32 v[12:13], v[8:9], v[12:13], v[118:119] op_sel_hi:[0,1,1]
	v_pk_fma_f32 v[14:15], v[8:9], v[14:15], v[150:151] op_sel_hi:[0,1,1]
	v_permlane32_swap_b32_e32 v153, v169
	v_mfma_f32_32x32x16_bf16 v[32:47], v[84:87], v[68:71], v[32:47]
	v_pk_fma_f32 v[132:133], v[10:11], v[14:15], v[132:133] op_sel_hi:[0,1,1]
	v_pk_fma_f32 v[164:165], v[8:9], v[12:13], v[164:165] op_sel:[1,0,0]
	v_permlane32_swap_b32_e32 v122, v138
	v_pk_fma_f32 v[12:13], v[8:9], v[12:13], v[132:133] op_sel_hi:[0,1,1]
	v_pk_fma_f32 v[14:15], v[8:9], v[14:15], v[164:165] op_sel_hi:[0,1,1]
	v_permlane32_swap_b32_e32 v154, v170
	v_mfma_f32_32x32x16_bf16 v[200:215], v[84:87], v[72:75], v[200:215]
	v_pk_fma_f32 v[134:135], v[10:11], v[14:15], v[134:135] op_sel_hi:[0,1,1]
	v_pk_fma_f32 v[166:167], v[8:9], v[12:13], v[166:167] op_sel:[1,0,0]
	v_permlane32_swap_b32_e32 v123, v139
	v_pk_fma_f32 v[12:13], v[8:9], v[12:13], v[134:135] op_sel_hi:[0,1,1]
	v_pk_fma_f32 v[14:15], v[8:9], v[14:15], v[166:167] op_sel_hi:[0,1,1]
	v_permlane32_swap_b32_e32 v155, v171
	v_mfma_f32_32x32x16_bf16 v[216:231], v[84:87], v[76:79], v[216:231]
	v_pk_fma_f32 v[120:121], v[10:11], v[14:15], v[120:121] op_sel_hi:[0,1,1]
	v_pk_fma_f32 v[152:153], v[8:9], v[12:13], v[152:153] op_sel:[1,0,0]
	v_permlane32_swap_b32_e32 v124, v140
	v_pk_fma_f32 v[12:13], v[8:9], v[12:13], v[120:121] op_sel_hi:[0,1,1]
	v_pk_fma_f32 v[14:15], v[8:9], v[14:15], v[152:153] op_sel_hi:[0,1,1]
	v_permlane32_swap_b32_e32 v156, v172
	v_pk_fma_f32 v[122:123], v[10:11], v[14:15], v[122:123] op_sel_hi:[0,1,1]
	v_pk_fma_f32 v[154:155], v[8:9], v[12:13], v[154:155] op_sel:[1,0,0]
	v_permlane32_swap_b32_e32 v125, v141
	v_pk_fma_f32 v[12:13], v[8:9], v[12:13], v[122:123] op_sel_hi:[0,1,1]
; #define LDS_WAIT() asm volatile("s_waitcnt lgkmcnt(0)" ::: "memory")
; __device__ __forceinline__ void p5_phase(Frame& F) {
;     ...
;     for (int it = F.gw; it < NB * NCH * NGRP; it += F.ngw) {
;         bf16x8 afr[4];
; #pragma unroll
;         for (int sub = 0; sub < 4; ++sub) afr[sub] = nfr[sub];
;         if (it + F.ngw < NB * NCH * NGRP) { const int bc = (it + F.ngw) >> 7, r0 = (bc / NCH) * SEQ + (bc % NCH) * TCH;
; #pragma unroll
;             for (int sub = 0; sub < 4; ++sub) nfr[sub] = ssm_load_afrag(U, r0 + 16 * sub, g, F.lane); }
;         float sr = 0.f, si = 0.f;
; #pragma unroll
;         for (int sub = 0; sub < 4; ++sub) {
;             ssm_bu16(afr[sub], bf, bubuf, F.lane);
; #pragma unroll
;             for (int tt = 0; tt < 16; ++tt) { const float bur = bubuf[tt * BUP + F.lane], bui = bubuf[tt * BUP + 64 + F.lane];
;                 const float nr = fmaf(ab.x, sr, fmaf(-ab.y, si, bur)), ni = fmaf(ab.x, si, fmaf(ab.y, sr, bui)); sr = nr; si = ni; }
;             LDS_WAIT(); asm volatile("" ::: "memory");
;         }
	v_pk_fma_f32 v[14:15], v[8:9], v[14:15], v[154:155] op_sel_hi:[0,1,1]
	v_permlane32_swap_b32_e32 v157, v173
	v_pk_fma_f32 v[136:137], v[10:11], v[14:15], v[136:137] op_sel_hi:[0,1,1]
	v_pk_fma_f32 v[168:169], v[8:9], v[12:13], v[168:169] op_sel:[1,0,0]
	v_permlane32_swap_b32_e32 v126, v142
	v_pk_fma_f32 v[12:13], v[8:9], v[12:13], v[136:137] op_sel_hi:[0,1,1]
	v_pk_fma_f32 v[14:15], v[8:9], v[14:15], v[168:169] op_sel_hi:[0,1,1]
	v_permlane32_swap_b32_e32 v158, v174
	v_pk_fma_f32 v[138:139], v[10:11], v[14:15], v[138:139] op_sel_hi:[0,1,1]
	v_pk_fma_f32 v[170:171], v[8:9], v[12:13], v[170:171] op_sel:[1,0,0]
	v_permlane32_swap_b32_e32 v127, v143
	v_pk_fma_f32 v[12:13], v[8:9], v[12:13], v[138:139] op_sel_hi:[0,1,1]
	v_pk_fma_f32 v[14:15], v[8:9], v[14:15], v[170:171] op_sel_hi:[0,1,1]
	v_permlane32_swap_b32_e32 v159, v175
	v_pk_fma_f32 v[124:125], v[10:11], v[14:15], v[124:125] op_sel_hi:[0,1,1]
	v_pk_fma_f32 v[156:157], v[8:9], v[12:13], v[156:157] op_sel:[1,0,0]
	s_nop 0
	v_pk_fma_f32 v[12:13], v[8:9], v[12:13], v[124:125] op_sel_hi:[0,1,1]
	v_pk_fma_f32 v[14:15], v[8:9], v[14:15], v[156:157] op_sel_hi:[0,1,1]
	s_nop 0
	v_pk_fma_f32 v[126:127], v[10:11], v[14:15], v[126:127] op_sel_hi:[0,1,1]
	v_pk_fma_f32 v[158:159], v[8:9], v[12:13], v[158:159] op_sel:[1,0,0]
	s_nop 0
	v_pk_fma_f32 v[12:13], v[8:9], v[12:13], v[126:127] op_sel_hi:[0,1,1]
	v_pk_fma_f32 v[14:15], v[8:9], v[14:15], v[158:159] op_sel_hi:[0,1,1]
	s_nop 0
	v_pk_fma_f32 v[140:141], v[10:11], v[14:15], v[140:141] op_sel_hi:[0,1,1]
	v_pk_fma_f32 v[172:173], v[8:9], v[12:13], v[172:173] op_sel:[1,0,0]
	s_nop 0
	v_pk_fma_f32 v[12:13], v[8:9], v[12:13], v[140:141] op_sel_hi:[0,1,1]
	v_pk_fma_f32 v[14:15], v[8:9], v[14:15], v[172:173] op_sel_hi:[0,1,1]
	s_nop 0
	v_pk_fma_f32 v[142:143], v[10:11], v[14:15], v[142:143] op_sel_hi:[0,1,1]
	v_pk_fma_f32 v[174:175], v[8:9], v[12:13], v[174:175] op_sel:[1,0,0]
	s_nop 0
	v_pk_fma_f32 v[12:13], v[8:9], v[12:13], v[142:143] op_sel_hi:[0,1,1]
	v_pk_fma_f32 v[14:15], v[8:9], v[14:15], v[174:175] op_sel_hi:[0,1,1]
	s_nop 0
	s_nop 0
	v_fma_f32 v181, v180, v14, v13
	v_fma_f32 v182, v179, v12, v15
	v_fma_f32 v12, v178, v12, v181
	v_fma_f32 v14, v178, v14, v182
	v_mov_b32_e32 v13, 0
	v_mov_b32_e32 v15, 0
	s_nop 3
	v_permlane32_swap_b32_e32 v16, v32
	v_permlane32_swap_b32_e32 v200, v216
	v_permlane32_swap_b32_e32 v17, v33
	v_permlane32_swap_b32_e32 v201, v217
	v_permlane32_swap_b32_e32 v18, v34
	v_permlane32_swap_b32_e32 v202, v218
	v_permlane32_swap_b32_e32 v19, v35
	v_permlane32_swap_b32_e32 v203, v219
	v_pk_fma_f32 v[16:17], v[10:11], v[14:15], v[16:17] op_sel_hi:[0,1,1]
	v_pk_fma_f32 v[200:201], v[8:9], v[12:13], v[200:201] op_sel:[1,0,0]
	v_permlane32_swap_b32_e32 v20, v36
	v_pk_fma_f32 v[12:13], v[8:9], v[12:13], v[16:17] op_sel_hi:[0,1,1]
	v_pk_fma_f32 v[14:15], v[8:9], v[14:15], v[200:201] op_sel_hi:[0,1,1]
	v_permlane32_swap_b32_e32 v204, v220
	s_waitcnt vmcnt(5)
	v_mfma_f32_32x32x16_bf16 v[112:127], v[88:91], v[48:51], 0
	v_pk_fma_f32 v[18:19], v[10:11], v[14:15], v[18:19] op_sel_hi:[0,1,1]
	v_pk_fma_f32 v[202:203], v[8:9], v[12:13], v[202:203] op_sel:[1,0,0]
	v_permlane32_swap_b32_e32 v21, v37
	v_pk_fma_f32 v[12:13], v[8:9], v[12:13], v[18:19] op_sel_hi:[0,1,1]
	v_pk_fma_f32 v[14:15], v[8:9], v[14:15], v[202:203] op_sel_hi:[0,1,1]
	v_permlane32_swap_b32_e32 v205, v221
	v_mfma_f32_32x32x16_bf16 v[128:143], v[88:91], v[52:55], 0
	v_pk_fma_f32 v[32:33], v[10:11], v[14:15], v[32:33] op_sel_hi:[0,1,1]
	v_pk_fma_f32 v[216:217], v[8:9], v[12:13], v[216:217] op_sel:[1,0,0]
	v_permlane32_swap_b32_e32 v22, v38
	v_pk_fma_f32 v[12:13], v[8:9], v[12:13], v[32:33] op_sel_hi:[0,1,1]
	v_pk_fma_f32 v[14:15], v[8:9], v[14:15], v[216:217] op_sel_hi:[0,1,1]
	v_permlane32_swap_b32_e32 v206, v222
	v_mfma_f32_32x32x16_bf16 v[144:159], v[88:91], v[56:59], 0
	v_pk_fma_f32 v[34:35], v[10:11], v[14:15], v[34:35] op_sel_hi:[0,1,1]
	v_pk_fma_f32 v[218:219], v[8:9], v[12:13], v[218:219] op_sel:[1,0,0]
	v_permlane32_swap_b32_e32 v23, v39
	v_pk_fma_f32 v[12:13], v[8:9], v[12:13], v[34:35] op_sel_hi:[0,1,1]
	v_pk_fma_f32 v[14:15], v[8:9], v[14:15], v[218:219] op_sel_hi:[0,1,1]
	v_permlane32_swap_b32_e32 v207, v223
	v_mfma_f32_32x32x16_bf16 v[160:175], v[88:91], v[60:63], 0
	v_pk_fma_f32 v[20:21], v[10:11], v[14:15], v[20:21] op_sel_hi:[0,1,1]
	v_pk_fma_f32 v[204:205], v[8:9], v[12:13], v[204:205] op_sel:[1,0,0]
	v_permlane32_swap_b32_e32 v24, v40
	v_pk_fma_f32 v[12:13], v[8:9], v[12:13], v[20:21] op_sel_hi:[0,1,1]
	v_pk_fma_f32 v[14:15], v[8:9], v[14:15], v[204:205] op_sel_hi:[0,1,1]
	v_permlane32_swap_b32_e32 v208, v224
	v_mfma_f32_32x32x16_bf16 v[112:127], v[88:91], v[64:67], v[112:127]
	v_pk_fma_f32 v[22:23], v[10:11], v[14:15], v[22:23] op_sel_hi:[0,1,1]
	v_pk_fma_f32 v[206:207], v[8:9], v[12:13], v[206:207] op_sel:[1,0,0]
	v_permlane32_swap_b32_e32 v25, v41
	v_pk_fma_f32 v[12:13], v[8:9], v[12:13], v[22:23] op_sel_hi:[0,1,1]
	v_pk_fma_f32 v[14:15], v[8:9], v[14:15], v[206:207] op_sel_hi:[0,1,1]
	v_permlane32_swap_b32_e32 v209, v225
	v_mfma_f32_32x32x16_bf16 v[128:143], v[88:91], v[68:71], v[128:143]
	v_pk_fma_f32 v[36:37], v[10:11], v[14:15], v[36:37] op_sel_hi:[0,1,1]
	v_pk_fma_f32 v[220:221], v[8:9], v[12:13], v[220:221] op_sel:[1,0,0]
	v_permlane32_swap_b32_e32 v26, v42
	v_pk_fma_f32 v[12:13], v[8:9], v[12:13], v[36:37] op_sel_hi:[0,1,1]
	v_pk_fma_f32 v[14:15], v[8:9], v[14:15], v[220:221] op_sel_hi:[0,1,1]
	v_permlane32_swap_b32_e32 v210, v226
	v_mfma_f32_32x32x16_bf16 v[144:159], v[88:91], v[72:75], v[144:159]
	v_pk_fma_f32 v[38:39], v[10:11], v[14:15], v[38:39] op_sel_hi:[0,1,1]
	v_pk_fma_f32 v[222:223], v[8:9], v[12:13], v[222:223] op_sel:[1,0,0]
; #define LDS_WAIT() asm volatile("s_waitcnt lgkmcnt(0)" ::: "memory")
; __device__ __forceinline__ void p5_phase(Frame& F) {
;     ...
;     for (int it = F.gw; it < NB * NCH * NGRP; it += F.ngw) {
;         bf16x8 afr[4];
; #pragma unroll
;         for (int sub = 0; sub < 4; ++sub) afr[sub] = nfr[sub];
;         if (it + F.ngw < NB * NCH * NGRP) { const int bc = (it + F.ngw) >> 7, r0 = (bc / NCH) * SEQ + (bc % NCH) * TCH;
; #pragma unroll
;             for (int sub = 0; sub < 4; ++sub) nfr[sub] = ssm_load_afrag(U, r0 + 16 * sub, g, F.lane); }
;         float sr = 0.f, si = 0.f;
; #pragma unroll
;         for (int sub = 0; sub < 4; ++sub) {
;             ssm_bu16(afr[sub], bf, bubuf, F.lane);
; #pragma unroll
;             for (int tt = 0; tt < 16; ++tt) { const float bur = bubuf[tt * BUP + F.lane], bui = bubuf[tt * BUP + 64 + F.lane];
;                 const float nr = fmaf(ab.x, sr, fmaf(-ab.y, si, bur)), ni = fmaf(ab.x, si, fmaf(ab.y, sr, bui)); sr = nr; si = ni; }
;             LDS_WAIT(); asm volatile("" ::: "memory");
;         }
;         ((f32x2*)(F.ws + WS_E))[(size_t)it * NST + F.lane] = (f32x2){sr, si};
	v_permlane32_swap_b32_e32 v27, v43
	v_pk_fma_f32 v[12:13], v[8:9], v[12:13], v[38:39] op_sel_hi:[0,1,1]
	v_pk_fma_f32 v[14:15], v[8:9], v[14:15], v[222:223] op_sel_hi:[0,1,1]
	v_permlane32_swap_b32_e32 v211, v227
	v_mfma_f32_32x32x16_bf16 v[160:175], v[88:91], v[76:79], v[160:175]
	v_pk_fma_f32 v[24:25], v[10:11], v[14:15], v[24:25] op_sel_hi:[0,1,1]
	v_pk_fma_f32 v[208:209], v[8:9], v[12:13], v[208:209] op_sel:[1,0,0]
	v_permlane32_swap_b32_e32 v28, v44
	v_pk_fma_f32 v[12:13], v[8:9], v[12:13], v[24:25] op_sel_hi:[0,1,1]
	v_pk_fma_f32 v[14:15], v[8:9], v[14:15], v[208:209] op_sel_hi:[0,1,1]
	v_permlane32_swap_b32_e32 v212, v228
	v_pk_fma_f32 v[26:27], v[10:11], v[14:15], v[26:27] op_sel_hi:[0,1,1]
	v_pk_fma_f32 v[210:211], v[8:9], v[12:13], v[210:211] op_sel:[1,0,0]
	v_permlane32_swap_b32_e32 v29, v45
	v_pk_fma_f32 v[12:13], v[8:9], v[12:13], v[26:27] op_sel_hi:[0,1,1]
	v_pk_fma_f32 v[14:15], v[8:9], v[14:15], v[210:211] op_sel_hi:[0,1,1]
	v_permlane32_swap_b32_e32 v213, v229
	v_pk_fma_f32 v[40:41], v[10:11], v[14:15], v[40:41] op_sel_hi:[0,1,1]
	v_pk_fma_f32 v[224:225], v[8:9], v[12:13], v[224:225] op_sel:[1,0,0]
	v_permlane32_swap_b32_e32 v30, v46
	v_pk_fma_f32 v[12:13], v[8:9], v[12:13], v[40:41] op_sel_hi:[0,1,1]
	v_pk_fma_f32 v[14:15], v[8:9], v[14:15], v[224:225] op_sel_hi:[0,1,1]
	v_permlane32_swap_b32_e32 v214, v230
	v_pk_fma_f32 v[42:43], v[10:11], v[14:15], v[42:43] op_sel_hi:[0,1,1]
	v_pk_fma_f32 v[226:227], v[8:9], v[12:13], v[226:227] op_sel:[1,0,0]
	v_permlane32_swap_b32_e32 v31, v47
	v_pk_fma_f32 v[12:13], v[8:9], v[12:13], v[42:43] op_sel_hi:[0,1,1]
	v_pk_fma_f32 v[14:15], v[8:9], v[14:15], v[226:227] op_sel_hi:[0,1,1]
	v_permlane32_swap_b32_e32 v215, v231
	v_pk_fma_f32 v[28:29], v[10:11], v[14:15], v[28:29] op_sel_hi:[0,1,1]
	v_pk_fma_f32 v[212:213], v[8:9], v[12:13], v[212:213] op_sel:[1,0,0]
	s_nop 0
	v_pk_fma_f32 v[12:13], v[8:9], v[12:13], v[28:29] op_sel_hi:[0,1,1]
	v_pk_fma_f32 v[14:15], v[8:9], v[14:15], v[212:213] op_sel_hi:[0,1,1]
	s_nop 0
	v_pk_fma_f32 v[30:31], v[10:11], v[14:15], v[30:31] op_sel_hi:[0,1,1]
	v_pk_fma_f32 v[214:215], v[8:9], v[12:13], v[214:215] op_sel:[1,0,0]
	s_nop 0
	v_pk_fma_f32 v[12:13], v[8:9], v[12:13], v[30:31] op_sel_hi:[0,1,1]
	v_pk_fma_f32 v[14:15], v[8:9], v[14:15], v[214:215] op_sel_hi:[0,1,1]
	s_nop 0
	v_pk_fma_f32 v[44:45], v[10:11], v[14:15], v[44:45] op_sel_hi:[0,1,1]
	v_pk_fma_f32 v[228:229], v[8:9], v[12:13], v[228:229] op_sel:[1,0,0]
	s_nop 0
	v_pk_fma_f32 v[12:13], v[8:9], v[12:13], v[44:45] op_sel_hi:[0,1,1]
	v_pk_fma_f32 v[14:15], v[8:9], v[14:15], v[228:229] op_sel_hi:[0,1,1]
	s_nop 0
	v_pk_fma_f32 v[46:47], v[10:11], v[14:15], v[46:47] op_sel_hi:[0,1,1]
	v_pk_fma_f32 v[230:231], v[8:9], v[12:13], v[230:231] op_sel:[1,0,0]
	s_nop 0
	v_pk_fma_f32 v[12:13], v[8:9], v[12:13], v[46:47] op_sel_hi:[0,1,1]
	v_pk_fma_f32 v[14:15], v[8:9], v[14:15], v[230:231] op_sel_hi:[0,1,1]
	s_nop 0
	s_nop 0
	v_fma_f32 v181, v180, v14, v13
	v_fma_f32 v182, v179, v12, v15
	v_fma_f32 v12, v178, v12, v181
	v_fma_f32 v14, v178, v14, v182
	v_mov_b32_e32 v13, 0
	v_mov_b32_e32 v15, 0
	v_mov_b32_e32 v182, v12
	v_mov_b32_e32 v183, v14
	global_store_dwordx2 v7, v[182:183], s[48:49]
	s_add_u32 s48, s48, 0x100000
	s_addc_u32 s49, s49, 0
	global_load_dwordx4 v[80:83], v5, s[54:55]
	global_load_dwordx4 v[84:87], v6, s[54:55]
	s_add_u32 s54, s54, 0x400000
	s_addc_u32 s55, s55, 0
	v_mov_b32_e32 v12, 0
	v_mov_b32_e32 v13, 0
	v_mov_b32_e32 v14, 0
	v_mov_b32_e32 v15, 0
	s_nop 3
	v_permlane32_swap_b32_e32 v112, v128
	v_permlane32_swap_b32_e32 v144, v160
	v_permlane32_swap_b32_e32 v113, v129
	v_permlane32_swap_b32_e32 v145, v161
	v_permlane32_swap_b32_e32 v114, v130
	v_permlane32_swap_b32_e32 v146, v162
	v_permlane32_swap_b32_e32 v115, v131
	v_permlane32_swap_b32_e32 v147, v163
	v_pk_fma_f32 v[112:113], v[10:11], v[14:15], v[112:113] op_sel_hi:[0,1,1]
	v_pk_fma_f32 v[144:145], v[8:9], v[12:13], v[144:145] op_sel:[1,0,0]
	v_permlane32_swap_b32_e32 v116, v132
	v_pk_fma_f32 v[12:13], v[8:9], v[12:13], v[112:113] op_sel_hi:[0,1,1]
	v_pk_fma_f32 v[14:15], v[8:9], v[14:15], v[144:145] op_sel_hi:[0,1,1]
	v_permlane32_swap_b32_e32 v148, v164
	s_waitcnt vmcnt(7)
	v_mfma_f32_32x32x16_bf16 v[16:31], v[92:95], v[48:51], 0
	v_pk_fma_f32 v[114:115], v[10:11], v[14:15], v[114:115] op_sel_hi:[0,1,1]
	v_pk_fma_f32 v[146:147], v[8:9], v[12:13], v[146:147] op_sel:[1,0,0]
	v_permlane32_swap_b32_e32 v117, v133
	v_pk_fma_f32 v[12:13], v[8:9], v[12:13], v[114:115] op_sel_hi:[0,1,1]
	v_pk_fma_f32 v[14:15], v[8:9], v[14:15], v[146:147] op_sel_hi:[0,1,1]
	v_permlane32_swap_b32_e32 v149, v165
	v_mfma_f32_32x32x16_bf16 v[32:47], v[92:95], v[52:55], 0
	v_pk_fma_f32 v[128:129], v[10:11], v[14:15], v[128:129] op_sel_hi:[0,1,1]
	v_pk_fma_f32 v[160:161], v[8:9], v[12:13], v[160:161] op_sel:[1,0,0]
	v_permlane32_swap_b32_e32 v118, v134
	v_pk_fma_f32 v[12:13], v[8:9], v[12:13], v[128:129] op_sel_hi:[0,1,1]
	v_pk_fma_f32 v[14:15], v[8:9], v[14:15], v[160:161] op_sel_hi:[0,1,1]
	v_permlane32_swap_b32_e32 v150, v166
	v_mfma_f32_32x32x16_bf16 v[200:215], v[92:95], v[56:59], 0
	v_pk_fma_f32 v[130:131], v[10:11], v[14:15], v[130:131] op_sel_hi:[0,1,1]
	v_pk_fma_f32 v[162:163], v[8:9], v[12:13], v[162:163] op_sel:[1,0,0]
	v_permlane32_swap_b32_e32 v119, v135
	v_pk_fma_f32 v[12:13], v[8:9], v[12:13], v[130:131] op_sel_hi:[0,1,1]
	v_pk_fma_f32 v[14:15], v[8:9], v[14:15], v[162:163] op_sel_hi:[0,1,1]
	v_permlane32_swap_b32_e32 v151, v167
	v_mfma_f32_32x32x16_bf16 v[216:231], v[92:95], v[60:63], 0
	v_pk_fma_f32 v[116:117], v[10:11], v[14:15], v[116:117] op_sel_hi:[0,1,1]
	v_pk_fma_f32 v[148:149], v[8:9], v[12:13], v[148:149] op_sel:[1,0,0]
; #define LDS_WAIT() asm volatile("s_waitcnt lgkmcnt(0)" ::: "memory")
; __device__ __forceinline__ void p5_phase(Frame& F) {
;     ...
;     for (int it = F.gw; it < NB * NCH * NGRP; it += F.ngw) {
;         bf16x8 afr[4];
; #pragma unroll
;         for (int sub = 0; sub < 4; ++sub) afr[sub] = nfr[sub];
;         if (it + F.ngw < NB * NCH * NGRP) { const int bc = (it + F.ngw) >> 7, r0 = (bc / NCH) * SEQ + (bc % NCH) * TCH;
; #pragma unroll
;             for (int sub = 0; sub < 4; ++sub) nfr[sub] = ssm_load_afrag(U, r0 + 16 * sub, g, F.lane); }
;         float sr = 0.f, si = 0.f;
; #pragma unroll
;         for (int sub = 0; sub < 4; ++sub) {
;             ssm_bu16(afr[sub], bf, bubuf, F.lane);
; #pragma unroll
;             for (int tt = 0; tt < 16; ++tt) { const float bur = bubuf[tt * BUP + F.lane], bui = bubuf[tt * BUP + 64 + F.lane];
;                 const float nr = fmaf(ab.x, sr, fmaf(-ab.y, si, bur)), ni = fmaf(ab.x, si, fmaf(ab.y, sr, bui)); sr = nr; si = ni; }
;             LDS_WAIT(); asm volatile("" ::: "memory");
;         }
	v_permlane32_swap_b32_e32 v120, v136
	v_pk_fma_f32 v[12:13], v[8:9], v[12:13], v[116:117] op_sel_hi:[0,1,1]
	v_pk_fma_f32 v[14:15], v[8:9], v[14:15], v[148:149] op_sel_hi:[0,1,1]
	v_permlane32_swap_b32_e32 v152, v168
	v_mfma_f32_32x32x16_bf16 v[16:31], v[92:95], v[64:67], v[16:31]
	v_pk_fma_f32 v[118:119], v[10:11], v[14:15], v[118:119] op_sel_hi:[0,1,1]
	v_pk_fma_f32 v[150:151], v[8:9], v[12:13], v[150:151] op_sel:[1,0,0]
	v_permlane32_swap_b32_e32 v121, v137
	v_pk_fma_f32 v[12:13], v[8:9], v[12:13], v[118:119] op_sel_hi:[0,1,1]
	v_pk_fma_f32 v[14:15], v[8:9], v[14:15], v[150:151] op_sel_hi:[0,1,1]
	v_permlane32_swap_b32_e32 v153, v169
	v_mfma_f32_32x32x16_bf16 v[32:47], v[92:95], v[68:71], v[32:47]
	v_pk_fma_f32 v[132:133], v[10:11], v[14:15], v[132:133] op_sel_hi:[0,1,1]
	v_pk_fma_f32 v[164:165], v[8:9], v[12:13], v[164:165] op_sel:[1,0,0]
	v_permlane32_swap_b32_e32 v122, v138
	v_pk_fma_f32 v[12:13], v[8:9], v[12:13], v[132:133] op_sel_hi:[0,1,1]
	v_pk_fma_f32 v[14:15], v[8:9], v[14:15], v[164:165] op_sel_hi:[0,1,1]
	v_permlane32_swap_b32_e32 v154, v170
	v_mfma_f32_32x32x16_bf16 v[200:215], v[92:95], v[72:75], v[200:215]
	v_pk_fma_f32 v[134:135], v[10:11], v[14:15], v[134:135] op_sel_hi:[0,1,1]
	v_pk_fma_f32 v[166:167], v[8:9], v[12:13], v[166:167] op_sel:[1,0,0]
	v_permlane32_swap_b32_e32 v123, v139
	v_pk_fma_f32 v[12:13], v[8:9], v[12:13], v[134:135] op_sel_hi:[0,1,1]
	v_pk_fma_f32 v[14:15], v[8:9], v[14:15], v[166:167] op_sel_hi:[0,1,1]
	v_permlane32_swap_b32_e32 v155, v171
	v_mfma_f32_32x32x16_bf16 v[216:231], v[92:95], v[76:79], v[216:231]
	v_pk_fma_f32 v[120:121], v[10:11], v[14:15], v[120:121] op_sel_hi:[0,1,1]
	v_pk_fma_f32 v[152:153], v[8:9], v[12:13], v[152:153] op_sel:[1,0,0]
	v_permlane32_swap_b32_e32 v124, v140
	v_pk_fma_f32 v[12:13], v[8:9], v[12:13], v[120:121] op_sel_hi:[0,1,1]
	v_pk_fma_f32 v[14:15], v[8:9], v[14:15], v[152:153] op_sel_hi:[0,1,1]
	v_permlane32_swap_b32_e32 v156, v172
	v_pk_fma_f32 v[122:123], v[10:11], v[14:15], v[122:123] op_sel_hi:[0,1,1]
	v_pk_fma_f32 v[154:155], v[8:9], v[12:13], v[154:155] op_sel:[1,0,0]
	v_permlane32_swap_b32_e32 v125, v141
	v_pk_fma_f32 v[12:13], v[8:9], v[12:13], v[122:123] op_sel_hi:[0,1,1]
	v_pk_fma_f32 v[14:15], v[8:9], v[14:15], v[154:155] op_sel_hi:[0,1,1]
	v_permlane32_swap_b32_e32 v157, v173
	v_pk_fma_f32 v[136:137], v[10:11], v[14:15], v[136:137] op_sel_hi:[0,1,1]
	v_pk_fma_f32 v[168:169], v[8:9], v[12:13], v[168:169] op_sel:[1,0,0]
	v_permlane32_swap_b32_e32 v126, v142
	v_pk_fma_f32 v[12:13], v[8:9], v[12:13], v[136:137] op_sel_hi:[0,1,1]
	v_pk_fma_f32 v[14:15], v[8:9], v[14:15], v[168:169] op_sel_hi:[0,1,1]
	v_permlane32_swap_b32_e32 v158, v174
	v_pk_fma_f32 v[138:139], v[10:11], v[14:15], v[138:139] op_sel_hi:[0,1,1]
	v_pk_fma_f32 v[170:171], v[8:9], v[12:13], v[170:171] op_sel:[1,0,0]
	v_permlane32_swap_b32_e32 v127, v143
	v_pk_fma_f32 v[12:13], v[8:9], v[12:13], v[138:139] op_sel_hi:[0,1,1]
	v_pk_fma_f32 v[14:15], v[8:9], v[14:15], v[170:171] op_sel_hi:[0,1,1]
	v_permlane32_swap_b32_e32 v159, v175
	v_pk_fma_f32 v[124:125], v[10:11], v[14:15], v[124:125] op_sel_hi:[0,1,1]
	v_pk_fma_f32 v[156:157], v[8:9], v[12:13], v[156:157] op_sel:[1,0,0]
	s_nop 0
	v_pk_fma_f32 v[12:13], v[8:9], v[12:13], v[124:125] op_sel_hi:[0,1,1]
	v_pk_fma_f32 v[14:15], v[8:9], v[14:15], v[156:157] op_sel_hi:[0,1,1]
	s_nop 0
	v_pk_fma_f32 v[126:127], v[10:11], v[14:15], v[126:127] op_sel_hi:[0,1,1]
	v_pk_fma_f32 v[158:159], v[8:9], v[12:13], v[158:159] op_sel:[1,0,0]
	s_nop 0
	v_pk_fma_f32 v[12:13], v[8:9], v[12:13], v[126:127] op_sel_hi:[0,1,1]
	v_pk_fma_f32 v[14:15], v[8:9], v[14:15], v[158:159] op_sel_hi:[0,1,1]
	s_nop 0
	v_pk_fma_f32 v[140:141], v[10:11], v[14:15], v[140:141] op_sel_hi:[0,1,1]
	v_pk_fma_f32 v[172:173], v[8:9], v[12:13], v[172:173] op_sel:[1,0,0]
	s_nop 0
	v_pk_fma_f32 v[12:13], v[8:9], v[12:13], v[140:141] op_sel_hi:[0,1,1]
	v_pk_fma_f32 v[14:15], v[8:9], v[14:15], v[172:173] op_sel_hi:[0,1,1]
	s_nop 0
	v_pk_fma_f32 v[142:143], v[10:11], v[14:15], v[142:143] op_sel_hi:[0,1,1]
	v_pk_fma_f32 v[174:175], v[8:9], v[12:13], v[174:175] op_sel:[1,0,0]
	s_nop 0
	v_pk_fma_f32 v[12:13], v[8:9], v[12:13], v[142:143] op_sel_hi:[0,1,1]
	v_pk_fma_f32 v[14:15], v[8:9], v[14:15], v[174:175] op_sel_hi:[0,1,1]
	s_nop 0
	s_nop 0
	v_fma_f32 v181, v180, v14, v13
	v_fma_f32 v182, v179, v12, v15
	v_fma_f32 v12, v178, v12, v181
	v_fma_f32 v14, v178, v14, v182
	v_mov_b32_e32 v13, 0
	v_mov_b32_e32 v15, 0
	s_nop 3
	v_permlane32_swap_b32_e32 v16, v32
	v_permlane32_swap_b32_e32 v200, v216
	v_permlane32_swap_b32_e32 v17, v33
	v_permlane32_swap_b32_e32 v201, v217
	v_permlane32_swap_b32_e32 v18, v34
	v_permlane32_swap_b32_e32 v202, v218
	v_permlane32_swap_b32_e32 v19, v35
	v_permlane32_swap_b32_e32 v203, v219
	v_pk_fma_f32 v[16:17], v[10:11], v[14:15], v[16:17] op_sel_hi:[0,1,1]
	v_pk_fma_f32 v[200:201], v[8:9], v[12:13], v[200:201] op_sel:[1,0,0]
	v_permlane32_swap_b32_e32 v20, v36
	v_pk_fma_f32 v[12:13], v[8:9], v[12:13], v[16:17] op_sel_hi:[0,1,1]
	v_pk_fma_f32 v[14:15], v[8:9], v[14:15], v[200:201] op_sel_hi:[0,1,1]
	v_permlane32_swap_b32_e32 v204, v220
	s_waitcnt vmcnt(6)
; #define LDS_WAIT() asm volatile("s_waitcnt lgkmcnt(0)" ::: "memory")
; __device__ __forceinline__ void p5_phase(Frame& F) {
;     ...
;     for (int it = F.gw; it < NB * NCH * NGRP; it += F.ngw) {
;         bf16x8 afr[4];
; #pragma unroll
;         for (int sub = 0; sub < 4; ++sub) afr[sub] = nfr[sub];
;         if (it + F.ngw < NB * NCH * NGRP) { const int bc = (it + F.ngw) >> 7, r0 = (bc / NCH) * SEQ + (bc % NCH) * TCH;
; #pragma unroll
;             for (int sub = 0; sub < 4; ++sub) nfr[sub] = ssm_load_afrag(U, r0 + 16 * sub, g, F.lane); }
;         float sr = 0.f, si = 0.f;
; #pragma unroll
;         for (int sub = 0; sub < 4; ++sub) {
;             ssm_bu16(afr[sub], bf, bubuf, F.lane);
; #pragma unroll
;             for (int tt = 0; tt < 16; ++tt) { const float bur = bubuf[tt * BUP + F.lane], bui = bubuf[tt * BUP + 64 + F.lane];
;                 const float nr = fmaf(ab.x, sr, fmaf(-ab.y, si, bur)), ni = fmaf(ab.x, si, fmaf(ab.y, sr, bui)); sr = nr; si = ni; }
;             LDS_WAIT(); asm volatile("" ::: "memory");
;         }
;         ((f32x2*)(F.ws + WS_E))[(size_t)it * NST + F.lane] = (f32x2){sr, si};
	v_mfma_f32_32x32x16_bf16 v[112:127], v[96:99], v[48:51], 0
	v_pk_fma_f32 v[18:19], v[10:11], v[14:15], v[18:19] op_sel_hi:[0,1,1]
	v_pk_fma_f32 v[202:203], v[8:9], v[12:13], v[202:203] op_sel:[1,0,0]
	v_permlane32_swap_b32_e32 v21, v37
	v_pk_fma_f32 v[12:13], v[8:9], v[12:13], v[18:19] op_sel_hi:[0,1,1]
	v_pk_fma_f32 v[14:15], v[8:9], v[14:15], v[202:203] op_sel_hi:[0,1,1]
	v_permlane32_swap_b32_e32 v205, v221
	v_mfma_f32_32x32x16_bf16 v[128:143], v[96:99], v[52:55], 0
	v_pk_fma_f32 v[32:33], v[10:11], v[14:15], v[32:33] op_sel_hi:[0,1,1]
	v_pk_fma_f32 v[216:217], v[8:9], v[12:13], v[216:217] op_sel:[1,0,0]
	v_permlane32_swap_b32_e32 v22, v38
	v_pk_fma_f32 v[12:13], v[8:9], v[12:13], v[32:33] op_sel_hi:[0,1,1]
	v_pk_fma_f32 v[14:15], v[8:9], v[14:15], v[216:217] op_sel_hi:[0,1,1]
	v_permlane32_swap_b32_e32 v206, v222
	v_mfma_f32_32x32x16_bf16 v[144:159], v[96:99], v[56:59], 0
	v_pk_fma_f32 v[34:35], v[10:11], v[14:15], v[34:35] op_sel_hi:[0,1,1]
	v_pk_fma_f32 v[218:219], v[8:9], v[12:13], v[218:219] op_sel:[1,0,0]
	v_permlane32_swap_b32_e32 v23, v39
	v_pk_fma_f32 v[12:13], v[8:9], v[12:13], v[34:35] op_sel_hi:[0,1,1]
	v_pk_fma_f32 v[14:15], v[8:9], v[14:15], v[218:219] op_sel_hi:[0,1,1]
	v_permlane32_swap_b32_e32 v207, v223
	v_mfma_f32_32x32x16_bf16 v[160:175], v[96:99], v[60:63], 0
	v_pk_fma_f32 v[20:21], v[10:11], v[14:15], v[20:21] op_sel_hi:[0,1,1]
	v_pk_fma_f32 v[204:205], v[8:9], v[12:13], v[204:205] op_sel:[1,0,0]
	v_permlane32_swap_b32_e32 v24, v40
	v_pk_fma_f32 v[12:13], v[8:9], v[12:13], v[20:21] op_sel_hi:[0,1,1]
	v_pk_fma_f32 v[14:15], v[8:9], v[14:15], v[204:205] op_sel_hi:[0,1,1]
	v_permlane32_swap_b32_e32 v208, v224
	v_mfma_f32_32x32x16_bf16 v[112:127], v[96:99], v[64:67], v[112:127]
	v_pk_fma_f32 v[22:23], v[10:11], v[14:15], v[22:23] op_sel_hi:[0,1,1]
	v_pk_fma_f32 v[206:207], v[8:9], v[12:13], v[206:207] op_sel:[1,0,0]
	v_permlane32_swap_b32_e32 v25, v41
	v_pk_fma_f32 v[12:13], v[8:9], v[12:13], v[22:23] op_sel_hi:[0,1,1]
	v_pk_fma_f32 v[14:15], v[8:9], v[14:15], v[206:207] op_sel_hi:[0,1,1]
	v_permlane32_swap_b32_e32 v209, v225
	v_mfma_f32_32x32x16_bf16 v[128:143], v[96:99], v[68:71], v[128:143]
	v_pk_fma_f32 v[36:37], v[10:11], v[14:15], v[36:37] op_sel_hi:[0,1,1]
	v_pk_fma_f32 v[220:221], v[8:9], v[12:13], v[220:221] op_sel:[1,0,0]
	v_permlane32_swap_b32_e32 v26, v42
	v_pk_fma_f32 v[12:13], v[8:9], v[12:13], v[36:37] op_sel_hi:[0,1,1]
	v_pk_fma_f32 v[14:15], v[8:9], v[14:15], v[220:221] op_sel_hi:[0,1,1]
	v_permlane32_swap_b32_e32 v210, v226
	v_mfma_f32_32x32x16_bf16 v[144:159], v[96:99], v[72:75], v[144:159]
	v_pk_fma_f32 v[38:39], v[10:11], v[14:15], v[38:39] op_sel_hi:[0,1,1]
	v_pk_fma_f32 v[222:223], v[8:9], v[12:13], v[222:223] op_sel:[1,0,0]
	v_permlane32_swap_b32_e32 v27, v43
	v_pk_fma_f32 v[12:13], v[8:9], v[12:13], v[38:39] op_sel_hi:[0,1,1]
	v_pk_fma_f32 v[14:15], v[8:9], v[14:15], v[222:223] op_sel_hi:[0,1,1]
	v_permlane32_swap_b32_e32 v211, v227
	v_mfma_f32_32x32x16_bf16 v[160:175], v[96:99], v[76:79], v[160:175]
	v_pk_fma_f32 v[24:25], v[10:11], v[14:15], v[24:25] op_sel_hi:[0,1,1]
	v_pk_fma_f32 v[208:209], v[8:9], v[12:13], v[208:209] op_sel:[1,0,0]
	v_permlane32_swap_b32_e32 v28, v44
	v_pk_fma_f32 v[12:13], v[8:9], v[12:13], v[24:25] op_sel_hi:[0,1,1]
	v_pk_fma_f32 v[14:15], v[8:9], v[14:15], v[208:209] op_sel_hi:[0,1,1]
	v_permlane32_swap_b32_e32 v212, v228
	v_pk_fma_f32 v[26:27], v[10:11], v[14:15], v[26:27] op_sel_hi:[0,1,1]
	v_pk_fma_f32 v[210:211], v[8:9], v[12:13], v[210:211] op_sel:[1,0,0]
	v_permlane32_swap_b32_e32 v29, v45
	v_pk_fma_f32 v[12:13], v[8:9], v[12:13], v[26:27] op_sel_hi:[0,1,1]
	v_pk_fma_f32 v[14:15], v[8:9], v[14:15], v[210:211] op_sel_hi:[0,1,1]
	v_permlane32_swap_b32_e32 v213, v229
	v_pk_fma_f32 v[40:41], v[10:11], v[14:15], v[40:41] op_sel_hi:[0,1,1]
	v_pk_fma_f32 v[224:225], v[8:9], v[12:13], v[224:225] op_sel:[1,0,0]
	v_permlane32_swap_b32_e32 v30, v46
	v_pk_fma_f32 v[12:13], v[8:9], v[12:13], v[40:41] op_sel_hi:[0,1,1]
	v_pk_fma_f32 v[14:15], v[8:9], v[14:15], v[224:225] op_sel_hi:[0,1,1]
	v_permlane32_swap_b32_e32 v214, v230
	v_pk_fma_f32 v[42:43], v[10:11], v[14:15], v[42:43] op_sel_hi:[0,1,1]
	v_pk_fma_f32 v[226:227], v[8:9], v[12:13], v[226:227] op_sel:[1,0,0]
	v_permlane32_swap_b32_e32 v31, v47
	v_pk_fma_f32 v[12:13], v[8:9], v[12:13], v[42:43] op_sel_hi:[0,1,1]
	v_pk_fma_f32 v[14:15], v[8:9], v[14:15], v[226:227] op_sel_hi:[0,1,1]
	v_permlane32_swap_b32_e32 v215, v231
	v_pk_fma_f32 v[28:29], v[10:11], v[14:15], v[28:29] op_sel_hi:[0,1,1]
	v_pk_fma_f32 v[212:213], v[8:9], v[12:13], v[212:213] op_sel:[1,0,0]
	s_nop 0
	v_pk_fma_f32 v[12:13], v[8:9], v[12:13], v[28:29] op_sel_hi:[0,1,1]
	v_pk_fma_f32 v[14:15], v[8:9], v[14:15], v[212:213] op_sel_hi:[0,1,1]
	s_nop 0
	v_pk_fma_f32 v[30:31], v[10:11], v[14:15], v[30:31] op_sel_hi:[0,1,1]
	v_pk_fma_f32 v[214:215], v[8:9], v[12:13], v[214:215] op_sel:[1,0,0]
	s_nop 0
	v_pk_fma_f32 v[12:13], v[8:9], v[12:13], v[30:31] op_sel_hi:[0,1,1]
	v_pk_fma_f32 v[14:15], v[8:9], v[14:15], v[214:215] op_sel_hi:[0,1,1]
	s_nop 0
	v_pk_fma_f32 v[44:45], v[10:11], v[14:15], v[44:45] op_sel_hi:[0,1,1]
	v_pk_fma_f32 v[228:229], v[8:9], v[12:13], v[228:229] op_sel:[1,0,0]
	s_nop 0
	v_pk_fma_f32 v[12:13], v[8:9], v[12:13], v[44:45] op_sel_hi:[0,1,1]
	v_pk_fma_f32 v[14:15], v[8:9], v[14:15], v[228:229] op_sel_hi:[0,1,1]
	s_nop 0
	v_pk_fma_f32 v[46:47], v[10:11], v[14:15], v[46:47] op_sel_hi:[0,1,1]
	v_pk_fma_f32 v[230:231], v[8:9], v[12:13], v[230:231] op_sel:[1,0,0]
	s_nop 0
	v_pk_fma_f32 v[12:13], v[8:9], v[12:13], v[46:47] op_sel_hi:[0,1,1]
	v_pk_fma_f32 v[14:15], v[8:9], v[14:15], v[230:231] op_sel_hi:[0,1,1]
	s_nop 0
	s_nop 0
	v_fma_f32 v181, v180, v14, v13
	v_fma_f32 v182, v179, v12, v15
	v_fma_f32 v12, v178, v12, v181
	v_fma_f32 v14, v178, v14, v182
	v_mov_b32_e32 v13, 0
	v_mov_b32_e32 v15, 0
	v_mov_b32_e32 v182, v12
	v_mov_b32_e32 v183, v14
	global_store_dwordx2 v7, v[182:183], s[48:49]
	s_add_u32 s48, s48, 0x100000
	s_addc_u32 s49, s49, 0
	global_load_dwordx4 v[88:91], v5, s[54:55]
	global_load_dwordx4 v[92:95], v6, s[54:55]
	s_add_u32 s54, s54, 0x400000
	s_addc_u32 s55, s55, 0
	v_mov_b32_e32 v12, 0
	v_mov_b32_e32 v13, 0
	v_mov_b32_e32 v14, 0
	v_mov_b32_e32 v15, 0
	s_nop 3
	v_permlane32_swap_b32_e32 v112, v128
	v_permlane32_swap_b32_e32 v144, v160
	v_permlane32_swap_b32_e32 v113, v129
	v_permlane32_swap_b32_e32 v145, v161
	v_permlane32_swap_b32_e32 v114, v130
	v_permlane32_swap_b32_e32 v146, v162
	v_permlane32_swap_b32_e32 v115, v131
	v_permlane32_swap_b32_e32 v147, v163
	v_pk_fma_f32 v[112:113], v[10:11], v[14:15], v[112:113] op_sel_hi:[0,1,1]
	v_pk_fma_f32 v[144:145], v[8:9], v[12:13], v[144:145] op_sel:[1,0,0]
	v_permlane32_swap_b32_e32 v116, v132
	v_pk_fma_f32 v[12:13], v[8:9], v[12:13], v[112:113] op_sel_hi:[0,1,1]
	v_pk_fma_f32 v[14:15], v[8:9], v[14:15], v[144:145] op_sel_hi:[0,1,1]
	v_permlane32_swap_b32_e32 v148, v164
	s_waitcnt vmcnt(8)
; #define LDS_WAIT() asm volatile("s_waitcnt lgkmcnt(0)" ::: "memory")
; __device__ __forceinline__ void p5_phase(Frame& F) {
;     ...
;     for (int it = F.gw; it < NB * NCH * NGRP; it += F.ngw) {
;         bf16x8 afr[4];
; #pragma unroll
;         for (int sub = 0; sub < 4; ++sub) afr[sub] = nfr[sub];
;         if (it + F.ngw < NB * NCH * NGRP) { const int bc = (it + F.ngw) >> 7, r0 = (bc / NCH) * SEQ + (bc % NCH) * TCH;
; #pragma unroll
;             for (int sub = 0; sub < 4; ++sub) nfr[sub] = ssm_load_afrag(U, r0 + 16 * sub, g, F.lane); }
;         float sr = 0.f, si = 0.f;
; #pragma unroll
;         for (int sub = 0; sub < 4; ++sub) {
;             ssm_bu16(afr[sub], bf, bubuf, F.lane);
; #pragma unroll
;             for (int tt = 0; tt < 16; ++tt) { const float bur = bubuf[tt * BUP + F.lane], bui = bubuf[tt * BUP + 64 + F.lane];
;                 const float nr = fmaf(ab.x, sr, fmaf(-ab.y, si, bur)), ni = fmaf(ab.x, si, fmaf(ab.y, sr, bui)); sr = nr; si = ni; }
;             LDS_WAIT(); asm volatile("" ::: "memory");
;         }
	v_mfma_f32_32x32x16_bf16 v[16:31], v[100:103], v[48:51], 0
	v_pk_fma_f32 v[114:115], v[10:11], v[14:15], v[114:115] op_sel_hi:[0,1,1]
	v_pk_fma_f32 v[146:147], v[8:9], v[12:13], v[146:147] op_sel:[1,0,0]
	v_permlane32_swap_b32_e32 v117, v133
	v_pk_fma_f32 v[12:13], v[8:9], v[12:13], v[114:115] op_sel_hi:[0,1,1]
	v_pk_fma_f32 v[14:15], v[8:9], v[14:15], v[146:147] op_sel_hi:[0,1,1]
	v_permlane32_swap_b32_e32 v149, v165
	v_mfma_f32_32x32x16_bf16 v[32:47], v[100:103], v[52:55], 0
	v_pk_fma_f32 v[128:129], v[10:11], v[14:15], v[128:129] op_sel_hi:[0,1,1]
	v_pk_fma_f32 v[160:161], v[8:9], v[12:13], v[160:161] op_sel:[1,0,0]
	v_permlane32_swap_b32_e32 v118, v134
	v_pk_fma_f32 v[12:13], v[8:9], v[12:13], v[128:129] op_sel_hi:[0,1,1]
	v_pk_fma_f32 v[14:15], v[8:9], v[14:15], v[160:161] op_sel_hi:[0,1,1]
	v_permlane32_swap_b32_e32 v150, v166
	v_mfma_f32_32x32x16_bf16 v[200:215], v[100:103], v[56:59], 0
	v_pk_fma_f32 v[130:131], v[10:11], v[14:15], v[130:131] op_sel_hi:[0,1,1]
	v_pk_fma_f32 v[162:163], v[8:9], v[12:13], v[162:163] op_sel:[1,0,0]
	v_permlane32_swap_b32_e32 v119, v135
	v_pk_fma_f32 v[12:13], v[8:9], v[12:13], v[130:131] op_sel_hi:[0,1,1]
	v_pk_fma_f32 v[14:15], v[8:9], v[14:15], v[162:163] op_sel_hi:[0,1,1]
	v_permlane32_swap_b32_e32 v151, v167
	v_mfma_f32_32x32x16_bf16 v[216:231], v[100:103], v[60:63], 0
	v_pk_fma_f32 v[116:117], v[10:11], v[14:15], v[116:117] op_sel_hi:[0,1,1]
	v_pk_fma_f32 v[148:149], v[8:9], v[12:13], v[148:149] op_sel:[1,0,0]
	v_permlane32_swap_b32_e32 v120, v136
	v_pk_fma_f32 v[12:13], v[8:9], v[12:13], v[116:117] op_sel_hi:[0,1,1]
	v_pk_fma_f32 v[14:15], v[8:9], v[14:15], v[148:149] op_sel_hi:[0,1,1]
	v_permlane32_swap_b32_e32 v152, v168
	v_mfma_f32_32x32x16_bf16 v[16:31], v[100:103], v[64:67], v[16:31]
	v_pk_fma_f32 v[118:119], v[10:11], v[14:15], v[118:119] op_sel_hi:[0,1,1]
	v_pk_fma_f32 v[150:151], v[8:9], v[12:13], v[150:151] op_sel:[1,0,0]
	v_permlane32_swap_b32_e32 v121, v137
	v_pk_fma_f32 v[12:13], v[8:9], v[12:13], v[118:119] op_sel_hi:[0,1,1]
	v_pk_fma_f32 v[14:15], v[8:9], v[14:15], v[150:151] op_sel_hi:[0,1,1]
	v_permlane32_swap_b32_e32 v153, v169
	v_mfma_f32_32x32x16_bf16 v[32:47], v[100:103], v[68:71], v[32:47]
	v_pk_fma_f32 v[132:133], v[10:11], v[14:15], v[132:133] op_sel_hi:[0,1,1]
	v_pk_fma_f32 v[164:165], v[8:9], v[12:13], v[164:165] op_sel:[1,0,0]
	v_permlane32_swap_b32_e32 v122, v138
	v_pk_fma_f32 v[12:13], v[8:9], v[12:13], v[132:133] op_sel_hi:[0,1,1]
	v_pk_fma_f32 v[14:15], v[8:9], v[14:15], v[164:165] op_sel_hi:[0,1,1]
	v_permlane32_swap_b32_e32 v154, v170
	v_mfma_f32_32x32x16_bf16 v[200:215], v[100:103], v[72:75], v[200:215]
	v_pk_fma_f32 v[134:135], v[10:11], v[14:15], v[134:135] op_sel_hi:[0,1,1]
	v_pk_fma_f32 v[166:167], v[8:9], v[12:13], v[166:167] op_sel:[1,0,0]
	v_permlane32_swap_b32_e32 v123, v139
	v_pk_fma_f32 v[12:13], v[8:9], v[12:13], v[134:135] op_sel_hi:[0,1,1]
	v_pk_fma_f32 v[14:15], v[8:9], v[14:15], v[166:167] op_sel_hi:[0,1,1]
	v_permlane32_swap_b32_e32 v155, v171
	v_mfma_f32_32x32x16_bf16 v[216:231], v[100:103], v[76:79], v[216:231]
	v_pk_fma_f32 v[120:121], v[10:11], v[14:15], v[120:121] op_sel_hi:[0,1,1]
	v_pk_fma_f32 v[152:153], v[8:9], v[12:13], v[152:153] op_sel:[1,0,0]
	v_permlane32_swap_b32_e32 v124, v140
	v_pk_fma_f32 v[12:13], v[8:9], v[12:13], v[120:121] op_sel_hi:[0,1,1]
	v_pk_fma_f32 v[14:15], v[8:9], v[14:15], v[152:153] op_sel_hi:[0,1,1]
	v_permlane32_swap_b32_e32 v156, v172
	v_pk_fma_f32 v[122:123], v[10:11], v[14:15], v[122:123] op_sel_hi:[0,1,1]
	v_pk_fma_f32 v[154:155], v[8:9], v[12:13], v[154:155] op_sel:[1,0,0]
	v_permlane32_swap_b32_e32 v125, v141
	v_pk_fma_f32 v[12:13], v[8:9], v[12:13], v[122:123] op_sel_hi:[0,1,1]
	v_pk_fma_f32 v[14:15], v[8:9], v[14:15], v[154:155] op_sel_hi:[0,1,1]
	v_permlane32_swap_b32_e32 v157, v173
	v_pk_fma_f32 v[136:137], v[10:11], v[14:15], v[136:137] op_sel_hi:[0,1,1]
	v_pk_fma_f32 v[168:169], v[8:9], v[12:13], v[168:169] op_sel:[1,0,0]
	v_permlane32_swap_b32_e32 v126, v142
	v_pk_fma_f32 v[12:13], v[8:9], v[12:13], v[136:137] op_sel_hi:[0,1,1]
	v_pk_fma_f32 v[14:15], v[8:9], v[14:15], v[168:169] op_sel_hi:[0,1,1]
	v_permlane32_swap_b32_e32 v158, v174
	v_pk_fma_f32 v[138:139], v[10:11], v[14:15], v[138:139] op_sel_hi:[0,1,1]
	v_pk_fma_f32 v[170:171], v[8:9], v[12:13], v[170:171] op_sel:[1,0,0]
	v_permlane32_swap_b32_e32 v127, v143
	v_pk_fma_f32 v[12:13], v[8:9], v[12:13], v[138:139] op_sel_hi:[0,1,1]
	v_pk_fma_f32 v[14:15], v[8:9], v[14:15], v[170:171] op_sel_hi:[0,1,1]
	v_permlane32_swap_b32_e32 v159, v175
	v_pk_fma_f32 v[124:125], v[10:11], v[14:15], v[124:125] op_sel_hi:[0,1,1]
	v_pk_fma_f32 v[156:157], v[8:9], v[12:13], v[156:157] op_sel:[1,0,0]
	s_nop 0
	v_pk_fma_f32 v[12:13], v[8:9], v[12:13], v[124:125] op_sel_hi:[0,1,1]
	v_pk_fma_f32 v[14:15], v[8:9], v[14:15], v[156:157] op_sel_hi:[0,1,1]
	s_nop 0
	v_pk_fma_f32 v[126:127], v[10:11], v[14:15], v[126:127] op_sel_hi:[0,1,1]
	v_pk_fma_f32 v[158:159], v[8:9], v[12:13], v[158:159] op_sel:[1,0,0]
	s_nop 0
	v_pk_fma_f32 v[12:13], v[8:9], v[12:13], v[126:127] op_sel_hi:[0,1,1]
	v_pk_fma_f32 v[14:15], v[8:9], v[14:15], v[158:159] op_sel_hi:[0,1,1]
	s_nop 0
	v_pk_fma_f32 v[140:141], v[10:11], v[14:15], v[140:141] op_sel_hi:[0,1,1]
	v_pk_fma_f32 v[172:173], v[8:9], v[12:13], v[172:173] op_sel:[1,0,0]
	s_nop 0
	v_pk_fma_f32 v[12:13], v[8:9], v[12:13], v[140:141] op_sel_hi:[0,1,1]
	v_pk_fma_f32 v[14:15], v[8:9], v[14:15], v[172:173] op_sel_hi:[0,1,1]
	s_nop 0
	v_pk_fma_f32 v[142:143], v[10:11], v[14:15], v[142:143] op_sel_hi:[0,1,1]
	v_pk_fma_f32 v[174:175], v[8:9], v[12:13], v[174:175] op_sel:[1,0,0]
	s_nop 0
	v_pk_fma_f32 v[12:13], v[8:9], v[12:13], v[142:143] op_sel_hi:[0,1,1]
	v_pk_fma_f32 v[14:15], v[8:9], v[14:15], v[174:175] op_sel_hi:[0,1,1]
	s_nop 0
	s_nop 0
	v_fma_f32 v181, v180, v14, v13
	v_fma_f32 v182, v179, v12, v15
	v_fma_f32 v12, v178, v12, v181
	v_fma_f32 v14, v178, v14, v182
	v_mov_b32_e32 v13, 0
	v_mov_b32_e32 v15, 0
	s_nop 3
	v_permlane32_swap_b32_e32 v16, v32
	v_permlane32_swap_b32_e32 v200, v216
	v_permlane32_swap_b32_e32 v17, v33
	v_permlane32_swap_b32_e32 v201, v217
	v_permlane32_swap_b32_e32 v18, v34
	v_permlane32_swap_b32_e32 v202, v218
	v_permlane32_swap_b32_e32 v19, v35
	v_permlane32_swap_b32_e32 v203, v219
	v_pk_fma_f32 v[16:17], v[10:11], v[14:15], v[16:17] op_sel_hi:[0,1,1]
	v_pk_fma_f32 v[200:201], v[8:9], v[12:13], v[200:201] op_sel:[1,0,0]
	v_permlane32_swap_b32_e32 v20, v36
	v_pk_fma_f32 v[12:13], v[8:9], v[12:13], v[16:17] op_sel_hi:[0,1,1]
	v_pk_fma_f32 v[14:15], v[8:9], v[14:15], v[200:201] op_sel_hi:[0,1,1]
	v_permlane32_swap_b32_e32 v204, v220
	s_waitcnt vmcnt(7)
; #define LDS_WAIT() asm volatile("s_waitcnt lgkmcnt(0)" ::: "memory")
; __device__ __forceinline__ void p5_phase(Frame& F) {
;     ...
;     for (int it = F.gw; it < NB * NCH * NGRP; it += F.ngw) {
;         bf16x8 afr[4];
; #pragma unroll
;         for (int sub = 0; sub < 4; ++sub) afr[sub] = nfr[sub];
;         if (it + F.ngw < NB * NCH * NGRP) { const int bc = (it + F.ngw) >> 7, r0 = (bc / NCH) * SEQ + (bc % NCH) * TCH;
; #pragma unroll
;             for (int sub = 0; sub < 4; ++sub) nfr[sub] = ssm_load_afrag(U, r0 + 16 * sub, g, F.lane); }
;         float sr = 0.f, si = 0.f;
; #pragma unroll
;         for (int sub = 0; sub < 4; ++sub) {
;             ssm_bu16(afr[sub], bf, bubuf, F.lane);
; #pragma unroll
;             for (int tt = 0; tt < 16; ++tt) { const float bur = bubuf[tt * BUP + F.lane], bui = bubuf[tt * BUP + 64 + F.lane];
;                 const float nr = fmaf(ab.x, sr, fmaf(-ab.y, si, bur)), ni = fmaf(ab.x, si, fmaf(ab.y, sr, bui)); sr = nr; si = ni; }
;             LDS_WAIT(); asm volatile("" ::: "memory");
;         }
;         ((f32x2*)(F.ws + WS_E))[(size_t)it * NST + F.lane] = (f32x2){sr, si};
	v_mfma_f32_32x32x16_bf16 v[112:127], v[104:107], v[48:51], 0
	v_pk_fma_f32 v[18:19], v[10:11], v[14:15], v[18:19] op_sel_hi:[0,1,1]
	v_pk_fma_f32 v[202:203], v[8:9], v[12:13], v[202:203] op_sel:[1,0,0]
	v_permlane32_swap_b32_e32 v21, v37
	v_pk_fma_f32 v[12:13], v[8:9], v[12:13], v[18:19] op_sel_hi:[0,1,1]
	v_pk_fma_f32 v[14:15], v[8:9], v[14:15], v[202:203] op_sel_hi:[0,1,1]
	v_permlane32_swap_b32_e32 v205, v221
	v_mfma_f32_32x32x16_bf16 v[128:143], v[104:107], v[52:55], 0
	v_pk_fma_f32 v[32:33], v[10:11], v[14:15], v[32:33] op_sel_hi:[0,1,1]
	v_pk_fma_f32 v[216:217], v[8:9], v[12:13], v[216:217] op_sel:[1,0,0]
	v_permlane32_swap_b32_e32 v22, v38
	v_pk_fma_f32 v[12:13], v[8:9], v[12:13], v[32:33] op_sel_hi:[0,1,1]
	v_pk_fma_f32 v[14:15], v[8:9], v[14:15], v[216:217] op_sel_hi:[0,1,1]
	v_permlane32_swap_b32_e32 v206, v222
	v_mfma_f32_32x32x16_bf16 v[144:159], v[104:107], v[56:59], 0
	v_pk_fma_f32 v[34:35], v[10:11], v[14:15], v[34:35] op_sel_hi:[0,1,1]
	v_pk_fma_f32 v[218:219], v[8:9], v[12:13], v[218:219] op_sel:[1,0,0]
	v_permlane32_swap_b32_e32 v23, v39
	v_pk_fma_f32 v[12:13], v[8:9], v[12:13], v[34:35] op_sel_hi:[0,1,1]
	v_pk_fma_f32 v[14:15], v[8:9], v[14:15], v[218:219] op_sel_hi:[0,1,1]
	v_permlane32_swap_b32_e32 v207, v223
	v_mfma_f32_32x32x16_bf16 v[160:175], v[104:107], v[60:63], 0
	v_pk_fma_f32 v[20:21], v[10:11], v[14:15], v[20:21] op_sel_hi:[0,1,1]
	v_pk_fma_f32 v[204:205], v[8:9], v[12:13], v[204:205] op_sel:[1,0,0]
	v_permlane32_swap_b32_e32 v24, v40
	v_pk_fma_f32 v[12:13], v[8:9], v[12:13], v[20:21] op_sel_hi:[0,1,1]
	v_pk_fma_f32 v[14:15], v[8:9], v[14:15], v[204:205] op_sel_hi:[0,1,1]
	v_permlane32_swap_b32_e32 v208, v224
	v_mfma_f32_32x32x16_bf16 v[112:127], v[104:107], v[64:67], v[112:127]
	v_pk_fma_f32 v[22:23], v[10:11], v[14:15], v[22:23] op_sel_hi:[0,1,1]
	v_pk_fma_f32 v[206:207], v[8:9], v[12:13], v[206:207] op_sel:[1,0,0]
	v_permlane32_swap_b32_e32 v25, v41
	v_pk_fma_f32 v[12:13], v[8:9], v[12:13], v[22:23] op_sel_hi:[0,1,1]
	v_pk_fma_f32 v[14:15], v[8:9], v[14:15], v[206:207] op_sel_hi:[0,1,1]
	v_permlane32_swap_b32_e32 v209, v225
	v_mfma_f32_32x32x16_bf16 v[128:143], v[104:107], v[68:71], v[128:143]
	v_pk_fma_f32 v[36:37], v[10:11], v[14:15], v[36:37] op_sel_hi:[0,1,1]
	v_pk_fma_f32 v[220:221], v[8:9], v[12:13], v[220:221] op_sel:[1,0,0]
	v_permlane32_swap_b32_e32 v26, v42
	v_pk_fma_f32 v[12:13], v[8:9], v[12:13], v[36:37] op_sel_hi:[0,1,1]
	v_pk_fma_f32 v[14:15], v[8:9], v[14:15], v[220:221] op_sel_hi:[0,1,1]
	v_permlane32_swap_b32_e32 v210, v226
	v_mfma_f32_32x32x16_bf16 v[144:159], v[104:107], v[72:75], v[144:159]
	v_pk_fma_f32 v[38:39], v[10:11], v[14:15], v[38:39] op_sel_hi:[0,1,1]
	v_pk_fma_f32 v[222:223], v[8:9], v[12:13], v[222:223] op_sel:[1,0,0]
	v_permlane32_swap_b32_e32 v27, v43
	v_pk_fma_f32 v[12:13], v[8:9], v[12:13], v[38:39] op_sel_hi:[0,1,1]
	v_pk_fma_f32 v[14:15], v[8:9], v[14:15], v[222:223] op_sel_hi:[0,1,1]
	v_permlane32_swap_b32_e32 v211, v227
	v_mfma_f32_32x32x16_bf16 v[160:175], v[104:107], v[76:79], v[160:175]
	v_pk_fma_f32 v[24:25], v[10:11], v[14:15], v[24:25] op_sel_hi:[0,1,1]
	v_pk_fma_f32 v[208:209], v[8:9], v[12:13], v[208:209] op_sel:[1,0,0]
	v_permlane32_swap_b32_e32 v28, v44
	v_pk_fma_f32 v[12:13], v[8:9], v[12:13], v[24:25] op_sel_hi:[0,1,1]
	v_pk_fma_f32 v[14:15], v[8:9], v[14:15], v[208:209] op_sel_hi:[0,1,1]
	v_permlane32_swap_b32_e32 v212, v228
	v_pk_fma_f32 v[26:27], v[10:11], v[14:15], v[26:27] op_sel_hi:[0,1,1]
	v_pk_fma_f32 v[210:211], v[8:9], v[12:13], v[210:211] op_sel:[1,0,0]
	v_permlane32_swap_b32_e32 v29, v45
	v_pk_fma_f32 v[12:13], v[8:9], v[12:13], v[26:27] op_sel_hi:[0,1,1]
	v_pk_fma_f32 v[14:15], v[8:9], v[14:15], v[210:211] op_sel_hi:[0,1,1]
	v_permlane32_swap_b32_e32 v213, v229
	v_pk_fma_f32 v[40:41], v[10:11], v[14:15], v[40:41] op_sel_hi:[0,1,1]
	v_pk_fma_f32 v[224:225], v[8:9], v[12:13], v[224:225] op_sel:[1,0,0]
	v_permlane32_swap_b32_e32 v30, v46
	v_pk_fma_f32 v[12:13], v[8:9], v[12:13], v[40:41] op_sel_hi:[0,1,1]
	v_pk_fma_f32 v[14:15], v[8:9], v[14:15], v[224:225] op_sel_hi:[0,1,1]
	v_permlane32_swap_b32_e32 v214, v230
	v_pk_fma_f32 v[42:43], v[10:11], v[14:15], v[42:43] op_sel_hi:[0,1,1]
	v_pk_fma_f32 v[226:227], v[8:9], v[12:13], v[226:227] op_sel:[1,0,0]
	v_permlane32_swap_b32_e32 v31, v47
	v_pk_fma_f32 v[12:13], v[8:9], v[12:13], v[42:43] op_sel_hi:[0,1,1]
	v_pk_fma_f32 v[14:15], v[8:9], v[14:15], v[226:227] op_sel_hi:[0,1,1]
	v_permlane32_swap_b32_e32 v215, v231
	v_pk_fma_f32 v[28:29], v[10:11], v[14:15], v[28:29] op_sel_hi:[0,1,1]
	v_pk_fma_f32 v[212:213], v[8:9], v[12:13], v[212:213] op_sel:[1,0,0]
	s_nop 0
	v_pk_fma_f32 v[12:13], v[8:9], v[12:13], v[28:29] op_sel_hi:[0,1,1]
	v_pk_fma_f32 v[14:15], v[8:9], v[14:15], v[212:213] op_sel_hi:[0,1,1]
	s_nop 0
	v_pk_fma_f32 v[30:31], v[10:11], v[14:15], v[30:31] op_sel_hi:[0,1,1]
	v_pk_fma_f32 v[214:215], v[8:9], v[12:13], v[214:215] op_sel:[1,0,0]
	s_nop 0
	v_pk_fma_f32 v[12:13], v[8:9], v[12:13], v[30:31] op_sel_hi:[0,1,1]
	v_pk_fma_f32 v[14:15], v[8:9], v[14:15], v[214:215] op_sel_hi:[0,1,1]
	s_nop 0
	v_pk_fma_f32 v[44:45], v[10:11], v[14:15], v[44:45] op_sel_hi:[0,1,1]
	v_pk_fma_f32 v[228:229], v[8:9], v[12:13], v[228:229] op_sel:[1,0,0]
	s_nop 0
	v_pk_fma_f32 v[12:13], v[8:9], v[12:13], v[44:45] op_sel_hi:[0,1,1]
	v_pk_fma_f32 v[14:15], v[8:9], v[14:15], v[228:229] op_sel_hi:[0,1,1]
	s_nop 0
	v_pk_fma_f32 v[46:47], v[10:11], v[14:15], v[46:47] op_sel_hi:[0,1,1]
	v_pk_fma_f32 v[230:231], v[8:9], v[12:13], v[230:231] op_sel:[1,0,0]
	s_nop 0
	v_pk_fma_f32 v[12:13], v[8:9], v[12:13], v[46:47] op_sel_hi:[0,1,1]
	v_pk_fma_f32 v[14:15], v[8:9], v[14:15], v[230:231] op_sel_hi:[0,1,1]
	s_nop 0
	s_nop 0
	v_fma_f32 v181, v180, v14, v13
	v_fma_f32 v182, v179, v12, v15
	v_fma_f32 v12, v178, v12, v181
	v_fma_f32 v14, v178, v14, v182
	v_mov_b32_e32 v13, 0
	v_mov_b32_e32 v15, 0
	v_mov_b32_e32 v182, v12
	v_mov_b32_e32 v183, v14
	global_store_dwordx2 v7, v[182:183], s[48:49]
	s_add_u32 s48, s48, 0x100000
	s_addc_u32 s49, s49, 0
	global_load_dwordx4 v[96:99], v5, s[54:55]
	global_load_dwordx4 v[100:103], v6, s[54:55]
	s_add_u32 s54, s54, 0x400000
	s_addc_u32 s55, s55, 0
	v_mov_b32_e32 v12, 0
	v_mov_b32_e32 v13, 0
	v_mov_b32_e32 v14, 0
	v_mov_b32_e32 v15, 0
	s_nop 3
	v_permlane32_swap_b32_e32 v112, v128
	v_permlane32_swap_b32_e32 v144, v160
	v_permlane32_swap_b32_e32 v113, v129
	v_permlane32_swap_b32_e32 v145, v161
	v_permlane32_swap_b32_e32 v114, v130
	v_permlane32_swap_b32_e32 v146, v162
	v_permlane32_swap_b32_e32 v115, v131
	v_permlane32_swap_b32_e32 v147, v163
	v_pk_fma_f32 v[112:113], v[10:11], v[14:15], v[112:113] op_sel_hi:[0,1,1]
	v_pk_fma_f32 v[144:145], v[8:9], v[12:13], v[144:145] op_sel:[1,0,0]
	v_permlane32_swap_b32_e32 v116, v132
	v_pk_fma_f32 v[12:13], v[8:9], v[12:13], v[112:113] op_sel_hi:[0,1,1]
	v_pk_fma_f32 v[14:15], v[8:9], v[14:15], v[144:145] op_sel_hi:[0,1,1]
	v_permlane32_swap_b32_e32 v148, v164
	s_waitcnt vmcnt(9)
; #define LDS_WAIT() asm volatile("s_waitcnt lgkmcnt(0)" ::: "memory")
; __device__ __forceinline__ void p5_phase(Frame& F) {
;     ...
;     for (int it = F.gw; it < NB * NCH * NGRP; it += F.ngw) {
;         bf16x8 afr[4];
; #pragma unroll
;         for (int sub = 0; sub < 4; ++sub) afr[sub] = nfr[sub];
;         if (it + F.ngw < NB * NCH * NGRP) { const int bc = (it + F.ngw) >> 7, r0 = (bc / NCH) * SEQ + (bc % NCH) * TCH;
; #pragma unroll
;             for (int sub = 0; sub < 4; ++sub) nfr[sub] = ssm_load_afrag(U, r0 + 16 * sub, g, F.lane); }
;         float sr = 0.f, si = 0.f;
; #pragma unroll
;         for (int sub = 0; sub < 4; ++sub) {
;             ssm_bu16(afr[sub], bf, bubuf, F.lane);
; #pragma unroll
;             for (int tt = 0; tt < 16; ++tt) { const float bur = bubuf[tt * BUP + F.lane], bui = bubuf[tt * BUP + 64 + F.lane];
;                 const float nr = fmaf(ab.x, sr, fmaf(-ab.y, si, bur)), ni = fmaf(ab.x, si, fmaf(ab.y, sr, bui)); sr = nr; si = ni; }
;             LDS_WAIT(); asm volatile("" ::: "memory");
;         }
	v_mfma_f32_32x32x16_bf16 v[16:31], v[108:111], v[48:51], 0
	v_pk_fma_f32 v[114:115], v[10:11], v[14:15], v[114:115] op_sel_hi:[0,1,1]
	v_pk_fma_f32 v[146:147], v[8:9], v[12:13], v[146:147] op_sel:[1,0,0]
	v_permlane32_swap_b32_e32 v117, v133
	v_pk_fma_f32 v[12:13], v[8:9], v[12:13], v[114:115] op_sel_hi:[0,1,1]
	v_pk_fma_f32 v[14:15], v[8:9], v[14:15], v[146:147] op_sel_hi:[0,1,1]
	v_permlane32_swap_b32_e32 v149, v165
	v_mfma_f32_32x32x16_bf16 v[32:47], v[108:111], v[52:55], 0
	v_pk_fma_f32 v[128:129], v[10:11], v[14:15], v[128:129] op_sel_hi:[0,1,1]
	v_pk_fma_f32 v[160:161], v[8:9], v[12:13], v[160:161] op_sel:[1,0,0]
	v_permlane32_swap_b32_e32 v118, v134
	v_pk_fma_f32 v[12:13], v[8:9], v[12:13], v[128:129] op_sel_hi:[0,1,1]
	v_pk_fma_f32 v[14:15], v[8:9], v[14:15], v[160:161] op_sel_hi:[0,1,1]
	v_permlane32_swap_b32_e32 v150, v166
	v_mfma_f32_32x32x16_bf16 v[200:215], v[108:111], v[56:59], 0
	v_pk_fma_f32 v[130:131], v[10:11], v[14:15], v[130:131] op_sel_hi:[0,1,1]
	v_pk_fma_f32 v[162:163], v[8:9], v[12:13], v[162:163] op_sel:[1,0,0]
	v_permlane32_swap_b32_e32 v119, v135
	v_pk_fma_f32 v[12:13], v[8:9], v[12:13], v[130:131] op_sel_hi:[0,1,1]
	v_pk_fma_f32 v[14:15], v[8:9], v[14:15], v[162:163] op_sel_hi:[0,1,1]
	v_permlane32_swap_b32_e32 v151, v167
	v_mfma_f32_32x32x16_bf16 v[216:231], v[108:111], v[60:63], 0
	v_pk_fma_f32 v[116:117], v[10:11], v[14:15], v[116:117] op_sel_hi:[0,1,1]
	v_pk_fma_f32 v[148:149], v[8:9], v[12:13], v[148:149] op_sel:[1,0,0]
	v_permlane32_swap_b32_e32 v120, v136
	v_pk_fma_f32 v[12:13], v[8:9], v[12:13], v[116:117] op_sel_hi:[0,1,1]
	v_pk_fma_f32 v[14:15], v[8:9], v[14:15], v[148:149] op_sel_hi:[0,1,1]
	v_permlane32_swap_b32_e32 v152, v168
	v_mfma_f32_32x32x16_bf16 v[16:31], v[108:111], v[64:67], v[16:31]
	v_pk_fma_f32 v[118:119], v[10:11], v[14:15], v[118:119] op_sel_hi:[0,1,1]
	v_pk_fma_f32 v[150:151], v[8:9], v[12:13], v[150:151] op_sel:[1,0,0]
	v_permlane32_swap_b32_e32 v121, v137
	v_pk_fma_f32 v[12:13], v[8:9], v[12:13], v[118:119] op_sel_hi:[0,1,1]
	v_pk_fma_f32 v[14:15], v[8:9], v[14:15], v[150:151] op_sel_hi:[0,1,1]
	v_permlane32_swap_b32_e32 v153, v169
	v_mfma_f32_32x32x16_bf16 v[32:47], v[108:111], v[68:71], v[32:47]
	v_pk_fma_f32 v[132:133], v[10:11], v[14:15], v[132:133] op_sel_hi:[0,1,1]
	v_pk_fma_f32 v[164:165], v[8:9], v[12:13], v[164:165] op_sel:[1,0,0]
	v_permlane32_swap_b32_e32 v122, v138
	v_pk_fma_f32 v[12:13], v[8:9], v[12:13], v[132:133] op_sel_hi:[0,1,1]
	v_pk_fma_f32 v[14:15], v[8:9], v[14:15], v[164:165] op_sel_hi:[0,1,1]
	v_permlane32_swap_b32_e32 v154, v170
	v_mfma_f32_32x32x16_bf16 v[200:215], v[108:111], v[72:75], v[200:215]
	v_pk_fma_f32 v[134:135], v[10:11], v[14:15], v[134:135] op_sel_hi:[0,1,1]
	v_pk_fma_f32 v[166:167], v[8:9], v[12:13], v[166:167] op_sel:[1,0,0]
	v_permlane32_swap_b32_e32 v123, v139
	v_pk_fma_f32 v[12:13], v[8:9], v[12:13], v[134:135] op_sel_hi:[0,1,1]
	v_pk_fma_f32 v[14:15], v[8:9], v[14:15], v[166:167] op_sel_hi:[0,1,1]
	v_permlane32_swap_b32_e32 v155, v171
	v_mfma_f32_32x32x16_bf16 v[216:231], v[108:111], v[76:79], v[216:231]
	v_pk_fma_f32 v[120:121], v[10:11], v[14:15], v[120:121] op_sel_hi:[0,1,1]
	v_pk_fma_f32 v[152:153], v[8:9], v[12:13], v[152:153] op_sel:[1,0,0]
	v_permlane32_swap_b32_e32 v124, v140
	v_pk_fma_f32 v[12:13], v[8:9], v[12:13], v[120:121] op_sel_hi:[0,1,1]
	v_pk_fma_f32 v[14:15], v[8:9], v[14:15], v[152:153] op_sel_hi:[0,1,1]
	v_permlane32_swap_b32_e32 v156, v172
	v_pk_fma_f32 v[122:123], v[10:11], v[14:15], v[122:123] op_sel_hi:[0,1,1]
	v_pk_fma_f32 v[154:155], v[8:9], v[12:13], v[154:155] op_sel:[1,0,0]
	v_permlane32_swap_b32_e32 v125, v141
	v_pk_fma_f32 v[12:13], v[8:9], v[12:13], v[122:123] op_sel_hi:[0,1,1]
	v_pk_fma_f32 v[14:15], v[8:9], v[14:15], v[154:155] op_sel_hi:[0,1,1]
	v_permlane32_swap_b32_e32 v157, v173
	v_pk_fma_f32 v[136:137], v[10:11], v[14:15], v[136:137] op_sel_hi:[0,1,1]
	v_pk_fma_f32 v[168:169], v[8:9], v[12:13], v[168:169] op_sel:[1,0,0]
	v_permlane32_swap_b32_e32 v126, v142
	v_pk_fma_f32 v[12:13], v[8:9], v[12:13], v[136:137] op_sel_hi:[0,1,1]
	v_pk_fma_f32 v[14:15], v[8:9], v[14:15], v[168:169] op_sel_hi:[0,1,1]
	v_permlane32_swap_b32_e32 v158, v174
	v_pk_fma_f32 v[138:139], v[10:11], v[14:15], v[138:139] op_sel_hi:[0,1,1]
	v_pk_fma_f32 v[170:171], v[8:9], v[12:13], v[170:171] op_sel:[1,0,0]
	v_permlane32_swap_b32_e32 v127, v143
	v_pk_fma_f32 v[12:13], v[8:9], v[12:13], v[138:139] op_sel_hi:[0,1,1]
	v_pk_fma_f32 v[14:15], v[8:9], v[14:15], v[170:171] op_sel_hi:[0,1,1]
	v_permlane32_swap_b32_e32 v159, v175
	v_pk_fma_f32 v[124:125], v[10:11], v[14:15], v[124:125] op_sel_hi:[0,1,1]
	v_pk_fma_f32 v[156:157], v[8:9], v[12:13], v[156:157] op_sel:[1,0,0]
	s_nop 0
	v_pk_fma_f32 v[12:13], v[8:9], v[12:13], v[124:125] op_sel_hi:[0,1,1]
	v_pk_fma_f32 v[14:15], v[8:9], v[14:15], v[156:157] op_sel_hi:[0,1,1]
	s_nop 0
	v_pk_fma_f32 v[126:127], v[10:11], v[14:15], v[126:127] op_sel_hi:[0,1,1]
	v_pk_fma_f32 v[158:159], v[8:9], v[12:13], v[158:159] op_sel:[1,0,0]
	s_nop 0
	v_pk_fma_f32 v[12:13], v[8:9], v[12:13], v[126:127] op_sel_hi:[0,1,1]
	v_pk_fma_f32 v[14:15], v[8:9], v[14:15], v[158:159] op_sel_hi:[0,1,1]
	s_nop 0
	v_pk_fma_f32 v[140:141], v[10:11], v[14:15], v[140:141] op_sel_hi:[0,1,1]
	v_pk_fma_f32 v[172:173], v[8:9], v[12:13], v[172:173] op_sel:[1,0,0]
	s_nop 0
	v_pk_fma_f32 v[12:13], v[8:9], v[12:13], v[140:141] op_sel_hi:[0,1,1]
	v_pk_fma_f32 v[14:15], v[8:9], v[14:15], v[172:173] op_sel_hi:[0,1,1]
	s_nop 0
	v_pk_fma_f32 v[142:143], v[10:11], v[14:15], v[142:143] op_sel_hi:[0,1,1]
	v_pk_fma_f32 v[174:175], v[8:9], v[12:13], v[174:175] op_sel:[1,0,0]
	s_nop 0
	v_pk_fma_f32 v[12:13], v[8:9], v[12:13], v[142:143] op_sel_hi:[0,1,1]
	v_pk_fma_f32 v[14:15], v[8:9], v[14:15], v[174:175] op_sel_hi:[0,1,1]
	s_nop 0
	s_nop 0
	v_fma_f32 v181, v180, v14, v13
	v_fma_f32 v182, v179, v12, v15
	v_fma_f32 v12, v178, v12, v181
	v_fma_f32 v14, v178, v14, v182
	v_mov_b32_e32 v13, 0
	v_mov_b32_e32 v15, 0
	s_nop 3
	v_permlane32_swap_b32_e32 v16, v32
	v_permlane32_swap_b32_e32 v200, v216
	v_permlane32_swap_b32_e32 v17, v33
	v_permlane32_swap_b32_e32 v201, v217
	v_permlane32_swap_b32_e32 v18, v34
	v_permlane32_swap_b32_e32 v202, v218
	v_permlane32_swap_b32_e32 v19, v35
	v_permlane32_swap_b32_e32 v203, v219
	v_pk_fma_f32 v[16:17], v[10:11], v[14:15], v[16:17] op_sel_hi:[0,1,1]
	v_pk_fma_f32 v[200:201], v[8:9], v[12:13], v[200:201] op_sel:[1,0,0]
	v_permlane32_swap_b32_e32 v20, v36
	v_pk_fma_f32 v[12:13], v[8:9], v[12:13], v[16:17] op_sel_hi:[0,1,1]
	v_pk_fma_f32 v[14:15], v[8:9], v[14:15], v[200:201] op_sel_hi:[0,1,1]
	v_permlane32_swap_b32_e32 v204, v220
	s_waitcnt vmcnt(7)
; #define LDS_WAIT() asm volatile("s_waitcnt lgkmcnt(0)" ::: "memory")
; __device__ __forceinline__ void p5_phase(Frame& F) {
;     ...
;     for (int it = F.gw; it < NB * NCH * NGRP; it += F.ngw) {
;         bf16x8 afr[4];
; #pragma unroll
;         for (int sub = 0; sub < 4; ++sub) afr[sub] = nfr[sub];
;         if (it + F.ngw < NB * NCH * NGRP) { const int bc = (it + F.ngw) >> 7, r0 = (bc / NCH) * SEQ + (bc % NCH) * TCH;
; #pragma unroll
;             for (int sub = 0; sub < 4; ++sub) nfr[sub] = ssm_load_afrag(U, r0 + 16 * sub, g, F.lane); }
;         float sr = 0.f, si = 0.f;
; #pragma unroll
;         for (int sub = 0; sub < 4; ++sub) {
;             ssm_bu16(afr[sub], bf, bubuf, F.lane);
; #pragma unroll
;             for (int tt = 0; tt < 16; ++tt) { const float bur = bubuf[tt * BUP + F.lane], bui = bubuf[tt * BUP + 64 + F.lane];
;                 const float nr = fmaf(ab.x, sr, fmaf(-ab.y, si, bur)), ni = fmaf(ab.x, si, fmaf(ab.y, sr, bui)); sr = nr; si = ni; }
;             LDS_WAIT(); asm volatile("" ::: "memory");
;         }
;         ((f32x2*)(F.ws + WS_E))[(size_t)it * NST + F.lane] = (f32x2){sr, si};
	v_mfma_f32_32x32x16_bf16 v[112:127], v[80:83], v[48:51], 0
	v_pk_fma_f32 v[18:19], v[10:11], v[14:15], v[18:19] op_sel_hi:[0,1,1]
	v_pk_fma_f32 v[202:203], v[8:9], v[12:13], v[202:203] op_sel:[1,0,0]
	v_permlane32_swap_b32_e32 v21, v37
	v_pk_fma_f32 v[12:13], v[8:9], v[12:13], v[18:19] op_sel_hi:[0,1,1]
	v_pk_fma_f32 v[14:15], v[8:9], v[14:15], v[202:203] op_sel_hi:[0,1,1]
	v_permlane32_swap_b32_e32 v205, v221
	v_mfma_f32_32x32x16_bf16 v[128:143], v[80:83], v[52:55], 0
	v_pk_fma_f32 v[32:33], v[10:11], v[14:15], v[32:33] op_sel_hi:[0,1,1]
	v_pk_fma_f32 v[216:217], v[8:9], v[12:13], v[216:217] op_sel:[1,0,0]
	v_permlane32_swap_b32_e32 v22, v38
	v_pk_fma_f32 v[12:13], v[8:9], v[12:13], v[32:33] op_sel_hi:[0,1,1]
	v_pk_fma_f32 v[14:15], v[8:9], v[14:15], v[216:217] op_sel_hi:[0,1,1]
	v_permlane32_swap_b32_e32 v206, v222
	v_mfma_f32_32x32x16_bf16 v[144:159], v[80:83], v[56:59], 0
	v_pk_fma_f32 v[34:35], v[10:11], v[14:15], v[34:35] op_sel_hi:[0,1,1]
	v_pk_fma_f32 v[218:219], v[8:9], v[12:13], v[218:219] op_sel:[1,0,0]
	v_permlane32_swap_b32_e32 v23, v39
	v_pk_fma_f32 v[12:13], v[8:9], v[12:13], v[34:35] op_sel_hi:[0,1,1]
	v_pk_fma_f32 v[14:15], v[8:9], v[14:15], v[218:219] op_sel_hi:[0,1,1]
	v_permlane32_swap_b32_e32 v207, v223
	v_mfma_f32_32x32x16_bf16 v[160:175], v[80:83], v[60:63], 0
	v_pk_fma_f32 v[20:21], v[10:11], v[14:15], v[20:21] op_sel_hi:[0,1,1]
	v_pk_fma_f32 v[204:205], v[8:9], v[12:13], v[204:205] op_sel:[1,0,0]
	v_permlane32_swap_b32_e32 v24, v40
	v_pk_fma_f32 v[12:13], v[8:9], v[12:13], v[20:21] op_sel_hi:[0,1,1]
	v_pk_fma_f32 v[14:15], v[8:9], v[14:15], v[204:205] op_sel_hi:[0,1,1]
	v_permlane32_swap_b32_e32 v208, v224
	v_mfma_f32_32x32x16_bf16 v[112:127], v[80:83], v[64:67], v[112:127]
	v_pk_fma_f32 v[22:23], v[10:11], v[14:15], v[22:23] op_sel_hi:[0,1,1]
	v_pk_fma_f32 v[206:207], v[8:9], v[12:13], v[206:207] op_sel:[1,0,0]
	v_permlane32_swap_b32_e32 v25, v41
	v_pk_fma_f32 v[12:13], v[8:9], v[12:13], v[22:23] op_sel_hi:[0,1,1]
	v_pk_fma_f32 v[14:15], v[8:9], v[14:15], v[206:207] op_sel_hi:[0,1,1]
	v_permlane32_swap_b32_e32 v209, v225
	v_mfma_f32_32x32x16_bf16 v[128:143], v[80:83], v[68:71], v[128:143]
	v_pk_fma_f32 v[36:37], v[10:11], v[14:15], v[36:37] op_sel_hi:[0,1,1]
	v_pk_fma_f32 v[220:221], v[8:9], v[12:13], v[220:221] op_sel:[1,0,0]
	v_permlane32_swap_b32_e32 v26, v42
	v_pk_fma_f32 v[12:13], v[8:9], v[12:13], v[36:37] op_sel_hi:[0,1,1]
	v_pk_fma_f32 v[14:15], v[8:9], v[14:15], v[220:221] op_sel_hi:[0,1,1]
	v_permlane32_swap_b32_e32 v210, v226
	v_mfma_f32_32x32x16_bf16 v[144:159], v[80:83], v[72:75], v[144:159]
	v_pk_fma_f32 v[38:39], v[10:11], v[14:15], v[38:39] op_sel_hi:[0,1,1]
	v_pk_fma_f32 v[222:223], v[8:9], v[12:13], v[222:223] op_sel:[1,0,0]
	v_permlane32_swap_b32_e32 v27, v43
	v_pk_fma_f32 v[12:13], v[8:9], v[12:13], v[38:39] op_sel_hi:[0,1,1]
	v_pk_fma_f32 v[14:15], v[8:9], v[14:15], v[222:223] op_sel_hi:[0,1,1]
	v_permlane32_swap_b32_e32 v211, v227
	v_mfma_f32_32x32x16_bf16 v[160:175], v[80:83], v[76:79], v[160:175]
	v_pk_fma_f32 v[24:25], v[10:11], v[14:15], v[24:25] op_sel_hi:[0,1,1]
	v_pk_fma_f32 v[208:209], v[8:9], v[12:13], v[208:209] op_sel:[1,0,0]
	v_permlane32_swap_b32_e32 v28, v44
	v_pk_fma_f32 v[12:13], v[8:9], v[12:13], v[24:25] op_sel_hi:[0,1,1]
	v_pk_fma_f32 v[14:15], v[8:9], v[14:15], v[208:209] op_sel_hi:[0,1,1]
	v_permlane32_swap_b32_e32 v212, v228
	v_pk_fma_f32 v[26:27], v[10:11], v[14:15], v[26:27] op_sel_hi:[0,1,1]
	v_pk_fma_f32 v[210:211], v[8:9], v[12:13], v[210:211] op_sel:[1,0,0]
	v_permlane32_swap_b32_e32 v29, v45
	v_pk_fma_f32 v[12:13], v[8:9], v[12:13], v[26:27] op_sel_hi:[0,1,1]
	v_pk_fma_f32 v[14:15], v[8:9], v[14:15], v[210:211] op_sel_hi:[0,1,1]
	v_permlane32_swap_b32_e32 v213, v229
	v_pk_fma_f32 v[40:41], v[10:11], v[14:15], v[40:41] op_sel_hi:[0,1,1]
	v_pk_fma_f32 v[224:225], v[8:9], v[12:13], v[224:225] op_sel:[1,0,0]
	v_permlane32_swap_b32_e32 v30, v46
	v_pk_fma_f32 v[12:13], v[8:9], v[12:13], v[40:41] op_sel_hi:[0,1,1]
	v_pk_fma_f32 v[14:15], v[8:9], v[14:15], v[224:225] op_sel_hi:[0,1,1]
	v_permlane32_swap_b32_e32 v214, v230
	v_pk_fma_f32 v[42:43], v[10:11], v[14:15], v[42:43] op_sel_hi:[0,1,1]
	v_pk_fma_f32 v[226:227], v[8:9], v[12:13], v[226:227] op_sel:[1,0,0]
	v_permlane32_swap_b32_e32 v31, v47
	v_pk_fma_f32 v[12:13], v[8:9], v[12:13], v[42:43] op_sel_hi:[0,1,1]
	v_pk_fma_f32 v[14:15], v[8:9], v[14:15], v[226:227] op_sel_hi:[0,1,1]
	v_permlane32_swap_b32_e32 v215, v231
	v_pk_fma_f32 v[28:29], v[10:11], v[14:15], v[28:29] op_sel_hi:[0,1,1]
	v_pk_fma_f32 v[212:213], v[8:9], v[12:13], v[212:213] op_sel:[1,0,0]
	s_nop 0
	v_pk_fma_f32 v[12:13], v[8:9], v[12:13], v[28:29] op_sel_hi:[0,1,1]
	v_pk_fma_f32 v[14:15], v[8:9], v[14:15], v[212:213] op_sel_hi:[0,1,1]
	s_nop 0
	v_pk_fma_f32 v[30:31], v[10:11], v[14:15], v[30:31] op_sel_hi:[0,1,1]
	v_pk_fma_f32 v[214:215], v[8:9], v[12:13], v[214:215] op_sel:[1,0,0]
	s_nop 0
	v_pk_fma_f32 v[12:13], v[8:9], v[12:13], v[30:31] op_sel_hi:[0,1,1]
	v_pk_fma_f32 v[14:15], v[8:9], v[14:15], v[214:215] op_sel_hi:[0,1,1]
	s_nop 0
	v_pk_fma_f32 v[44:45], v[10:11], v[14:15], v[44:45] op_sel_hi:[0,1,1]
	v_pk_fma_f32 v[228:229], v[8:9], v[12:13], v[228:229] op_sel:[1,0,0]
	s_nop 0
	v_pk_fma_f32 v[12:13], v[8:9], v[12:13], v[44:45] op_sel_hi:[0,1,1]
	v_pk_fma_f32 v[14:15], v[8:9], v[14:15], v[228:229] op_sel_hi:[0,1,1]
	s_nop 0
	v_pk_fma_f32 v[46:47], v[10:11], v[14:15], v[46:47] op_sel_hi:[0,1,1]
	v_pk_fma_f32 v[230:231], v[8:9], v[12:13], v[230:231] op_sel:[1,0,0]
	s_nop 0
	v_pk_fma_f32 v[12:13], v[8:9], v[12:13], v[46:47] op_sel_hi:[0,1,1]
	v_pk_fma_f32 v[14:15], v[8:9], v[14:15], v[230:231] op_sel_hi:[0,1,1]
	s_nop 0
	s_nop 0
	v_fma_f32 v181, v180, v14, v13
	v_fma_f32 v182, v179, v12, v15
	v_fma_f32 v12, v178, v12, v181
	v_fma_f32 v14, v178, v14, v182
	v_mov_b32_e32 v13, 0
	v_mov_b32_e32 v15, 0
	v_mov_b32_e32 v182, v12
	v_mov_b32_e32 v183, v14
	global_store_dwordx2 v7, v[182:183], s[48:49]
	s_add_u32 s48, s48, 0x100000
	s_addc_u32 s49, s49, 0
	global_load_dwordx4 v[104:107], v5, s[54:55]
	global_load_dwordx4 v[108:111], v6, s[54:55]
	s_add_u32 s54, s54, 0x400000
	s_addc_u32 s55, s55, 0
	v_mov_b32_e32 v12, 0
	v_mov_b32_e32 v13, 0
	v_mov_b32_e32 v14, 0
	v_mov_b32_e32 v15, 0
	s_nop 3
	v_permlane32_swap_b32_e32 v112, v128
	v_permlane32_swap_b32_e32 v144, v160
	v_permlane32_swap_b32_e32 v113, v129
	v_permlane32_swap_b32_e32 v145, v161
	v_permlane32_swap_b32_e32 v114, v130
	v_permlane32_swap_b32_e32 v146, v162
	v_permlane32_swap_b32_e32 v115, v131
	v_permlane32_swap_b32_e32 v147, v163
	v_pk_fma_f32 v[112:113], v[10:11], v[14:15], v[112:113] op_sel_hi:[0,1,1]
	v_pk_fma_f32 v[144:145], v[8:9], v[12:13], v[144:145] op_sel:[1,0,0]
	v_permlane32_swap_b32_e32 v116, v132
	v_pk_fma_f32 v[12:13], v[8:9], v[12:13], v[112:113] op_sel_hi:[0,1,1]
	v_pk_fma_f32 v[14:15], v[8:9], v[14:15], v[144:145] op_sel_hi:[0,1,1]
	v_permlane32_swap_b32_e32 v148, v164
	s_waitcnt vmcnt(9)
; #define LDS_WAIT() asm volatile("s_waitcnt lgkmcnt(0)" ::: "memory")
; __device__ __forceinline__ void p5_phase(Frame& F) {
;     ...
;     for (int it = F.gw; it < NB * NCH * NGRP; it += F.ngw) {
;         bf16x8 afr[4];
; #pragma unroll
;         for (int sub = 0; sub < 4; ++sub) afr[sub] = nfr[sub];
;         if (it + F.ngw < NB * NCH * NGRP) { const int bc = (it + F.ngw) >> 7, r0 = (bc / NCH) * SEQ + (bc % NCH) * TCH;
; #pragma unroll
;             for (int sub = 0; sub < 4; ++sub) nfr[sub] = ssm_load_afrag(U, r0 + 16 * sub, g, F.lane); }
;         float sr = 0.f, si = 0.f;
; #pragma unroll
;         for (int sub = 0; sub < 4; ++sub) {
;             ssm_bu16(afr[sub], bf, bubuf, F.lane);
; #pragma unroll
;             for (int tt = 0; tt < 16; ++tt) { const float bur = bubuf[tt * BUP + F.lane], bui = bubuf[tt * BUP + 64 + F.lane];
;                 const float nr = fmaf(ab.x, sr, fmaf(-ab.y, si, bur)), ni = fmaf(ab.x, si, fmaf(ab.y, sr, bui)); sr = nr; si = ni; }
;             LDS_WAIT(); asm volatile("" ::: "memory");
;         }
	v_mfma_f32_32x32x16_bf16 v[16:31], v[84:87], v[48:51], 0
	v_pk_fma_f32 v[114:115], v[10:11], v[14:15], v[114:115] op_sel_hi:[0,1,1]
	v_pk_fma_f32 v[146:147], v[8:9], v[12:13], v[146:147] op_sel:[1,0,0]
	v_permlane32_swap_b32_e32 v117, v133
	v_pk_fma_f32 v[12:13], v[8:9], v[12:13], v[114:115] op_sel_hi:[0,1,1]
	v_pk_fma_f32 v[14:15], v[8:9], v[14:15], v[146:147] op_sel_hi:[0,1,1]
	v_permlane32_swap_b32_e32 v149, v165
	v_mfma_f32_32x32x16_bf16 v[32:47], v[84:87], v[52:55], 0
	v_pk_fma_f32 v[128:129], v[10:11], v[14:15], v[128:129] op_sel_hi:[0,1,1]
	v_pk_fma_f32 v[160:161], v[8:9], v[12:13], v[160:161] op_sel:[1,0,0]
	v_permlane32_swap_b32_e32 v118, v134
	v_pk_fma_f32 v[12:13], v[8:9], v[12:13], v[128:129] op_sel_hi:[0,1,1]
	v_pk_fma_f32 v[14:15], v[8:9], v[14:15], v[160:161] op_sel_hi:[0,1,1]
	v_permlane32_swap_b32_e32 v150, v166
	v_mfma_f32_32x32x16_bf16 v[200:215], v[84:87], v[56:59], 0
	v_pk_fma_f32 v[130:131], v[10:11], v[14:15], v[130:131] op_sel_hi:[0,1,1]
	v_pk_fma_f32 v[162:163], v[8:9], v[12:13], v[162:163] op_sel:[1,0,0]
	v_permlane32_swap_b32_e32 v119, v135
	v_pk_fma_f32 v[12:13], v[8:9], v[12:13], v[130:131] op_sel_hi:[0,1,1]
	v_pk_fma_f32 v[14:15], v[8:9], v[14:15], v[162:163] op_sel_hi:[0,1,1]
	v_permlane32_swap_b32_e32 v151, v167
	v_mfma_f32_32x32x16_bf16 v[216:231], v[84:87], v[60:63], 0
	v_pk_fma_f32 v[116:117], v[10:11], v[14:15], v[116:117] op_sel_hi:[0,1,1]
	v_pk_fma_f32 v[148:149], v[8:9], v[12:13], v[148:149] op_sel:[1,0,0]
	v_permlane32_swap_b32_e32 v120, v136
	v_pk_fma_f32 v[12:13], v[8:9], v[12:13], v[116:117] op_sel_hi:[0,1,1]
	v_pk_fma_f32 v[14:15], v[8:9], v[14:15], v[148:149] op_sel_hi:[0,1,1]
	v_permlane32_swap_b32_e32 v152, v168
	v_mfma_f32_32x32x16_bf16 v[16:31], v[84:87], v[64:67], v[16:31]
	v_pk_fma_f32 v[118:119], v[10:11], v[14:15], v[118:119] op_sel_hi:[0,1,1]
	v_pk_fma_f32 v[150:151], v[8:9], v[12:13], v[150:151] op_sel:[1,0,0]
	v_permlane32_swap_b32_e32 v121, v137
	v_pk_fma_f32 v[12:13], v[8:9], v[12:13], v[118:119] op_sel_hi:[0,1,1]
	v_pk_fma_f32 v[14:15], v[8:9], v[14:15], v[150:151] op_sel_hi:[0,1,1]
	v_permlane32_swap_b32_e32 v153, v169
	v_mfma_f32_32x32x16_bf16 v[32:47], v[84:87], v[68:71], v[32:47]
	v_pk_fma_f32 v[132:133], v[10:11], v[14:15], v[132:133] op_sel_hi:[0,1,1]
	v_pk_fma_f32 v[164:165], v[8:9], v[12:13], v[164:165] op_sel:[1,0,0]
	v_permlane32_swap_b32_e32 v122, v138
	v_pk_fma_f32 v[12:13], v[8:9], v[12:13], v[132:133] op_sel_hi:[0,1,1]
	v_pk_fma_f32 v[14:15], v[8:9], v[14:15], v[164:165] op_sel_hi:[0,1,1]
	v_permlane32_swap_b32_e32 v154, v170
	v_mfma_f32_32x32x16_bf16 v[200:215], v[84:87], v[72:75], v[200:215]
	v_pk_fma_f32 v[134:135], v[10:11], v[14:15], v[134:135] op_sel_hi:[0,1,1]
	v_pk_fma_f32 v[166:167], v[8:9], v[12:13], v[166:167] op_sel:[1,0,0]
	v_permlane32_swap_b32_e32 v123, v139
	v_pk_fma_f32 v[12:13], v[8:9], v[12:13], v[134:135] op_sel_hi:[0,1,1]
	v_pk_fma_f32 v[14:15], v[8:9], v[14:15], v[166:167] op_sel_hi:[0,1,1]
	v_permlane32_swap_b32_e32 v155, v171
	v_mfma_f32_32x32x16_bf16 v[216:231], v[84:87], v[76:79], v[216:231]
	v_pk_fma_f32 v[120:121], v[10:11], v[14:15], v[120:121] op_sel_hi:[0,1,1]
	v_pk_fma_f32 v[152:153], v[8:9], v[12:13], v[152:153] op_sel:[1,0,0]
	v_permlane32_swap_b32_e32 v124, v140
	v_pk_fma_f32 v[12:13], v[8:9], v[12:13], v[120:121] op_sel_hi:[0,1,1]
	v_pk_fma_f32 v[14:15], v[8:9], v[14:15], v[152:153] op_sel_hi:[0,1,1]
	v_permlane32_swap_b32_e32 v156, v172
	v_pk_fma_f32 v[122:123], v[10:11], v[14:15], v[122:123] op_sel_hi:[0,1,1]
	v_pk_fma_f32 v[154:155], v[8:9], v[12:13], v[154:155] op_sel:[1,0,0]
	v_permlane32_swap_b32_e32 v125, v141
	v_pk_fma_f32 v[12:13], v[8:9], v[12:13], v[122:123] op_sel_hi:[0,1,1]
	v_pk_fma_f32 v[14:15], v[8:9], v[14:15], v[154:155] op_sel_hi:[0,1,1]
	v_permlane32_swap_b32_e32 v157, v173
	v_pk_fma_f32 v[136:137], v[10:11], v[14:15], v[136:137] op_sel_hi:[0,1,1]
	v_pk_fma_f32 v[168:169], v[8:9], v[12:13], v[168:169] op_sel:[1,0,0]
	v_permlane32_swap_b32_e32 v126, v142
	v_pk_fma_f32 v[12:13], v[8:9], v[12:13], v[136:137] op_sel_hi:[0,1,1]
	v_pk_fma_f32 v[14:15], v[8:9], v[14:15], v[168:169] op_sel_hi:[0,1,1]
	v_permlane32_swap_b32_e32 v158, v174
	v_pk_fma_f32 v[138:139], v[10:11], v[14:15], v[138:139] op_sel_hi:[0,1,1]
	v_pk_fma_f32 v[170:171], v[8:9], v[12:13], v[170:171] op_sel:[1,0,0]
	v_permlane32_swap_b32_e32 v127, v143
	v_pk_fma_f32 v[12:13], v[8:9], v[12:13], v[138:139] op_sel_hi:[0,1,1]
	v_pk_fma_f32 v[14:15], v[8:9], v[14:15], v[170:171] op_sel_hi:[0,1,1]
	v_permlane32_swap_b32_e32 v159, v175
	v_pk_fma_f32 v[124:125], v[10:11], v[14:15], v[124:125] op_sel_hi:[0,1,1]
	v_pk_fma_f32 v[156:157], v[8:9], v[12:13], v[156:157] op_sel:[1,0,0]
	s_nop 0
	v_pk_fma_f32 v[12:13], v[8:9], v[12:13], v[124:125] op_sel_hi:[0,1,1]
	v_pk_fma_f32 v[14:15], v[8:9], v[14:15], v[156:157] op_sel_hi:[0,1,1]
	s_nop 0
	v_pk_fma_f32 v[126:127], v[10:11], v[14:15], v[126:127] op_sel_hi:[0,1,1]
	v_pk_fma_f32 v[158:159], v[8:9], v[12:13], v[158:159] op_sel:[1,0,0]
	s_nop 0
	v_pk_fma_f32 v[12:13], v[8:9], v[12:13], v[126:127] op_sel_hi:[0,1,1]
	v_pk_fma_f32 v[14:15], v[8:9], v[14:15], v[158:159] op_sel_hi:[0,1,1]
	s_nop 0
	v_pk_fma_f32 v[140:141], v[10:11], v[14:15], v[140:141] op_sel_hi:[0,1,1]
	v_pk_fma_f32 v[172:173], v[8:9], v[12:13], v[172:173] op_sel:[1,0,0]
	s_nop 0
	v_pk_fma_f32 v[12:13], v[8:9], v[12:13], v[140:141] op_sel_hi:[0,1,1]
	v_pk_fma_f32 v[14:15], v[8:9], v[14:15], v[172:173] op_sel_hi:[0,1,1]
	s_nop 0
	v_pk_fma_f32 v[142:143], v[10:11], v[14:15], v[142:143] op_sel_hi:[0,1,1]
	v_pk_fma_f32 v[174:175], v[8:9], v[12:13], v[174:175] op_sel:[1,0,0]
	s_nop 0
	v_pk_fma_f32 v[12:13], v[8:9], v[12:13], v[142:143] op_sel_hi:[0,1,1]
	v_pk_fma_f32 v[14:15], v[8:9], v[14:15], v[174:175] op_sel_hi:[0,1,1]
	s_nop 0
	s_nop 0
	v_fma_f32 v181, v180, v14, v13
	v_fma_f32 v182, v179, v12, v15
	v_fma_f32 v12, v178, v12, v181
	v_fma_f32 v14, v178, v14, v182
	v_mov_b32_e32 v13, 0
	v_mov_b32_e32 v15, 0
	s_nop 3
	v_permlane32_swap_b32_e32 v16, v32
	v_permlane32_swap_b32_e32 v200, v216
	v_permlane32_swap_b32_e32 v17, v33
	v_permlane32_swap_b32_e32 v201, v217
	v_permlane32_swap_b32_e32 v18, v34
	v_permlane32_swap_b32_e32 v202, v218
	v_permlane32_swap_b32_e32 v19, v35
	v_permlane32_swap_b32_e32 v203, v219
	v_pk_fma_f32 v[16:17], v[10:11], v[14:15], v[16:17] op_sel_hi:[0,1,1]
	v_pk_fma_f32 v[200:201], v[8:9], v[12:13], v[200:201] op_sel:[1,0,0]
	v_permlane32_swap_b32_e32 v20, v36
	v_pk_fma_f32 v[12:13], v[8:9], v[12:13], v[16:17] op_sel_hi:[0,1,1]
	v_pk_fma_f32 v[14:15], v[8:9], v[14:15], v[200:201] op_sel_hi:[0,1,1]
	v_permlane32_swap_b32_e32 v204, v220
	s_waitcnt vmcnt(7)
; #define LDS_WAIT() asm volatile("s_waitcnt lgkmcnt(0)" ::: "memory")
; __device__ __forceinline__ void p5_phase(Frame& F) {
;     ...
;     for (int it = F.gw; it < NB * NCH * NGRP; it += F.ngw) {
;         bf16x8 afr[4];
; #pragma unroll
;         for (int sub = 0; sub < 4; ++sub) afr[sub] = nfr[sub];
;         if (it + F.ngw < NB * NCH * NGRP) { const int bc = (it + F.ngw) >> 7, r0 = (bc / NCH) * SEQ + (bc % NCH) * TCH;
; #pragma unroll
;             for (int sub = 0; sub < 4; ++sub) nfr[sub] = ssm_load_afrag(U, r0 + 16 * sub, g, F.lane); }
;         float sr = 0.f, si = 0.f;
; #pragma unroll
;         for (int sub = 0; sub < 4; ++sub) {
;             ssm_bu16(afr[sub], bf, bubuf, F.lane);
; #pragma unroll
;             for (int tt = 0; tt < 16; ++tt) { const float bur = bubuf[tt * BUP + F.lane], bui = bubuf[tt * BUP + 64 + F.lane];
;                 const float nr = fmaf(ab.x, sr, fmaf(-ab.y, si, bur)), ni = fmaf(ab.x, si, fmaf(ab.y, sr, bui)); sr = nr; si = ni; }
;             LDS_WAIT(); asm volatile("" ::: "memory");
;         }
;         ((f32x2*)(F.ws + WS_E))[(size_t)it * NST + F.lane] = (f32x2){sr, si};
	v_mfma_f32_32x32x16_bf16 v[112:127], v[88:91], v[48:51], 0
	v_pk_fma_f32 v[18:19], v[10:11], v[14:15], v[18:19] op_sel_hi:[0,1,1]
	v_pk_fma_f32 v[202:203], v[8:9], v[12:13], v[202:203] op_sel:[1,0,0]
	v_permlane32_swap_b32_e32 v21, v37
	v_pk_fma_f32 v[12:13], v[8:9], v[12:13], v[18:19] op_sel_hi:[0,1,1]
	v_pk_fma_f32 v[14:15], v[8:9], v[14:15], v[202:203] op_sel_hi:[0,1,1]
	v_permlane32_swap_b32_e32 v205, v221
	v_mfma_f32_32x32x16_bf16 v[128:143], v[88:91], v[52:55], 0
	v_pk_fma_f32 v[32:33], v[10:11], v[14:15], v[32:33] op_sel_hi:[0,1,1]
	v_pk_fma_f32 v[216:217], v[8:9], v[12:13], v[216:217] op_sel:[1,0,0]
	v_permlane32_swap_b32_e32 v22, v38
	v_pk_fma_f32 v[12:13], v[8:9], v[12:13], v[32:33] op_sel_hi:[0,1,1]
	v_pk_fma_f32 v[14:15], v[8:9], v[14:15], v[216:217] op_sel_hi:[0,1,1]
	v_permlane32_swap_b32_e32 v206, v222
	v_mfma_f32_32x32x16_bf16 v[144:159], v[88:91], v[56:59], 0
	v_pk_fma_f32 v[34:35], v[10:11], v[14:15], v[34:35] op_sel_hi:[0,1,1]
	v_pk_fma_f32 v[218:219], v[8:9], v[12:13], v[218:219] op_sel:[1,0,0]
	v_permlane32_swap_b32_e32 v23, v39
	v_pk_fma_f32 v[12:13], v[8:9], v[12:13], v[34:35] op_sel_hi:[0,1,1]
	v_pk_fma_f32 v[14:15], v[8:9], v[14:15], v[218:219] op_sel_hi:[0,1,1]
	v_permlane32_swap_b32_e32 v207, v223
	v_mfma_f32_32x32x16_bf16 v[160:175], v[88:91], v[60:63], 0
	v_pk_fma_f32 v[20:21], v[10:11], v[14:15], v[20:21] op_sel_hi:[0,1,1]
	v_pk_fma_f32 v[204:205], v[8:9], v[12:13], v[204:205] op_sel:[1,0,0]
	v_permlane32_swap_b32_e32 v24, v40
	v_pk_fma_f32 v[12:13], v[8:9], v[12:13], v[20:21] op_sel_hi:[0,1,1]
	v_pk_fma_f32 v[14:15], v[8:9], v[14:15], v[204:205] op_sel_hi:[0,1,1]
	v_permlane32_swap_b32_e32 v208, v224
	v_mfma_f32_32x32x16_bf16 v[112:127], v[88:91], v[64:67], v[112:127]
	v_pk_fma_f32 v[22:23], v[10:11], v[14:15], v[22:23] op_sel_hi:[0,1,1]
	v_pk_fma_f32 v[206:207], v[8:9], v[12:13], v[206:207] op_sel:[1,0,0]
	v_permlane32_swap_b32_e32 v25, v41
	v_pk_fma_f32 v[12:13], v[8:9], v[12:13], v[22:23] op_sel_hi:[0,1,1]
	v_pk_fma_f32 v[14:15], v[8:9], v[14:15], v[206:207] op_sel_hi:[0,1,1]
	v_permlane32_swap_b32_e32 v209, v225
	v_mfma_f32_32x32x16_bf16 v[128:143], v[88:91], v[68:71], v[128:143]
	v_pk_fma_f32 v[36:37], v[10:11], v[14:15], v[36:37] op_sel_hi:[0,1,1]
	v_pk_fma_f32 v[220:221], v[8:9], v[12:13], v[220:221] op_sel:[1,0,0]
	v_permlane32_swap_b32_e32 v26, v42
	v_pk_fma_f32 v[12:13], v[8:9], v[12:13], v[36:37] op_sel_hi:[0,1,1]
	v_pk_fma_f32 v[14:15], v[8:9], v[14:15], v[220:221] op_sel_hi:[0,1,1]
	v_permlane32_swap_b32_e32 v210, v226
	v_mfma_f32_32x32x16_bf16 v[144:159], v[88:91], v[72:75], v[144:159]
	v_pk_fma_f32 v[38:39], v[10:11], v[14:15], v[38:39] op_sel_hi:[0,1,1]
	v_pk_fma_f32 v[222:223], v[8:9], v[12:13], v[222:223] op_sel:[1,0,0]
	v_permlane32_swap_b32_e32 v27, v43
	v_pk_fma_f32 v[12:13], v[8:9], v[12:13], v[38:39] op_sel_hi:[0,1,1]
	v_pk_fma_f32 v[14:15], v[8:9], v[14:15], v[222:223] op_sel_hi:[0,1,1]
	v_permlane32_swap_b32_e32 v211, v227
	v_mfma_f32_32x32x16_bf16 v[160:175], v[88:91], v[76:79], v[160:175]
	v_pk_fma_f32 v[24:25], v[10:11], v[14:15], v[24:25] op_sel_hi:[0,1,1]
	v_pk_fma_f32 v[208:209], v[8:9], v[12:13], v[208:209] op_sel:[1,0,0]
	v_permlane32_swap_b32_e32 v28, v44
	v_pk_fma_f32 v[12:13], v[8:9], v[12:13], v[24:25] op_sel_hi:[0,1,1]
	v_pk_fma_f32 v[14:15], v[8:9], v[14:15], v[208:209] op_sel_hi:[0,1,1]
	v_permlane32_swap_b32_e32 v212, v228
	v_pk_fma_f32 v[26:27], v[10:11], v[14:15], v[26:27] op_sel_hi:[0,1,1]
	v_pk_fma_f32 v[210:211], v[8:9], v[12:13], v[210:211] op_sel:[1,0,0]
	v_permlane32_swap_b32_e32 v29, v45
	v_pk_fma_f32 v[12:13], v[8:9], v[12:13], v[26:27] op_sel_hi:[0,1,1]
	v_pk_fma_f32 v[14:15], v[8:9], v[14:15], v[210:211] op_sel_hi:[0,1,1]
	v_permlane32_swap_b32_e32 v213, v229
	v_pk_fma_f32 v[40:41], v[10:11], v[14:15], v[40:41] op_sel_hi:[0,1,1]
	v_pk_fma_f32 v[224:225], v[8:9], v[12:13], v[224:225] op_sel:[1,0,0]
	v_permlane32_swap_b32_e32 v30, v46
	v_pk_fma_f32 v[12:13], v[8:9], v[12:13], v[40:41] op_sel_hi:[0,1,1]
	v_pk_fma_f32 v[14:15], v[8:9], v[14:15], v[224:225] op_sel_hi:[0,1,1]
	v_permlane32_swap_b32_e32 v214, v230
	v_pk_fma_f32 v[42:43], v[10:11], v[14:15], v[42:43] op_sel_hi:[0,1,1]
	v_pk_fma_f32 v[226:227], v[8:9], v[12:13], v[226:227] op_sel:[1,0,0]
	v_permlane32_swap_b32_e32 v31, v47
	v_pk_fma_f32 v[12:13], v[8:9], v[12:13], v[42:43] op_sel_hi:[0,1,1]
	v_pk_fma_f32 v[14:15], v[8:9], v[14:15], v[226:227] op_sel_hi:[0,1,1]
	v_permlane32_swap_b32_e32 v215, v231
	v_pk_fma_f32 v[28:29], v[10:11], v[14:15], v[28:29] op_sel_hi:[0,1,1]
	v_pk_fma_f32 v[212:213], v[8:9], v[12:13], v[212:213] op_sel:[1,0,0]
	s_nop 0
	v_pk_fma_f32 v[12:13], v[8:9], v[12:13], v[28:29] op_sel_hi:[0,1,1]
	v_pk_fma_f32 v[14:15], v[8:9], v[14:15], v[212:213] op_sel_hi:[0,1,1]
	s_nop 0
	v_pk_fma_f32 v[30:31], v[10:11], v[14:15], v[30:31] op_sel_hi:[0,1,1]
	v_pk_fma_f32 v[214:215], v[8:9], v[12:13], v[214:215] op_sel:[1,0,0]
	s_nop 0
	v_pk_fma_f32 v[12:13], v[8:9], v[12:13], v[30:31] op_sel_hi:[0,1,1]
	v_pk_fma_f32 v[14:15], v[8:9], v[14:15], v[214:215] op_sel_hi:[0,1,1]
	s_nop 0
	v_pk_fma_f32 v[44:45], v[10:11], v[14:15], v[44:45] op_sel_hi:[0,1,1]
	v_pk_fma_f32 v[228:229], v[8:9], v[12:13], v[228:229] op_sel:[1,0,0]
	s_nop 0
	v_pk_fma_f32 v[12:13], v[8:9], v[12:13], v[44:45] op_sel_hi:[0,1,1]
	v_pk_fma_f32 v[14:15], v[8:9], v[14:15], v[228:229] op_sel_hi:[0,1,1]
	s_nop 0
	v_pk_fma_f32 v[46:47], v[10:11], v[14:15], v[46:47] op_sel_hi:[0,1,1]
	v_pk_fma_f32 v[230:231], v[8:9], v[12:13], v[230:231] op_sel:[1,0,0]
	s_nop 0
	v_pk_fma_f32 v[12:13], v[8:9], v[12:13], v[46:47] op_sel_hi:[0,1,1]
	v_pk_fma_f32 v[14:15], v[8:9], v[14:15], v[230:231] op_sel_hi:[0,1,1]
	s_nop 0
	s_nop 0
	v_fma_f32 v181, v180, v14, v13
	v_fma_f32 v182, v179, v12, v15
	v_fma_f32 v12, v178, v12, v181
	v_fma_f32 v14, v178, v14, v182
	v_mov_b32_e32 v13, 0
	v_mov_b32_e32 v15, 0
	v_mov_b32_e32 v182, v12
	v_mov_b32_e32 v183, v14
	global_store_dwordx2 v7, v[182:183], s[48:49]
	s_add_u32 s48, s48, 0x100000
	s_addc_u32 s49, s49, 0
	v_mov_b32_e32 v12, 0
	v_mov_b32_e32 v13, 0
	v_mov_b32_e32 v14, 0
	v_mov_b32_e32 v15, 0
	s_nop 3
	v_permlane32_swap_b32_e32 v112, v128
	v_permlane32_swap_b32_e32 v144, v160
	v_permlane32_swap_b32_e32 v113, v129
	v_permlane32_swap_b32_e32 v145, v161
	v_permlane32_swap_b32_e32 v114, v130
	v_permlane32_swap_b32_e32 v146, v162
	v_permlane32_swap_b32_e32 v115, v131
	v_permlane32_swap_b32_e32 v147, v163
	v_pk_fma_f32 v[112:113], v[10:11], v[14:15], v[112:113] op_sel_hi:[0,1,1]
	v_pk_fma_f32 v[144:145], v[8:9], v[12:13], v[144:145] op_sel:[1,0,0]
	v_permlane32_swap_b32_e32 v116, v132
	v_pk_fma_f32 v[12:13], v[8:9], v[12:13], v[112:113] op_sel_hi:[0,1,1]
	v_pk_fma_f32 v[14:15], v[8:9], v[14:15], v[144:145] op_sel_hi:[0,1,1]
	v_permlane32_swap_b32_e32 v148, v164
	s_waitcnt vmcnt(7)
; #define LDS_WAIT() asm volatile("s_waitcnt lgkmcnt(0)" ::: "memory")
; __device__ __forceinline__ void p5_phase(Frame& F) {
;     ...
;     for (int it = F.gw; it < NB * NCH * NGRP; it += F.ngw) {
;         bf16x8 afr[4];
; #pragma unroll
;         for (int sub = 0; sub < 4; ++sub) afr[sub] = nfr[sub];
;         if (it + F.ngw < NB * NCH * NGRP) { const int bc = (it + F.ngw) >> 7, r0 = (bc / NCH) * SEQ + (bc % NCH) * TCH;
; #pragma unroll
;             for (int sub = 0; sub < 4; ++sub) nfr[sub] = ssm_load_afrag(U, r0 + 16 * sub, g, F.lane); }
;         float sr = 0.f, si = 0.f;
; #pragma unroll
;         for (int sub = 0; sub < 4; ++sub) {
;             ssm_bu16(afr[sub], bf, bubuf, F.lane);
; #pragma unroll
;             for (int tt = 0; tt < 16; ++tt) { const float bur = bubuf[tt * BUP + F.lane], bui = bubuf[tt * BUP + 64 + F.lane];
;                 const float nr = fmaf(ab.x, sr, fmaf(-ab.y, si, bur)), ni = fmaf(ab.x, si, fmaf(ab.y, sr, bui)); sr = nr; si = ni; }
;             LDS_WAIT(); asm volatile("" ::: "memory");
;         }
	v_mfma_f32_32x32x16_bf16 v[16:31], v[92:95], v[48:51], 0
	v_pk_fma_f32 v[114:115], v[10:11], v[14:15], v[114:115] op_sel_hi:[0,1,1]
	v_pk_fma_f32 v[146:147], v[8:9], v[12:13], v[146:147] op_sel:[1,0,0]
	v_permlane32_swap_b32_e32 v117, v133
	v_pk_fma_f32 v[12:13], v[8:9], v[12:13], v[114:115] op_sel_hi:[0,1,1]
	v_pk_fma_f32 v[14:15], v[8:9], v[14:15], v[146:147] op_sel_hi:[0,1,1]
	v_permlane32_swap_b32_e32 v149, v165
	v_mfma_f32_32x32x16_bf16 v[32:47], v[92:95], v[52:55], 0
	v_pk_fma_f32 v[128:129], v[10:11], v[14:15], v[128:129] op_sel_hi:[0,1,1]
	v_pk_fma_f32 v[160:161], v[8:9], v[12:13], v[160:161] op_sel:[1,0,0]
	v_permlane32_swap_b32_e32 v118, v134
	v_pk_fma_f32 v[12:13], v[8:9], v[12:13], v[128:129] op_sel_hi:[0,1,1]
	v_pk_fma_f32 v[14:15], v[8:9], v[14:15], v[160:161] op_sel_hi:[0,1,1]
	v_permlane32_swap_b32_e32 v150, v166
	v_mfma_f32_32x32x16_bf16 v[200:215], v[92:95], v[56:59], 0
	v_pk_fma_f32 v[130:131], v[10:11], v[14:15], v[130:131] op_sel_hi:[0,1,1]
	v_pk_fma_f32 v[162:163], v[8:9], v[12:13], v[162:163] op_sel:[1,0,0]
	v_permlane32_swap_b32_e32 v119, v135
	v_pk_fma_f32 v[12:13], v[8:9], v[12:13], v[130:131] op_sel_hi:[0,1,1]
	v_pk_fma_f32 v[14:15], v[8:9], v[14:15], v[162:163] op_sel_hi:[0,1,1]
	v_permlane32_swap_b32_e32 v151, v167
	v_mfma_f32_32x32x16_bf16 v[216:231], v[92:95], v[60:63], 0
	v_pk_fma_f32 v[116:117], v[10:11], v[14:15], v[116:117] op_sel_hi:[0,1,1]
	v_pk_fma_f32 v[148:149], v[8:9], v[12:13], v[148:149] op_sel:[1,0,0]
	v_permlane32_swap_b32_e32 v120, v136
	v_pk_fma_f32 v[12:13], v[8:9], v[12:13], v[116:117] op_sel_hi:[0,1,1]
	v_pk_fma_f32 v[14:15], v[8:9], v[14:15], v[148:149] op_sel_hi:[0,1,1]
	v_permlane32_swap_b32_e32 v152, v168
	v_mfma_f32_32x32x16_bf16 v[16:31], v[92:95], v[64:67], v[16:31]
	v_pk_fma_f32 v[118:119], v[10:11], v[14:15], v[118:119] op_sel_hi:[0,1,1]
	v_pk_fma_f32 v[150:151], v[8:9], v[12:13], v[150:151] op_sel:[1,0,0]
	v_permlane32_swap_b32_e32 v121, v137
	v_pk_fma_f32 v[12:13], v[8:9], v[12:13], v[118:119] op_sel_hi:[0,1,1]
	v_pk_fma_f32 v[14:15], v[8:9], v[14:15], v[150:151] op_sel_hi:[0,1,1]
	v_permlane32_swap_b32_e32 v153, v169
	v_mfma_f32_32x32x16_bf16 v[32:47], v[92:95], v[68:71], v[32:47]
	v_pk_fma_f32 v[132:133], v[10:11], v[14:15], v[132:133] op_sel_hi:[0,1,1]
	v_pk_fma_f32 v[164:165], v[8:9], v[12:13], v[164:165] op_sel:[1,0,0]
	v_permlane32_swap_b32_e32 v122, v138
	v_pk_fma_f32 v[12:13], v[8:9], v[12:13], v[132:133] op_sel_hi:[0,1,1]
	v_pk_fma_f32 v[14:15], v[8:9], v[14:15], v[164:165] op_sel_hi:[0,1,1]
	v_permlane32_swap_b32_e32 v154, v170
	v_mfma_f32_32x32x16_bf16 v[200:215], v[92:95], v[72:75], v[200:215]
	v_pk_fma_f32 v[134:135], v[10:11], v[14:15], v[134:135] op_sel_hi:[0,1,1]
	v_pk_fma_f32 v[166:167], v[8:9], v[12:13], v[166:167] op_sel:[1,0,0]
	v_permlane32_swap_b32_e32 v123, v139
	v_pk_fma_f32 v[12:13], v[8:9], v[12:13], v[134:135] op_sel_hi:[0,1,1]
	v_pk_fma_f32 v[14:15], v[8:9], v[14:15], v[166:167] op_sel_hi:[0,1,1]
	v_permlane32_swap_b32_e32 v155, v171
	v_mfma_f32_32x32x16_bf16 v[216:231], v[92:95], v[76:79], v[216:231]
	v_pk_fma_f32 v[120:121], v[10:11], v[14:15], v[120:121] op_sel_hi:[0,1,1]
	v_pk_fma_f32 v[152:153], v[8:9], v[12:13], v[152:153] op_sel:[1,0,0]
	v_permlane32_swap_b32_e32 v124, v140
	v_pk_fma_f32 v[12:13], v[8:9], v[12:13], v[120:121] op_sel_hi:[0,1,1]
	v_pk_fma_f32 v[14:15], v[8:9], v[14:15], v[152:153] op_sel_hi:[0,1,1]
	v_permlane32_swap_b32_e32 v156, v172
	v_pk_fma_f32 v[122:123], v[10:11], v[14:15], v[122:123] op_sel_hi:[0,1,1]
	v_pk_fma_f32 v[154:155], v[8:9], v[12:13], v[154:155] op_sel:[1,0,0]
	v_permlane32_swap_b32_e32 v125, v141
	v_pk_fma_f32 v[12:13], v[8:9], v[12:13], v[122:123] op_sel_hi:[0,1,1]
	v_pk_fma_f32 v[14:15], v[8:9], v[14:15], v[154:155] op_sel_hi:[0,1,1]
	v_permlane32_swap_b32_e32 v157, v173
	v_pk_fma_f32 v[136:137], v[10:11], v[14:15], v[136:137] op_sel_hi:[0,1,1]
	v_pk_fma_f32 v[168:169], v[8:9], v[12:13], v[168:169] op_sel:[1,0,0]
	v_permlane32_swap_b32_e32 v126, v142
	v_pk_fma_f32 v[12:13], v[8:9], v[12:13], v[136:137] op_sel_hi:[0,1,1]
	v_pk_fma_f32 v[14:15], v[8:9], v[14:15], v[168:169] op_sel_hi:[0,1,1]
	v_permlane32_swap_b32_e32 v158, v174
	v_pk_fma_f32 v[138:139], v[10:11], v[14:15], v[138:139] op_sel_hi:[0,1,1]
	v_pk_fma_f32 v[170:171], v[8:9], v[12:13], v[170:171] op_sel:[1,0,0]
	v_permlane32_swap_b32_e32 v127, v143
	v_pk_fma_f32 v[12:13], v[8:9], v[12:13], v[138:139] op_sel_hi:[0,1,1]
	v_pk_fma_f32 v[14:15], v[8:9], v[14:15], v[170:171] op_sel_hi:[0,1,1]
	v_permlane32_swap_b32_e32 v159, v175
	v_pk_fma_f32 v[124:125], v[10:11], v[14:15], v[124:125] op_sel_hi:[0,1,1]
	v_pk_fma_f32 v[156:157], v[8:9], v[12:13], v[156:157] op_sel:[1,0,0]
	s_nop 0
	v_pk_fma_f32 v[12:13], v[8:9], v[12:13], v[124:125] op_sel_hi:[0,1,1]
	v_pk_fma_f32 v[14:15], v[8:9], v[14:15], v[156:157] op_sel_hi:[0,1,1]
	s_nop 0
	v_pk_fma_f32 v[126:127], v[10:11], v[14:15], v[126:127] op_sel_hi:[0,1,1]
	v_pk_fma_f32 v[158:159], v[8:9], v[12:13], v[158:159] op_sel:[1,0,0]
	s_nop 0
	v_pk_fma_f32 v[12:13], v[8:9], v[12:13], v[126:127] op_sel_hi:[0,1,1]
	v_pk_fma_f32 v[14:15], v[8:9], v[14:15], v[158:159] op_sel_hi:[0,1,1]
	s_nop 0
	v_pk_fma_f32 v[140:141], v[10:11], v[14:15], v[140:141] op_sel_hi:[0,1,1]
	v_pk_fma_f32 v[172:173], v[8:9], v[12:13], v[172:173] op_sel:[1,0,0]
	s_nop 0
	v_pk_fma_f32 v[12:13], v[8:9], v[12:13], v[140:141] op_sel_hi:[0,1,1]
	v_pk_fma_f32 v[14:15], v[8:9], v[14:15], v[172:173] op_sel_hi:[0,1,1]
	s_nop 0
	v_pk_fma_f32 v[142:143], v[10:11], v[14:15], v[142:143] op_sel_hi:[0,1,1]
	v_pk_fma_f32 v[174:175], v[8:9], v[12:13], v[174:175] op_sel:[1,0,0]
	s_nop 0
	v_pk_fma_f32 v[12:13], v[8:9], v[12:13], v[142:143] op_sel_hi:[0,1,1]
	v_pk_fma_f32 v[14:15], v[8:9], v[14:15], v[174:175] op_sel_hi:[0,1,1]
	s_nop 0
	s_nop 0
	v_fma_f32 v181, v180, v14, v13
	v_fma_f32 v182, v179, v12, v15
	v_fma_f32 v12, v178, v12, v181
	v_fma_f32 v14, v178, v14, v182
	v_mov_b32_e32 v13, 0
	v_mov_b32_e32 v15, 0
	s_nop 3
	v_permlane32_swap_b32_e32 v16, v32
	v_permlane32_swap_b32_e32 v200, v216
	v_permlane32_swap_b32_e32 v17, v33
	v_permlane32_swap_b32_e32 v201, v217
	v_permlane32_swap_b32_e32 v18, v34
	v_permlane32_swap_b32_e32 v202, v218
	v_permlane32_swap_b32_e32 v19, v35
	v_permlane32_swap_b32_e32 v203, v219
	v_pk_fma_f32 v[16:17], v[10:11], v[14:15], v[16:17] op_sel_hi:[0,1,1]
	v_pk_fma_f32 v[200:201], v[8:9], v[12:13], v[200:201] op_sel:[1,0,0]
	v_permlane32_swap_b32_e32 v20, v36
	v_pk_fma_f32 v[12:13], v[8:9], v[12:13], v[16:17] op_sel_hi:[0,1,1]
	v_pk_fma_f32 v[14:15], v[8:9], v[14:15], v[200:201] op_sel_hi:[0,1,1]
	v_permlane32_swap_b32_e32 v204, v220
	s_waitcnt vmcnt(5)
; #define LDS_WAIT() asm volatile("s_waitcnt lgkmcnt(0)" ::: "memory")
; __device__ __forceinline__ void p5_phase(Frame& F) {
;     ...
;     for (int it = F.gw; it < NB * NCH * NGRP; it += F.ngw) {
;         bf16x8 afr[4];
; #pragma unroll
;         for (int sub = 0; sub < 4; ++sub) afr[sub] = nfr[sub];
;         if (it + F.ngw < NB * NCH * NGRP) { const int bc = (it + F.ngw) >> 7, r0 = (bc / NCH) * SEQ + (bc % NCH) * TCH;
; #pragma unroll
;             for (int sub = 0; sub < 4; ++sub) nfr[sub] = ssm_load_afrag(U, r0 + 16 * sub, g, F.lane); }
;         float sr = 0.f, si = 0.f;
; #pragma unroll
;         for (int sub = 0; sub < 4; ++sub) {
;             ssm_bu16(afr[sub], bf, bubuf, F.lane);
; #pragma unroll
;             for (int tt = 0; tt < 16; ++tt) { const float bur = bubuf[tt * BUP + F.lane], bui = bubuf[tt * BUP + 64 + F.lane];
;                 const float nr = fmaf(ab.x, sr, fmaf(-ab.y, si, bur)), ni = fmaf(ab.x, si, fmaf(ab.y, sr, bui)); sr = nr; si = ni; }
;             LDS_WAIT(); asm volatile("" ::: "memory");
;         }
;         ((f32x2*)(F.ws + WS_E))[(size_t)it * NST + F.lane] = (f32x2){sr, si};
	v_mfma_f32_32x32x16_bf16 v[112:127], v[96:99], v[48:51], 0
	v_pk_fma_f32 v[18:19], v[10:11], v[14:15], v[18:19] op_sel_hi:[0,1,1]
	v_pk_fma_f32 v[202:203], v[8:9], v[12:13], v[202:203] op_sel:[1,0,0]
	v_permlane32_swap_b32_e32 v21, v37
	v_pk_fma_f32 v[12:13], v[8:9], v[12:13], v[18:19] op_sel_hi:[0,1,1]
	v_pk_fma_f32 v[14:15], v[8:9], v[14:15], v[202:203] op_sel_hi:[0,1,1]
	v_permlane32_swap_b32_e32 v205, v221
	v_mfma_f32_32x32x16_bf16 v[128:143], v[96:99], v[52:55], 0
	v_pk_fma_f32 v[32:33], v[10:11], v[14:15], v[32:33] op_sel_hi:[0,1,1]
	v_pk_fma_f32 v[216:217], v[8:9], v[12:13], v[216:217] op_sel:[1,0,0]
	v_permlane32_swap_b32_e32 v22, v38
	v_pk_fma_f32 v[12:13], v[8:9], v[12:13], v[32:33] op_sel_hi:[0,1,1]
	v_pk_fma_f32 v[14:15], v[8:9], v[14:15], v[216:217] op_sel_hi:[0,1,1]
	v_permlane32_swap_b32_e32 v206, v222
	v_mfma_f32_32x32x16_bf16 v[144:159], v[96:99], v[56:59], 0
	v_pk_fma_f32 v[34:35], v[10:11], v[14:15], v[34:35] op_sel_hi:[0,1,1]
	v_pk_fma_f32 v[218:219], v[8:9], v[12:13], v[218:219] op_sel:[1,0,0]
	v_permlane32_swap_b32_e32 v23, v39
	v_pk_fma_f32 v[12:13], v[8:9], v[12:13], v[34:35] op_sel_hi:[0,1,1]
	v_pk_fma_f32 v[14:15], v[8:9], v[14:15], v[218:219] op_sel_hi:[0,1,1]
	v_permlane32_swap_b32_e32 v207, v223
	v_mfma_f32_32x32x16_bf16 v[160:175], v[96:99], v[60:63], 0
	v_pk_fma_f32 v[20:21], v[10:11], v[14:15], v[20:21] op_sel_hi:[0,1,1]
	v_pk_fma_f32 v[204:205], v[8:9], v[12:13], v[204:205] op_sel:[1,0,0]
	v_permlane32_swap_b32_e32 v24, v40
	v_pk_fma_f32 v[12:13], v[8:9], v[12:13], v[20:21] op_sel_hi:[0,1,1]
	v_pk_fma_f32 v[14:15], v[8:9], v[14:15], v[204:205] op_sel_hi:[0,1,1]
	v_permlane32_swap_b32_e32 v208, v224
	v_mfma_f32_32x32x16_bf16 v[112:127], v[96:99], v[64:67], v[112:127]
	v_pk_fma_f32 v[22:23], v[10:11], v[14:15], v[22:23] op_sel_hi:[0,1,1]
	v_pk_fma_f32 v[206:207], v[8:9], v[12:13], v[206:207] op_sel:[1,0,0]
	v_permlane32_swap_b32_e32 v25, v41
	v_pk_fma_f32 v[12:13], v[8:9], v[12:13], v[22:23] op_sel_hi:[0,1,1]
	v_pk_fma_f32 v[14:15], v[8:9], v[14:15], v[206:207] op_sel_hi:[0,1,1]
	v_permlane32_swap_b32_e32 v209, v225
	v_mfma_f32_32x32x16_bf16 v[128:143], v[96:99], v[68:71], v[128:143]
	v_pk_fma_f32 v[36:37], v[10:11], v[14:15], v[36:37] op_sel_hi:[0,1,1]
	v_pk_fma_f32 v[220:221], v[8:9], v[12:13], v[220:221] op_sel:[1,0,0]
	v_permlane32_swap_b32_e32 v26, v42
	v_pk_fma_f32 v[12:13], v[8:9], v[12:13], v[36:37] op_sel_hi:[0,1,1]
	v_pk_fma_f32 v[14:15], v[8:9], v[14:15], v[220:221] op_sel_hi:[0,1,1]
	v_permlane32_swap_b32_e32 v210, v226
	v_mfma_f32_32x32x16_bf16 v[144:159], v[96:99], v[72:75], v[144:159]
	v_pk_fma_f32 v[38:39], v[10:11], v[14:15], v[38:39] op_sel_hi:[0,1,1]
	v_pk_fma_f32 v[222:223], v[8:9], v[12:13], v[222:223] op_sel:[1,0,0]
	v_permlane32_swap_b32_e32 v27, v43
	v_pk_fma_f32 v[12:13], v[8:9], v[12:13], v[38:39] op_sel_hi:[0,1,1]
	v_pk_fma_f32 v[14:15], v[8:9], v[14:15], v[222:223] op_sel_hi:[0,1,1]
	v_permlane32_swap_b32_e32 v211, v227
	v_mfma_f32_32x32x16_bf16 v[160:175], v[96:99], v[76:79], v[160:175]
	v_pk_fma_f32 v[24:25], v[10:11], v[14:15], v[24:25] op_sel_hi:[0,1,1]
	v_pk_fma_f32 v[208:209], v[8:9], v[12:13], v[208:209] op_sel:[1,0,0]
	v_permlane32_swap_b32_e32 v28, v44
	v_pk_fma_f32 v[12:13], v[8:9], v[12:13], v[24:25] op_sel_hi:[0,1,1]
	v_pk_fma_f32 v[14:15], v[8:9], v[14:15], v[208:209] op_sel_hi:[0,1,1]
	v_permlane32_swap_b32_e32 v212, v228
	v_pk_fma_f32 v[26:27], v[10:11], v[14:15], v[26:27] op_sel_hi:[0,1,1]
	v_pk_fma_f32 v[210:211], v[8:9], v[12:13], v[210:211] op_sel:[1,0,0]
	v_permlane32_swap_b32_e32 v29, v45
	v_pk_fma_f32 v[12:13], v[8:9], v[12:13], v[26:27] op_sel_hi:[0,1,1]
	v_pk_fma_f32 v[14:15], v[8:9], v[14:15], v[210:211] op_sel_hi:[0,1,1]
	v_permlane32_swap_b32_e32 v213, v229
	v_pk_fma_f32 v[40:41], v[10:11], v[14:15], v[40:41] op_sel_hi:[0,1,1]
	v_pk_fma_f32 v[224:225], v[8:9], v[12:13], v[224:225] op_sel:[1,0,0]
	v_permlane32_swap_b32_e32 v30, v46
	v_pk_fma_f32 v[12:13], v[8:9], v[12:13], v[40:41] op_sel_hi:[0,1,1]
	v_pk_fma_f32 v[14:15], v[8:9], v[14:15], v[224:225] op_sel_hi:[0,1,1]
	v_permlane32_swap_b32_e32 v214, v230
	v_pk_fma_f32 v[42:43], v[10:11], v[14:15], v[42:43] op_sel_hi:[0,1,1]
	v_pk_fma_f32 v[226:227], v[8:9], v[12:13], v[226:227] op_sel:[1,0,0]
	v_permlane32_swap_b32_e32 v31, v47
	v_pk_fma_f32 v[12:13], v[8:9], v[12:13], v[42:43] op_sel_hi:[0,1,1]
	v_pk_fma_f32 v[14:15], v[8:9], v[14:15], v[226:227] op_sel_hi:[0,1,1]
	v_permlane32_swap_b32_e32 v215, v231
	v_pk_fma_f32 v[28:29], v[10:11], v[14:15], v[28:29] op_sel_hi:[0,1,1]
	v_pk_fma_f32 v[212:213], v[8:9], v[12:13], v[212:213] op_sel:[1,0,0]
	s_nop 0
	v_pk_fma_f32 v[12:13], v[8:9], v[12:13], v[28:29] op_sel_hi:[0,1,1]
	v_pk_fma_f32 v[14:15], v[8:9], v[14:15], v[212:213] op_sel_hi:[0,1,1]
	s_nop 0
	v_pk_fma_f32 v[30:31], v[10:11], v[14:15], v[30:31] op_sel_hi:[0,1,1]
	v_pk_fma_f32 v[214:215], v[8:9], v[12:13], v[214:215] op_sel:[1,0,0]
	s_nop 0
	v_pk_fma_f32 v[12:13], v[8:9], v[12:13], v[30:31] op_sel_hi:[0,1,1]
	v_pk_fma_f32 v[14:15], v[8:9], v[14:15], v[214:215] op_sel_hi:[0,1,1]
	s_nop 0
	v_pk_fma_f32 v[44:45], v[10:11], v[14:15], v[44:45] op_sel_hi:[0,1,1]
	v_pk_fma_f32 v[228:229], v[8:9], v[12:13], v[228:229] op_sel:[1,0,0]
	s_nop 0
	v_pk_fma_f32 v[12:13], v[8:9], v[12:13], v[44:45] op_sel_hi:[0,1,1]
	v_pk_fma_f32 v[14:15], v[8:9], v[14:15], v[228:229] op_sel_hi:[0,1,1]
	s_nop 0
	v_pk_fma_f32 v[46:47], v[10:11], v[14:15], v[46:47] op_sel_hi:[0,1,1]
	v_pk_fma_f32 v[230:231], v[8:9], v[12:13], v[230:231] op_sel:[1,0,0]
	s_nop 0
	v_pk_fma_f32 v[12:13], v[8:9], v[12:13], v[46:47] op_sel_hi:[0,1,1]
	v_pk_fma_f32 v[14:15], v[8:9], v[14:15], v[230:231] op_sel_hi:[0,1,1]
	s_nop 0
	s_nop 0
	v_fma_f32 v181, v180, v14, v13
	v_fma_f32 v182, v179, v12, v15
	v_fma_f32 v12, v178, v12, v181
	v_fma_f32 v14, v178, v14, v182
	v_mov_b32_e32 v13, 0
	v_mov_b32_e32 v15, 0
	v_mov_b32_e32 v182, v12
	v_mov_b32_e32 v183, v14
	global_store_dwordx2 v7, v[182:183], s[48:49]
	s_add_u32 s48, s48, 0x100000
	s_addc_u32 s49, s49, 0
	v_mov_b32_e32 v12, 0
	v_mov_b32_e32 v13, 0
	v_mov_b32_e32 v14, 0
	v_mov_b32_e32 v15, 0
	s_nop 3
	v_permlane32_swap_b32_e32 v112, v128
	v_permlane32_swap_b32_e32 v144, v160
	v_permlane32_swap_b32_e32 v113, v129
	v_permlane32_swap_b32_e32 v145, v161
	v_permlane32_swap_b32_e32 v114, v130
	v_permlane32_swap_b32_e32 v146, v162
	v_permlane32_swap_b32_e32 v115, v131
	v_permlane32_swap_b32_e32 v147, v163
	v_pk_fma_f32 v[112:113], v[10:11], v[14:15], v[112:113] op_sel_hi:[0,1,1]
	v_pk_fma_f32 v[144:145], v[8:9], v[12:13], v[144:145] op_sel:[1,0,0]
	v_permlane32_swap_b32_e32 v116, v132
	v_pk_fma_f32 v[12:13], v[8:9], v[12:13], v[112:113] op_sel_hi:[0,1,1]
	v_pk_fma_f32 v[14:15], v[8:9], v[14:15], v[144:145] op_sel_hi:[0,1,1]
	v_permlane32_swap_b32_e32 v148, v164
	s_waitcnt vmcnt(5)
; #define LDS_WAIT() asm volatile("s_waitcnt lgkmcnt(0)" ::: "memory")
; __device__ __forceinline__ void p5_phase(Frame& F) {
;     ...
;     for (int it = F.gw; it < NB * NCH * NGRP; it += F.ngw) {
;         bf16x8 afr[4];
; #pragma unroll
;         for (int sub = 0; sub < 4; ++sub) afr[sub] = nfr[sub];
;         if (it + F.ngw < NB * NCH * NGRP) { const int bc = (it + F.ngw) >> 7, r0 = (bc / NCH) * SEQ + (bc % NCH) * TCH;
; #pragma unroll
;             for (int sub = 0; sub < 4; ++sub) nfr[sub] = ssm_load_afrag(U, r0 + 16 * sub, g, F.lane); }
;         float sr = 0.f, si = 0.f;
; #pragma unroll
;         for (int sub = 0; sub < 4; ++sub) {
;             ssm_bu16(afr[sub], bf, bubuf, F.lane);
; #pragma unroll
;             for (int tt = 0; tt < 16; ++tt) { const float bur = bubuf[tt * BUP + F.lane], bui = bubuf[tt * BUP + 64 + F.lane];
;                 const float nr = fmaf(ab.x, sr, fmaf(-ab.y, si, bur)), ni = fmaf(ab.x, si, fmaf(ab.y, sr, bui)); sr = nr; si = ni; }
;             LDS_WAIT(); asm volatile("" ::: "memory");
;         }
	v_mfma_f32_32x32x16_bf16 v[16:31], v[100:103], v[48:51], 0
	v_pk_fma_f32 v[114:115], v[10:11], v[14:15], v[114:115] op_sel_hi:[0,1,1]
	v_pk_fma_f32 v[146:147], v[8:9], v[12:13], v[146:147] op_sel:[1,0,0]
	v_permlane32_swap_b32_e32 v117, v133
	v_pk_fma_f32 v[12:13], v[8:9], v[12:13], v[114:115] op_sel_hi:[0,1,1]
	v_pk_fma_f32 v[14:15], v[8:9], v[14:15], v[146:147] op_sel_hi:[0,1,1]
	v_permlane32_swap_b32_e32 v149, v165
	v_mfma_f32_32x32x16_bf16 v[32:47], v[100:103], v[52:55], 0
	v_pk_fma_f32 v[128:129], v[10:11], v[14:15], v[128:129] op_sel_hi:[0,1,1]
	v_pk_fma_f32 v[160:161], v[8:9], v[12:13], v[160:161] op_sel:[1,0,0]
	v_permlane32_swap_b32_e32 v118, v134
	v_pk_fma_f32 v[12:13], v[8:9], v[12:13], v[128:129] op_sel_hi:[0,1,1]
	v_pk_fma_f32 v[14:15], v[8:9], v[14:15], v[160:161] op_sel_hi:[0,1,1]
	v_permlane32_swap_b32_e32 v150, v166
	v_mfma_f32_32x32x16_bf16 v[200:215], v[100:103], v[56:59], 0
	v_pk_fma_f32 v[130:131], v[10:11], v[14:15], v[130:131] op_sel_hi:[0,1,1]
	v_pk_fma_f32 v[162:163], v[8:9], v[12:13], v[162:163] op_sel:[1,0,0]
	v_permlane32_swap_b32_e32 v119, v135
	v_pk_fma_f32 v[12:13], v[8:9], v[12:13], v[130:131] op_sel_hi:[0,1,1]
	v_pk_fma_f32 v[14:15], v[8:9], v[14:15], v[162:163] op_sel_hi:[0,1,1]
	v_permlane32_swap_b32_e32 v151, v167
	v_mfma_f32_32x32x16_bf16 v[216:231], v[100:103], v[60:63], 0
	v_pk_fma_f32 v[116:117], v[10:11], v[14:15], v[116:117] op_sel_hi:[0,1,1]
	v_pk_fma_f32 v[148:149], v[8:9], v[12:13], v[148:149] op_sel:[1,0,0]
	v_permlane32_swap_b32_e32 v120, v136
	v_pk_fma_f32 v[12:13], v[8:9], v[12:13], v[116:117] op_sel_hi:[0,1,1]
	v_pk_fma_f32 v[14:15], v[8:9], v[14:15], v[148:149] op_sel_hi:[0,1,1]
	v_permlane32_swap_b32_e32 v152, v168
	v_mfma_f32_32x32x16_bf16 v[16:31], v[100:103], v[64:67], v[16:31]
	v_pk_fma_f32 v[118:119], v[10:11], v[14:15], v[118:119] op_sel_hi:[0,1,1]
	v_pk_fma_f32 v[150:151], v[8:9], v[12:13], v[150:151] op_sel:[1,0,0]
	v_permlane32_swap_b32_e32 v121, v137
	v_pk_fma_f32 v[12:13], v[8:9], v[12:13], v[118:119] op_sel_hi:[0,1,1]
	v_pk_fma_f32 v[14:15], v[8:9], v[14:15], v[150:151] op_sel_hi:[0,1,1]
	v_permlane32_swap_b32_e32 v153, v169
	v_mfma_f32_32x32x16_bf16 v[32:47], v[100:103], v[68:71], v[32:47]
	v_pk_fma_f32 v[132:133], v[10:11], v[14:15], v[132:133] op_sel_hi:[0,1,1]
	v_pk_fma_f32 v[164:165], v[8:9], v[12:13], v[164:165] op_sel:[1,0,0]
	v_permlane32_swap_b32_e32 v122, v138
	v_pk_fma_f32 v[12:13], v[8:9], v[12:13], v[132:133] op_sel_hi:[0,1,1]
	v_pk_fma_f32 v[14:15], v[8:9], v[14:15], v[164:165] op_sel_hi:[0,1,1]
	v_permlane32_swap_b32_e32 v154, v170
	v_mfma_f32_32x32x16_bf16 v[200:215], v[100:103], v[72:75], v[200:215]
	v_pk_fma_f32 v[134:135], v[10:11], v[14:15], v[134:135] op_sel_hi:[0,1,1]
	v_pk_fma_f32 v[166:167], v[8:9], v[12:13], v[166:167] op_sel:[1,0,0]
	v_permlane32_swap_b32_e32 v123, v139
	v_pk_fma_f32 v[12:13], v[8:9], v[12:13], v[134:135] op_sel_hi:[0,1,1]
	v_pk_fma_f32 v[14:15], v[8:9], v[14:15], v[166:167] op_sel_hi:[0,1,1]
	v_permlane32_swap_b32_e32 v155, v171
	v_mfma_f32_32x32x16_bf16 v[216:231], v[100:103], v[76:79], v[216:231]
	v_pk_fma_f32 v[120:121], v[10:11], v[14:15], v[120:121] op_sel_hi:[0,1,1]
	v_pk_fma_f32 v[152:153], v[8:9], v[12:13], v[152:153] op_sel:[1,0,0]
	v_permlane32_swap_b32_e32 v124, v140
	v_pk_fma_f32 v[12:13], v[8:9], v[12:13], v[120:121] op_sel_hi:[0,1,1]
	v_pk_fma_f32 v[14:15], v[8:9], v[14:15], v[152:153] op_sel_hi:[0,1,1]
	v_permlane32_swap_b32_e32 v156, v172
	v_pk_fma_f32 v[122:123], v[10:11], v[14:15], v[122:123] op_sel_hi:[0,1,1]
	v_pk_fma_f32 v[154:155], v[8:9], v[12:13], v[154:155] op_sel:[1,0,0]
	v_permlane32_swap_b32_e32 v125, v141
	v_pk_fma_f32 v[12:13], v[8:9], v[12:13], v[122:123] op_sel_hi:[0,1,1]
	v_pk_fma_f32 v[14:15], v[8:9], v[14:15], v[154:155] op_sel_hi:[0,1,1]
	v_permlane32_swap_b32_e32 v157, v173
	v_pk_fma_f32 v[136:137], v[10:11], v[14:15], v[136:137] op_sel_hi:[0,1,1]
	v_pk_fma_f32 v[168:169], v[8:9], v[12:13], v[168:169] op_sel:[1,0,0]
	v_permlane32_swap_b32_e32 v126, v142
	v_pk_fma_f32 v[12:13], v[8:9], v[12:13], v[136:137] op_sel_hi:[0,1,1]
	v_pk_fma_f32 v[14:15], v[8:9], v[14:15], v[168:169] op_sel_hi:[0,1,1]
	v_permlane32_swap_b32_e32 v158, v174
	v_pk_fma_f32 v[138:139], v[10:11], v[14:15], v[138:139] op_sel_hi:[0,1,1]
	v_pk_fma_f32 v[170:171], v[8:9], v[12:13], v[170:171] op_sel:[1,0,0]
	v_permlane32_swap_b32_e32 v127, v143
	v_pk_fma_f32 v[12:13], v[8:9], v[12:13], v[138:139] op_sel_hi:[0,1,1]
	v_pk_fma_f32 v[14:15], v[8:9], v[14:15], v[170:171] op_sel_hi:[0,1,1]
	v_permlane32_swap_b32_e32 v159, v175
	v_pk_fma_f32 v[124:125], v[10:11], v[14:15], v[124:125] op_sel_hi:[0,1,1]
	v_pk_fma_f32 v[156:157], v[8:9], v[12:13], v[156:157] op_sel:[1,0,0]
	s_nop 0
	v_pk_fma_f32 v[12:13], v[8:9], v[12:13], v[124:125] op_sel_hi:[0,1,1]
	v_pk_fma_f32 v[14:15], v[8:9], v[14:15], v[156:157] op_sel_hi:[0,1,1]
	s_nop 0
	v_pk_fma_f32 v[126:127], v[10:11], v[14:15], v[126:127] op_sel_hi:[0,1,1]
	v_pk_fma_f32 v[158:159], v[8:9], v[12:13], v[158:159] op_sel:[1,0,0]
	s_nop 0
	v_pk_fma_f32 v[12:13], v[8:9], v[12:13], v[126:127] op_sel_hi:[0,1,1]
	v_pk_fma_f32 v[14:15], v[8:9], v[14:15], v[158:159] op_sel_hi:[0,1,1]
	s_nop 0
	v_pk_fma_f32 v[140:141], v[10:11], v[14:15], v[140:141] op_sel_hi:[0,1,1]
	v_pk_fma_f32 v[172:173], v[8:9], v[12:13], v[172:173] op_sel:[1,0,0]
	s_nop 0
	v_pk_fma_f32 v[12:13], v[8:9], v[12:13], v[140:141] op_sel_hi:[0,1,1]
	v_pk_fma_f32 v[14:15], v[8:9], v[14:15], v[172:173] op_sel_hi:[0,1,1]
	s_nop 0
	v_pk_fma_f32 v[142:143], v[10:11], v[14:15], v[142:143] op_sel_hi:[0,1,1]
	v_pk_fma_f32 v[174:175], v[8:9], v[12:13], v[174:175] op_sel:[1,0,0]
	s_nop 0
	v_pk_fma_f32 v[12:13], v[8:9], v[12:13], v[142:143] op_sel_hi:[0,1,1]
	v_pk_fma_f32 v[14:15], v[8:9], v[14:15], v[174:175] op_sel_hi:[0,1,1]
	s_nop 0
	s_nop 0
	v_fma_f32 v181, v180, v14, v13
	v_fma_f32 v182, v179, v12, v15
	v_fma_f32 v12, v178, v12, v181
	v_fma_f32 v14, v178, v14, v182
	v_mov_b32_e32 v13, 0
	v_mov_b32_e32 v15, 0
	s_nop 3
	v_permlane32_swap_b32_e32 v16, v32
	v_permlane32_swap_b32_e32 v200, v216
	v_permlane32_swap_b32_e32 v17, v33
	v_permlane32_swap_b32_e32 v201, v217
	v_permlane32_swap_b32_e32 v18, v34
	v_permlane32_swap_b32_e32 v202, v218
	v_permlane32_swap_b32_e32 v19, v35
	v_permlane32_swap_b32_e32 v203, v219
	v_pk_fma_f32 v[16:17], v[10:11], v[14:15], v[16:17] op_sel_hi:[0,1,1]
	v_pk_fma_f32 v[200:201], v[8:9], v[12:13], v[200:201] op_sel:[1,0,0]
	v_permlane32_swap_b32_e32 v20, v36
	v_pk_fma_f32 v[12:13], v[8:9], v[12:13], v[16:17] op_sel_hi:[0,1,1]
	v_pk_fma_f32 v[14:15], v[8:9], v[14:15], v[200:201] op_sel_hi:[0,1,1]
	v_permlane32_swap_b32_e32 v204, v220
	s_waitcnt vmcnt(3)
; #define LDS_WAIT() asm volatile("s_waitcnt lgkmcnt(0)" ::: "memory")
; __device__ __forceinline__ void p5_phase(Frame& F) {
;     ...
;     for (int it = F.gw; it < NB * NCH * NGRP; it += F.ngw) {
;         bf16x8 afr[4];
; #pragma unroll
;         for (int sub = 0; sub < 4; ++sub) afr[sub] = nfr[sub];
;         if (it + F.ngw < NB * NCH * NGRP) { const int bc = (it + F.ngw) >> 7, r0 = (bc / NCH) * SEQ + (bc % NCH) * TCH;
; #pragma unroll
;             for (int sub = 0; sub < 4; ++sub) nfr[sub] = ssm_load_afrag(U, r0 + 16 * sub, g, F.lane); }
;         float sr = 0.f, si = 0.f;
; #pragma unroll
;         for (int sub = 0; sub < 4; ++sub) {
;             ssm_bu16(afr[sub], bf, bubuf, F.lane);
; #pragma unroll
;             for (int tt = 0; tt < 16; ++tt) { const float bur = bubuf[tt * BUP + F.lane], bui = bubuf[tt * BUP + 64 + F.lane];
;                 const float nr = fmaf(ab.x, sr, fmaf(-ab.y, si, bur)), ni = fmaf(ab.x, si, fmaf(ab.y, sr, bui)); sr = nr; si = ni; }
;             LDS_WAIT(); asm volatile("" ::: "memory");
;         }
;         ((f32x2*)(F.ws + WS_E))[(size_t)it * NST + F.lane] = (f32x2){sr, si};
	v_mfma_f32_32x32x16_bf16 v[112:127], v[104:107], v[48:51], 0
	v_pk_fma_f32 v[18:19], v[10:11], v[14:15], v[18:19] op_sel_hi:[0,1,1]
	v_pk_fma_f32 v[202:203], v[8:9], v[12:13], v[202:203] op_sel:[1,0,0]
	v_permlane32_swap_b32_e32 v21, v37
	v_pk_fma_f32 v[12:13], v[8:9], v[12:13], v[18:19] op_sel_hi:[0,1,1]
	v_pk_fma_f32 v[14:15], v[8:9], v[14:15], v[202:203] op_sel_hi:[0,1,1]
	v_permlane32_swap_b32_e32 v205, v221
	v_mfma_f32_32x32x16_bf16 v[128:143], v[104:107], v[52:55], 0
	v_pk_fma_f32 v[32:33], v[10:11], v[14:15], v[32:33] op_sel_hi:[0,1,1]
	v_pk_fma_f32 v[216:217], v[8:9], v[12:13], v[216:217] op_sel:[1,0,0]
	v_permlane32_swap_b32_e32 v22, v38
	v_pk_fma_f32 v[12:13], v[8:9], v[12:13], v[32:33] op_sel_hi:[0,1,1]
	v_pk_fma_f32 v[14:15], v[8:9], v[14:15], v[216:217] op_sel_hi:[0,1,1]
	v_permlane32_swap_b32_e32 v206, v222
	v_mfma_f32_32x32x16_bf16 v[144:159], v[104:107], v[56:59], 0
	v_pk_fma_f32 v[34:35], v[10:11], v[14:15], v[34:35] op_sel_hi:[0,1,1]
	v_pk_fma_f32 v[218:219], v[8:9], v[12:13], v[218:219] op_sel:[1,0,0]
	v_permlane32_swap_b32_e32 v23, v39
	v_pk_fma_f32 v[12:13], v[8:9], v[12:13], v[34:35] op_sel_hi:[0,1,1]
	v_pk_fma_f32 v[14:15], v[8:9], v[14:15], v[218:219] op_sel_hi:[0,1,1]
	v_permlane32_swap_b32_e32 v207, v223
	v_mfma_f32_32x32x16_bf16 v[160:175], v[104:107], v[60:63], 0
	v_pk_fma_f32 v[20:21], v[10:11], v[14:15], v[20:21] op_sel_hi:[0,1,1]
	v_pk_fma_f32 v[204:205], v[8:9], v[12:13], v[204:205] op_sel:[1,0,0]
	v_permlane32_swap_b32_e32 v24, v40
	v_pk_fma_f32 v[12:13], v[8:9], v[12:13], v[20:21] op_sel_hi:[0,1,1]
	v_pk_fma_f32 v[14:15], v[8:9], v[14:15], v[204:205] op_sel_hi:[0,1,1]
	v_permlane32_swap_b32_e32 v208, v224
	v_mfma_f32_32x32x16_bf16 v[112:127], v[104:107], v[64:67], v[112:127]
	v_pk_fma_f32 v[22:23], v[10:11], v[14:15], v[22:23] op_sel_hi:[0,1,1]
	v_pk_fma_f32 v[206:207], v[8:9], v[12:13], v[206:207] op_sel:[1,0,0]
	v_permlane32_swap_b32_e32 v25, v41
	v_pk_fma_f32 v[12:13], v[8:9], v[12:13], v[22:23] op_sel_hi:[0,1,1]
	v_pk_fma_f32 v[14:15], v[8:9], v[14:15], v[206:207] op_sel_hi:[0,1,1]
	v_permlane32_swap_b32_e32 v209, v225
	v_mfma_f32_32x32x16_bf16 v[128:143], v[104:107], v[68:71], v[128:143]
	v_pk_fma_f32 v[36:37], v[10:11], v[14:15], v[36:37] op_sel_hi:[0,1,1]
	v_pk_fma_f32 v[220:221], v[8:9], v[12:13], v[220:221] op_sel:[1,0,0]
	v_permlane32_swap_b32_e32 v26, v42
	v_pk_fma_f32 v[12:13], v[8:9], v[12:13], v[36:37] op_sel_hi:[0,1,1]
	v_pk_fma_f32 v[14:15], v[8:9], v[14:15], v[220:221] op_sel_hi:[0,1,1]
	v_permlane32_swap_b32_e32 v210, v226
	v_mfma_f32_32x32x16_bf16 v[144:159], v[104:107], v[72:75], v[144:159]
	v_pk_fma_f32 v[38:39], v[10:11], v[14:15], v[38:39] op_sel_hi:[0,1,1]
	v_pk_fma_f32 v[222:223], v[8:9], v[12:13], v[222:223] op_sel:[1,0,0]
	v_permlane32_swap_b32_e32 v27, v43
	v_pk_fma_f32 v[12:13], v[8:9], v[12:13], v[38:39] op_sel_hi:[0,1,1]
	v_pk_fma_f32 v[14:15], v[8:9], v[14:15], v[222:223] op_sel_hi:[0,1,1]
	v_permlane32_swap_b32_e32 v211, v227
	v_mfma_f32_32x32x16_bf16 v[160:175], v[104:107], v[76:79], v[160:175]
	v_pk_fma_f32 v[24:25], v[10:11], v[14:15], v[24:25] op_sel_hi:[0,1,1]
	v_pk_fma_f32 v[208:209], v[8:9], v[12:13], v[208:209] op_sel:[1,0,0]
	v_permlane32_swap_b32_e32 v28, v44
	v_pk_fma_f32 v[12:13], v[8:9], v[12:13], v[24:25] op_sel_hi:[0,1,1]
	v_pk_fma_f32 v[14:15], v[8:9], v[14:15], v[208:209] op_sel_hi:[0,1,1]
	v_permlane32_swap_b32_e32 v212, v228
	v_pk_fma_f32 v[26:27], v[10:11], v[14:15], v[26:27] op_sel_hi:[0,1,1]
	v_pk_fma_f32 v[210:211], v[8:9], v[12:13], v[210:211] op_sel:[1,0,0]
	v_permlane32_swap_b32_e32 v29, v45
	v_pk_fma_f32 v[12:13], v[8:9], v[12:13], v[26:27] op_sel_hi:[0,1,1]
	v_pk_fma_f32 v[14:15], v[8:9], v[14:15], v[210:211] op_sel_hi:[0,1,1]
	v_permlane32_swap_b32_e32 v213, v229
	v_pk_fma_f32 v[40:41], v[10:11], v[14:15], v[40:41] op_sel_hi:[0,1,1]
	v_pk_fma_f32 v[224:225], v[8:9], v[12:13], v[224:225] op_sel:[1,0,0]
	v_permlane32_swap_b32_e32 v30, v46
	v_pk_fma_f32 v[12:13], v[8:9], v[12:13], v[40:41] op_sel_hi:[0,1,1]
	v_pk_fma_f32 v[14:15], v[8:9], v[14:15], v[224:225] op_sel_hi:[0,1,1]
	v_permlane32_swap_b32_e32 v214, v230
	v_pk_fma_f32 v[42:43], v[10:11], v[14:15], v[42:43] op_sel_hi:[0,1,1]
	v_pk_fma_f32 v[226:227], v[8:9], v[12:13], v[226:227] op_sel:[1,0,0]
	v_permlane32_swap_b32_e32 v31, v47
	v_pk_fma_f32 v[12:13], v[8:9], v[12:13], v[42:43] op_sel_hi:[0,1,1]
	v_pk_fma_f32 v[14:15], v[8:9], v[14:15], v[226:227] op_sel_hi:[0,1,1]
	v_permlane32_swap_b32_e32 v215, v231
	v_pk_fma_f32 v[28:29], v[10:11], v[14:15], v[28:29] op_sel_hi:[0,1,1]
	v_pk_fma_f32 v[212:213], v[8:9], v[12:13], v[212:213] op_sel:[1,0,0]
	s_nop 0
	v_pk_fma_f32 v[12:13], v[8:9], v[12:13], v[28:29] op_sel_hi:[0,1,1]
	v_pk_fma_f32 v[14:15], v[8:9], v[14:15], v[212:213] op_sel_hi:[0,1,1]
	s_nop 0
	v_pk_fma_f32 v[30:31], v[10:11], v[14:15], v[30:31] op_sel_hi:[0,1,1]
	v_pk_fma_f32 v[214:215], v[8:9], v[12:13], v[214:215] op_sel:[1,0,0]
	s_nop 0
	v_pk_fma_f32 v[12:13], v[8:9], v[12:13], v[30:31] op_sel_hi:[0,1,1]
	v_pk_fma_f32 v[14:15], v[8:9], v[14:15], v[214:215] op_sel_hi:[0,1,1]
	s_nop 0
	v_pk_fma_f32 v[44:45], v[10:11], v[14:15], v[44:45] op_sel_hi:[0,1,1]
	v_pk_fma_f32 v[228:229], v[8:9], v[12:13], v[228:229] op_sel:[1,0,0]
	s_nop 0
	v_pk_fma_f32 v[12:13], v[8:9], v[12:13], v[44:45] op_sel_hi:[0,1,1]
	v_pk_fma_f32 v[14:15], v[8:9], v[14:15], v[228:229] op_sel_hi:[0,1,1]
	s_nop 0
	v_pk_fma_f32 v[46:47], v[10:11], v[14:15], v[46:47] op_sel_hi:[0,1,1]
	v_pk_fma_f32 v[230:231], v[8:9], v[12:13], v[230:231] op_sel:[1,0,0]
	s_nop 0
	v_pk_fma_f32 v[12:13], v[8:9], v[12:13], v[46:47] op_sel_hi:[0,1,1]
	v_pk_fma_f32 v[14:15], v[8:9], v[14:15], v[230:231] op_sel_hi:[0,1,1]
	s_nop 0
	s_nop 0
	v_fma_f32 v181, v180, v14, v13
	v_fma_f32 v182, v179, v12, v15
	v_fma_f32 v12, v178, v12, v181
	v_fma_f32 v14, v178, v14, v182
	v_mov_b32_e32 v13, 0
	v_mov_b32_e32 v15, 0
	v_mov_b32_e32 v182, v12
	v_mov_b32_e32 v183, v14
	global_store_dwordx2 v7, v[182:183], s[48:49]
	s_add_u32 s48, s48, 0x100000
	s_addc_u32 s49, s49, 0
	v_mov_b32_e32 v12, 0
	v_mov_b32_e32 v13, 0
	v_mov_b32_e32 v14, 0
	v_mov_b32_e32 v15, 0
	s_nop 3
	v_permlane32_swap_b32_e32 v112, v128
	v_permlane32_swap_b32_e32 v144, v160
	v_permlane32_swap_b32_e32 v113, v129
	v_permlane32_swap_b32_e32 v145, v161
	v_permlane32_swap_b32_e32 v114, v130
	v_permlane32_swap_b32_e32 v146, v162
	v_permlane32_swap_b32_e32 v115, v131
	v_permlane32_swap_b32_e32 v147, v163
	v_pk_fma_f32 v[112:113], v[10:11], v[14:15], v[112:113] op_sel_hi:[0,1,1]
	v_pk_fma_f32 v[144:145], v[8:9], v[12:13], v[144:145] op_sel:[1,0,0]
	v_permlane32_swap_b32_e32 v116, v132
	v_pk_fma_f32 v[12:13], v[8:9], v[12:13], v[112:113] op_sel_hi:[0,1,1]
	v_pk_fma_f32 v[14:15], v[8:9], v[14:15], v[144:145] op_sel_hi:[0,1,1]
	v_permlane32_swap_b32_e32 v148, v164
	s_waitcnt vmcnt(3)
; #define LAS __attribute__((address_space(3)))
; #define LDS_WAIT() asm volatile("s_waitcnt lgkmcnt(0)" ::: "memory")
; #define MFMA_PIN(a, b) do { __builtin_amdgcn_sched_barrier(0); asm volatile("" :: "v"(a), "v"(b)); } while (0)
; #define MFMA_SETTLE() do { __builtin_amdgcn_sched_barrier(0); asm volatile("s_nop 15"); __builtin_amdgcn_sched_barrier(0); } while (0)
; __device__ __forceinline__ void ssm_bu16(const bf16x8 afr, const bf16x8 (&bf)[8], LAS float* bubuf, int lane) {
;     LAS float* wp = bubuf + (4 * (lane >> 4)) * BUP + (lane & 15);
;     f32x4 d[8];
; #pragma unroll
;     for (int cb = 0; cb < 8; ++cb) { d[cb] = __builtin_amdgcn_mfma_f32_16x16x32_bf16(afr, bf[cb], (f32x4){0.f, 0.f, 0.f, 0.f}, 0, 0, 0); MFMA_PIN(afr, bf[cb]); }
;     MFMA_SETTLE();
; __device__ __forceinline__ void p5_phase(Frame& F) {
;     ...
;         for (int sub = 0; sub < 4; ++sub) {
;             ssm_bu16(afr[sub], bf, bubuf, F.lane);
; #pragma unroll
;             for (int tt = 0; tt < 16; ++tt) { const float bur = bubuf[tt * BUP + F.lane], bui = bubuf[tt * BUP + 64 + F.lane];
;                 const float nr = fmaf(ab.x, sr, fmaf(-ab.y, si, bur)), ni = fmaf(ab.x, si, fmaf(ab.y, sr, bui)); sr = nr; si = ni; }
;             LDS_WAIT(); asm volatile("" ::: "memory");
	v_mfma_f32_32x32x16_bf16 v[16:31], v[108:111], v[48:51], 0
	v_pk_fma_f32 v[114:115], v[10:11], v[14:15], v[114:115] op_sel_hi:[0,1,1]
	v_pk_fma_f32 v[146:147], v[8:9], v[12:13], v[146:147] op_sel:[1,0,0]
	v_permlane32_swap_b32_e32 v117, v133
	v_pk_fma_f32 v[12:13], v[8:9], v[12:13], v[114:115] op_sel_hi:[0,1,1]
	v_pk_fma_f32 v[14:15], v[8:9], v[14:15], v[146:147] op_sel_hi:[0,1,1]
	v_permlane32_swap_b32_e32 v149, v165
	v_mfma_f32_32x32x16_bf16 v[32:47], v[108:111], v[52:55], 0
	v_pk_fma_f32 v[128:129], v[10:11], v[14:15], v[128:129] op_sel_hi:[0,1,1]
	v_pk_fma_f32 v[160:161], v[8:9], v[12:13], v[160:161] op_sel:[1,0,0]
	v_permlane32_swap_b32_e32 v118, v134
	v_pk_fma_f32 v[12:13], v[8:9], v[12:13], v[128:129] op_sel_hi:[0,1,1]
	v_pk_fma_f32 v[14:15], v[8:9], v[14:15], v[160:161] op_sel_hi:[0,1,1]
	v_permlane32_swap_b32_e32 v150, v166
	v_mfma_f32_32x32x16_bf16 v[200:215], v[108:111], v[56:59], 0
	v_pk_fma_f32 v[130:131], v[10:11], v[14:15], v[130:131] op_sel_hi:[0,1,1]
	v_pk_fma_f32 v[162:163], v[8:9], v[12:13], v[162:163] op_sel:[1,0,0]
	v_permlane32_swap_b32_e32 v119, v135
	v_pk_fma_f32 v[12:13], v[8:9], v[12:13], v[130:131] op_sel_hi:[0,1,1]
	v_pk_fma_f32 v[14:15], v[8:9], v[14:15], v[162:163] op_sel_hi:[0,1,1]
	v_permlane32_swap_b32_e32 v151, v167
	v_mfma_f32_32x32x16_bf16 v[216:231], v[108:111], v[60:63], 0
	v_pk_fma_f32 v[116:117], v[10:11], v[14:15], v[116:117] op_sel_hi:[0,1,1]
	v_pk_fma_f32 v[148:149], v[8:9], v[12:13], v[148:149] op_sel:[1,0,0]
	v_permlane32_swap_b32_e32 v120, v136
	v_pk_fma_f32 v[12:13], v[8:9], v[12:13], v[116:117] op_sel_hi:[0,1,1]
	v_pk_fma_f32 v[14:15], v[8:9], v[14:15], v[148:149] op_sel_hi:[0,1,1]
	v_permlane32_swap_b32_e32 v152, v168
	v_mfma_f32_32x32x16_bf16 v[16:31], v[108:111], v[64:67], v[16:31]
	v_pk_fma_f32 v[118:119], v[10:11], v[14:15], v[118:119] op_sel_hi:[0,1,1]
	v_pk_fma_f32 v[150:151], v[8:9], v[12:13], v[150:151] op_sel:[1,0,0]
	v_permlane32_swap_b32_e32 v121, v137
	v_pk_fma_f32 v[12:13], v[8:9], v[12:13], v[118:119] op_sel_hi:[0,1,1]
	v_pk_fma_f32 v[14:15], v[8:9], v[14:15], v[150:151] op_sel_hi:[0,1,1]
	v_permlane32_swap_b32_e32 v153, v169
	v_mfma_f32_32x32x16_bf16 v[32:47], v[108:111], v[68:71], v[32:47]
	v_pk_fma_f32 v[132:133], v[10:11], v[14:15], v[132:133] op_sel_hi:[0,1,1]
	v_pk_fma_f32 v[164:165], v[8:9], v[12:13], v[164:165] op_sel:[1,0,0]
	v_permlane32_swap_b32_e32 v122, v138
	v_pk_fma_f32 v[12:13], v[8:9], v[12:13], v[132:133] op_sel_hi:[0,1,1]
	v_pk_fma_f32 v[14:15], v[8:9], v[14:15], v[164:165] op_sel_hi:[0,1,1]
	v_permlane32_swap_b32_e32 v154, v170
	v_mfma_f32_32x32x16_bf16 v[200:215], v[108:111], v[72:75], v[200:215]
	v_pk_fma_f32 v[134:135], v[10:11], v[14:15], v[134:135] op_sel_hi:[0,1,1]
	v_pk_fma_f32 v[166:167], v[8:9], v[12:13], v[166:167] op_sel:[1,0,0]
	v_permlane32_swap_b32_e32 v123, v139
	v_pk_fma_f32 v[12:13], v[8:9], v[12:13], v[134:135] op_sel_hi:[0,1,1]
	v_pk_fma_f32 v[14:15], v[8:9], v[14:15], v[166:167] op_sel_hi:[0,1,1]
	v_permlane32_swap_b32_e32 v155, v171
	v_mfma_f32_32x32x16_bf16 v[216:231], v[108:111], v[76:79], v[216:231]
	v_pk_fma_f32 v[120:121], v[10:11], v[14:15], v[120:121] op_sel_hi:[0,1,1]
	v_pk_fma_f32 v[152:153], v[8:9], v[12:13], v[152:153] op_sel:[1,0,0]
	v_permlane32_swap_b32_e32 v124, v140
	v_pk_fma_f32 v[12:13], v[8:9], v[12:13], v[120:121] op_sel_hi:[0,1,1]
	v_pk_fma_f32 v[14:15], v[8:9], v[14:15], v[152:153] op_sel_hi:[0,1,1]
	v_permlane32_swap_b32_e32 v156, v172
	v_pk_fma_f32 v[122:123], v[10:11], v[14:15], v[122:123] op_sel_hi:[0,1,1]
	v_pk_fma_f32 v[154:155], v[8:9], v[12:13], v[154:155] op_sel:[1,0,0]
	v_permlane32_swap_b32_e32 v125, v141
	v_pk_fma_f32 v[12:13], v[8:9], v[12:13], v[122:123] op_sel_hi:[0,1,1]
	v_pk_fma_f32 v[14:15], v[8:9], v[14:15], v[154:155] op_sel_hi:[0,1,1]
	v_permlane32_swap_b32_e32 v157, v173
	v_pk_fma_f32 v[136:137], v[10:11], v[14:15], v[136:137] op_sel_hi:[0,1,1]
	v_pk_fma_f32 v[168:169], v[8:9], v[12:13], v[168:169] op_sel:[1,0,0]
	v_permlane32_swap_b32_e32 v126, v142
	v_pk_fma_f32 v[12:13], v[8:9], v[12:13], v[136:137] op_sel_hi:[0,1,1]
	v_pk_fma_f32 v[14:15], v[8:9], v[14:15], v[168:169] op_sel_hi:[0,1,1]
	v_permlane32_swap_b32_e32 v158, v174
	v_pk_fma_f32 v[138:139], v[10:11], v[14:15], v[138:139] op_sel_hi:[0,1,1]
	v_pk_fma_f32 v[170:171], v[8:9], v[12:13], v[170:171] op_sel:[1,0,0]
	v_permlane32_swap_b32_e32 v127, v143
	v_pk_fma_f32 v[12:13], v[8:9], v[12:13], v[138:139] op_sel_hi:[0,1,1]
	v_pk_fma_f32 v[14:15], v[8:9], v[14:15], v[170:171] op_sel_hi:[0,1,1]
	v_permlane32_swap_b32_e32 v159, v175
	v_pk_fma_f32 v[124:125], v[10:11], v[14:15], v[124:125] op_sel_hi:[0,1,1]
	v_pk_fma_f32 v[156:157], v[8:9], v[12:13], v[156:157] op_sel:[1,0,0]
	s_nop 0
	v_pk_fma_f32 v[12:13], v[8:9], v[12:13], v[124:125] op_sel_hi:[0,1,1]
	v_pk_fma_f32 v[14:15], v[8:9], v[14:15], v[156:157] op_sel_hi:[0,1,1]
	s_nop 0
	v_pk_fma_f32 v[126:127], v[10:11], v[14:15], v[126:127] op_sel_hi:[0,1,1]
	v_pk_fma_f32 v[158:159], v[8:9], v[12:13], v[158:159] op_sel:[1,0,0]
	s_nop 0
	v_pk_fma_f32 v[12:13], v[8:9], v[12:13], v[126:127] op_sel_hi:[0,1,1]
	v_pk_fma_f32 v[14:15], v[8:9], v[14:15], v[158:159] op_sel_hi:[0,1,1]
	s_nop 0
	v_pk_fma_f32 v[140:141], v[10:11], v[14:15], v[140:141] op_sel_hi:[0,1,1]
	v_pk_fma_f32 v[172:173], v[8:9], v[12:13], v[172:173] op_sel:[1,0,0]
	s_nop 0
	v_pk_fma_f32 v[12:13], v[8:9], v[12:13], v[140:141] op_sel_hi:[0,1,1]
	v_pk_fma_f32 v[14:15], v[8:9], v[14:15], v[172:173] op_sel_hi:[0,1,1]
	s_nop 0
	v_pk_fma_f32 v[142:143], v[10:11], v[14:15], v[142:143] op_sel_hi:[0,1,1]
	v_pk_fma_f32 v[174:175], v[8:9], v[12:13], v[174:175] op_sel:[1,0,0]
	s_nop 0
	v_pk_fma_f32 v[12:13], v[8:9], v[12:13], v[142:143] op_sel_hi:[0,1,1]
; #define LDS_WAIT() asm volatile("s_waitcnt lgkmcnt(0)" ::: "memory")
; __device__ __forceinline__ void p5_phase(Frame& F) {
;     ...
;             ssm_bu16(afr[sub], bf, bubuf, F.lane);
; #pragma unroll
;             for (int tt = 0; tt < 16; ++tt) { const float bur = bubuf[tt * BUP + F.lane], bui = bubuf[tt * BUP + 64 + F.lane];
;                 const float nr = fmaf(ab.x, sr, fmaf(-ab.y, si, bur)), ni = fmaf(ab.x, si, fmaf(ab.y, sr, bui)); sr = nr; si = ni; }
;             LDS_WAIT(); asm volatile("" ::: "memory");
;         }
;         ((f32x2*)(F.ws + WS_E))[(size_t)it * NST + F.lane] = (f32x2){sr, si};
	v_pk_fma_f32 v[14:15], v[8:9], v[14:15], v[174:175] op_sel_hi:[0,1,1]
	s_nop 0
	s_nop 0
	v_fma_f32 v181, v180, v14, v13
	v_fma_f32 v182, v179, v12, v15
	v_fma_f32 v12, v178, v12, v181
	v_fma_f32 v14, v178, v14, v182
	v_mov_b32_e32 v13, 0
	v_mov_b32_e32 v15, 0
	s_nop 3
	v_permlane32_swap_b32_e32 v16, v32
	v_permlane32_swap_b32_e32 v200, v216
	v_permlane32_swap_b32_e32 v17, v33
	v_permlane32_swap_b32_e32 v201, v217
	v_permlane32_swap_b32_e32 v18, v34
	v_permlane32_swap_b32_e32 v202, v218
	v_permlane32_swap_b32_e32 v19, v35
	v_permlane32_swap_b32_e32 v203, v219
	v_pk_fma_f32 v[16:17], v[10:11], v[14:15], v[16:17] op_sel_hi:[0,1,1]
	v_pk_fma_f32 v[200:201], v[8:9], v[12:13], v[200:201] op_sel:[1,0,0]
	v_permlane32_swap_b32_e32 v20, v36
	v_pk_fma_f32 v[12:13], v[8:9], v[12:13], v[16:17] op_sel_hi:[0,1,1]
	v_pk_fma_f32 v[14:15], v[8:9], v[14:15], v[200:201] op_sel_hi:[0,1,1]
	v_permlane32_swap_b32_e32 v204, v220
	v_pk_fma_f32 v[18:19], v[10:11], v[14:15], v[18:19] op_sel_hi:[0,1,1]
	v_pk_fma_f32 v[202:203], v[8:9], v[12:13], v[202:203] op_sel:[1,0,0]
	v_permlane32_swap_b32_e32 v21, v37
	v_pk_fma_f32 v[12:13], v[8:9], v[12:13], v[18:19] op_sel_hi:[0,1,1]
	v_pk_fma_f32 v[14:15], v[8:9], v[14:15], v[202:203] op_sel_hi:[0,1,1]
	v_permlane32_swap_b32_e32 v205, v221
	v_pk_fma_f32 v[32:33], v[10:11], v[14:15], v[32:33] op_sel_hi:[0,1,1]
	v_pk_fma_f32 v[216:217], v[8:9], v[12:13], v[216:217] op_sel:[1,0,0]
	v_permlane32_swap_b32_e32 v22, v38
	v_pk_fma_f32 v[12:13], v[8:9], v[12:13], v[32:33] op_sel_hi:[0,1,1]
	v_pk_fma_f32 v[14:15], v[8:9], v[14:15], v[216:217] op_sel_hi:[0,1,1]
	v_permlane32_swap_b32_e32 v206, v222
	v_pk_fma_f32 v[34:35], v[10:11], v[14:15], v[34:35] op_sel_hi:[0,1,1]
	v_pk_fma_f32 v[218:219], v[8:9], v[12:13], v[218:219] op_sel:[1,0,0]
	v_permlane32_swap_b32_e32 v23, v39
	v_pk_fma_f32 v[12:13], v[8:9], v[12:13], v[34:35] op_sel_hi:[0,1,1]
	v_pk_fma_f32 v[14:15], v[8:9], v[14:15], v[218:219] op_sel_hi:[0,1,1]
	v_permlane32_swap_b32_e32 v207, v223
	v_pk_fma_f32 v[20:21], v[10:11], v[14:15], v[20:21] op_sel_hi:[0,1,1]
	v_pk_fma_f32 v[204:205], v[8:9], v[12:13], v[204:205] op_sel:[1,0,0]
	v_permlane32_swap_b32_e32 v24, v40
	v_pk_fma_f32 v[12:13], v[8:9], v[12:13], v[20:21] op_sel_hi:[0,1,1]
	v_pk_fma_f32 v[14:15], v[8:9], v[14:15], v[204:205] op_sel_hi:[0,1,1]
	v_permlane32_swap_b32_e32 v208, v224
	v_pk_fma_f32 v[22:23], v[10:11], v[14:15], v[22:23] op_sel_hi:[0,1,1]
	v_pk_fma_f32 v[206:207], v[8:9], v[12:13], v[206:207] op_sel:[1,0,0]
	v_permlane32_swap_b32_e32 v25, v41
	v_pk_fma_f32 v[12:13], v[8:9], v[12:13], v[22:23] op_sel_hi:[0,1,1]
	v_pk_fma_f32 v[14:15], v[8:9], v[14:15], v[206:207] op_sel_hi:[0,1,1]
	v_permlane32_swap_b32_e32 v209, v225
	v_pk_fma_f32 v[36:37], v[10:11], v[14:15], v[36:37] op_sel_hi:[0,1,1]
	v_pk_fma_f32 v[220:221], v[8:9], v[12:13], v[220:221] op_sel:[1,0,0]
	v_permlane32_swap_b32_e32 v26, v42
	v_pk_fma_f32 v[12:13], v[8:9], v[12:13], v[36:37] op_sel_hi:[0,1,1]
	v_pk_fma_f32 v[14:15], v[8:9], v[14:15], v[220:221] op_sel_hi:[0,1,1]
	v_permlane32_swap_b32_e32 v210, v226
	v_pk_fma_f32 v[38:39], v[10:11], v[14:15], v[38:39] op_sel_hi:[0,1,1]
	v_pk_fma_f32 v[222:223], v[8:9], v[12:13], v[222:223] op_sel:[1,0,0]
	v_permlane32_swap_b32_e32 v27, v43
	v_pk_fma_f32 v[12:13], v[8:9], v[12:13], v[38:39] op_sel_hi:[0,1,1]
	v_pk_fma_f32 v[14:15], v[8:9], v[14:15], v[222:223] op_sel_hi:[0,1,1]
	v_permlane32_swap_b32_e32 v211, v227
	v_pk_fma_f32 v[24:25], v[10:11], v[14:15], v[24:25] op_sel_hi:[0,1,1]
	v_pk_fma_f32 v[208:209], v[8:9], v[12:13], v[208:209] op_sel:[1,0,0]
	v_permlane32_swap_b32_e32 v28, v44
	v_pk_fma_f32 v[12:13], v[8:9], v[12:13], v[24:25] op_sel_hi:[0,1,1]
	v_pk_fma_f32 v[14:15], v[8:9], v[14:15], v[208:209] op_sel_hi:[0,1,1]
	v_permlane32_swap_b32_e32 v212, v228
	v_pk_fma_f32 v[26:27], v[10:11], v[14:15], v[26:27] op_sel_hi:[0,1,1]
	v_pk_fma_f32 v[210:211], v[8:9], v[12:13], v[210:211] op_sel:[1,0,0]
	v_permlane32_swap_b32_e32 v29, v45
	v_pk_fma_f32 v[12:13], v[8:9], v[12:13], v[26:27] op_sel_hi:[0,1,1]
	v_pk_fma_f32 v[14:15], v[8:9], v[14:15], v[210:211] op_sel_hi:[0,1,1]
	v_permlane32_swap_b32_e32 v213, v229
	v_pk_fma_f32 v[40:41], v[10:11], v[14:15], v[40:41] op_sel_hi:[0,1,1]
	v_pk_fma_f32 v[224:225], v[8:9], v[12:13], v[224:225] op_sel:[1,0,0]
	v_permlane32_swap_b32_e32 v30, v46
	v_pk_fma_f32 v[12:13], v[8:9], v[12:13], v[40:41] op_sel_hi:[0,1,1]
	v_pk_fma_f32 v[14:15], v[8:9], v[14:15], v[224:225] op_sel_hi:[0,1,1]
	v_permlane32_swap_b32_e32 v214, v230
	v_pk_fma_f32 v[42:43], v[10:11], v[14:15], v[42:43] op_sel_hi:[0,1,1]
	v_pk_fma_f32 v[226:227], v[8:9], v[12:13], v[226:227] op_sel:[1,0,0]
	v_permlane32_swap_b32_e32 v31, v47
	v_pk_fma_f32 v[12:13], v[8:9], v[12:13], v[42:43] op_sel_hi:[0,1,1]
	v_pk_fma_f32 v[14:15], v[8:9], v[14:15], v[226:227] op_sel_hi:[0,1,1]
	v_permlane32_swap_b32_e32 v215, v231
	v_pk_fma_f32 v[28:29], v[10:11], v[14:15], v[28:29] op_sel_hi:[0,1,1]
	v_pk_fma_f32 v[212:213], v[8:9], v[12:13], v[212:213] op_sel:[1,0,0]
	s_nop 0
	v_pk_fma_f32 v[12:13], v[8:9], v[12:13], v[28:29] op_sel_hi:[0,1,1]
	v_pk_fma_f32 v[14:15], v[8:9], v[14:15], v[212:213] op_sel_hi:[0,1,1]
	s_nop 0
	v_pk_fma_f32 v[30:31], v[10:11], v[14:15], v[30:31] op_sel_hi:[0,1,1]
	v_pk_fma_f32 v[214:215], v[8:9], v[12:13], v[214:215] op_sel:[1,0,0]
	s_nop 0
	v_pk_fma_f32 v[12:13], v[8:9], v[12:13], v[30:31] op_sel_hi:[0,1,1]
	v_pk_fma_f32 v[14:15], v[8:9], v[14:15], v[214:215] op_sel_hi:[0,1,1]
	s_nop 0
	v_pk_fma_f32 v[44:45], v[10:11], v[14:15], v[44:45] op_sel_hi:[0,1,1]
	v_pk_fma_f32 v[228:229], v[8:9], v[12:13], v[228:229] op_sel:[1,0,0]
	s_nop 0
	v_pk_fma_f32 v[12:13], v[8:9], v[12:13], v[44:45] op_sel_hi:[0,1,1]
	v_pk_fma_f32 v[14:15], v[8:9], v[14:15], v[228:229] op_sel_hi:[0,1,1]
	s_nop 0
	v_pk_fma_f32 v[46:47], v[10:11], v[14:15], v[46:47] op_sel_hi:[0,1,1]
	v_pk_fma_f32 v[230:231], v[8:9], v[12:13], v[230:231] op_sel:[1,0,0]
	s_nop 0
	v_pk_fma_f32 v[12:13], v[8:9], v[12:13], v[46:47] op_sel_hi:[0,1,1]
	v_pk_fma_f32 v[14:15], v[8:9], v[14:15], v[230:231] op_sel_hi:[0,1,1]
	s_nop 0
	s_nop 0
	v_fma_f32 v181, v180, v14, v13
	v_fma_f32 v182, v179, v12, v15
	v_fma_f32 v12, v178, v12, v181
	v_fma_f32 v14, v178, v14, v182
	v_mov_b32_e32 v13, 0
	v_mov_b32_e32 v15, 0
	v_mov_b32_e32 v182, v12
	v_mov_b32_e32 v183, v14
	global_store_dwordx2 v7, v[182:183], s[48:49]
	s_add_u32 s48, s48, 0x100000
	s_addc_u32 s49, s49, 0
